# GEMM MMA blocks: post-MMA s_barrier issued before s_setprio 0 (28 sites), on top of v42
# speedup vs baseline: 1.0001x; 1.0001x over previous
; #define PG8_STAGE(bufoff, gbase, voff) do { _Pragma("unroll") for (int _i = 0; _i < 2; ++_i) \
;         __builtin_amdgcn_global_load_lds((const unsigned*)((const char*)(gbase) + (voff)[_i]), (PG8_LAS unsigned*)(lds + (bufoff) + ldsw + _i * 8192), 16, 0, 0); } while (0)
; #define PG8_LDA(dst, b, h) do { _Pragma("unroll") for (int m = 0; m < 4; ++m) _Pragma("unroll") for (int k = 0; k < 2; ++k) dst[m][k] = *(const PG8_LAS bf16x8*)(lds + PG8_SA(b, h) + aoff + m * 2048 + k * 1024); } while (0)
; #define PG8_LDB(dst, b, h) do { _Pragma("unroll") for (int n = 0; n < 2; ++n) _Pragma("unroll") for (int k = 0; k < 2; ++k) dst[n][k] = *(const PG8_LAS bf16x8*)(lds + PG8_SB(b, h) + boff + n * 2048 + k * 1024); } while (0)
; #define PG8_MMA(ai, bj, At, Bt) do { __builtin_amdgcn_s_setprio(1); _Pragma("unroll") for (int m = 0; m < 4; ++m) _Pragma("unroll") for (int n = 0; n < 2; ++n) _Pragma("unroll") for (int k = 0; k < 2; ++k) \
;         acc[ai][bj][m][n] = __builtin_amdgcn_mfma_f32_16x16x32_bf16(Bt[n][k], At[m][k], acc[ai][bj][m][n], 0, 0, 0); __builtin_amdgcn_s_setprio(0); } while (0)
; #define PG8_WAIT_V(n) asm volatile("s_waitcnt vmcnt(" #n ")" ::: "memory")
; #define PG8_WAIT_L(n) asm volatile("s_waitcnt lgkmcnt(" #n ")" ::: "memory")
; #define PG8_BAR __builtin_amdgcn_s_barrier()
; #define PG8_SCHED __builtin_amdgcn_sched_barrier(0)
; template <class Epi, class Sched, bool ALIGN_EPI = false, bool SP2 = false>
; __device__ __forceinline__ void gemm_phase(PG8_LAS unsigned char* lds, const Gemm g, const Sched& S, const Epi& E) {
;     ...
;             const char* a2 = last ? nA : cA + (size_t)(t + 2) * kstep; const char* b2 = last ? nB : cB + (size_t)(t + 2) * kstep;
;             const char* a3 = a2 + kstep; const char* b3 = b2 + kstep;
;             if (last && has_next) S.a_ready(nxt);
;             if constexpr (SP2) {
;             PG8_LDB(B0, 0, 0); PG8_LDB(B1, 0, 1); PG8_SCHED; PG8_LDA(At, 0, 0); PG8_STAGE(PG8_SA(1, 1), a1 + hstep, voffA);
;             PG8_WAIT_V(8); PG8_WAIT_L(0); PG8_BAR; PG8_MMA(0, 0, At, B0); PG8_MMA(0, 1, At, B1); PG8_BAR; PG8_SCHED;
;             PG8_LDA(At, 0, 1); PG8_STAGE(PG8_SB(0, 0), b2, voffB); PG8_STAGE(PG8_SB(0, 1), b2 + hstep, voffB); PG8_STAGE(PG8_SA(0, 0), a2, voffA);
.LBB0_148:
	ds_read_b128 v[146:149], v164
	ds_read_b128 v[170:173], v164 offset:1024
	ds_read_b128 v[174:177], v164 offset:2048
	ds_read_b128 v[178:181], v164 offset:3072
	ds_read_b128 v[182:185], v165
	ds_read_b128 v[186:189], v165 offset:1024
	ds_read_b128 v[190:193], v165 offset:2048
	ds_read_b128 v[194:197], v165 offset:3072
	s_add_u32 s38, s6, 0xfffc0080
	s_addc_u32 s39, s7, -1
	s_cmp_eq_u32 s84, 12
	s_cselect_b32 s41, s9, s39
	s_cselect_b32 s40, s11, s38
	s_cselect_b32 s39, s29, s83
	s_cselect_b32 s38, s31, s82
	v_lshl_add_u64 v[150:151], s[6:7], 0, v[138:139]
	s_add_i32 m0, s44, 0xc000
	ds_read_b128 v[198:201], v166
	ds_read_b128 v[202:205], v166 offset:1024
	ds_read_b128 v[206:209], v166 offset:2048
	ds_read_b128 v[214:217], v166 offset:3072
	ds_read_b128 v[218:221], v166 offset:4096
	ds_read_b128 v[222:225], v166 offset:5120
	ds_read_b128 v[226:229], v166 offset:6144
	ds_read_b128 v[230:233], v166 offset:7168
	global_load_lds_dwordx4 v[150:151], off
	v_lshl_add_u64 v[150:151], s[6:7], 0, v[140:141]
	s_add_i32 m0, s44, 0xe000
	s_nop 0
	global_load_lds_dwordx4 v[150:151], off
	s_waitcnt vmcnt(8)
	s_waitcnt lgkmcnt(0)
	s_barrier
	s_setprio 1
	v_mfma_f32_16x16x32_bf16 v[124:127], v[146:149], v[198:201], v[124:127]
	v_mfma_f32_16x16x32_bf16 v[120:123], v[174:177], v[198:201], v[120:123]
	v_mfma_f32_16x16x32_bf16 v[108:111], v[146:149], v[206:209], v[108:111]
	v_mfma_f32_16x16x32_bf16 v[104:107], v[174:177], v[206:209], v[104:107]
	v_mfma_f32_16x16x32_bf16 v[92:95], v[146:149], v[218:221], v[92:95]
	v_mfma_f32_16x16x32_bf16 v[88:91], v[174:177], v[218:221], v[88:91]
	v_mfma_f32_16x16x32_bf16 v[76:79], v[146:149], v[226:229], v[76:79]
	v_mfma_f32_16x16x32_bf16 v[72:75], v[174:177], v[226:229], v[72:75]
	v_mfma_f32_16x16x32_bf16 v[124:127], v[170:173], v[202:205], v[124:127]
	v_mfma_f32_16x16x32_bf16 v[120:123], v[178:181], v[202:205], v[120:123]
	v_mfma_f32_16x16x32_bf16 v[108:111], v[170:173], v[214:217], v[108:111]
	v_mfma_f32_16x16x32_bf16 v[104:107], v[178:181], v[214:217], v[104:107]
	v_mfma_f32_16x16x32_bf16 v[92:95], v[170:173], v[222:225], v[92:95]
	v_mfma_f32_16x16x32_bf16 v[88:91], v[178:181], v[222:225], v[88:91]
	v_mfma_f32_16x16x32_bf16 v[76:79], v[170:173], v[230:233], v[76:79]
	v_mfma_f32_16x16x32_bf16 v[72:75], v[178:181], v[230:233], v[72:75]
	s_setprio 0
	s_setprio 1
	v_mfma_f32_16x16x32_bf16 v[116:119], v[182:185], v[198:201], v[116:119]
	v_mfma_f32_16x16x32_bf16 v[112:115], v[190:193], v[198:201], v[112:115]
	v_mfma_f32_16x16x32_bf16 v[100:103], v[182:185], v[206:209], v[100:103]
	v_mfma_f32_16x16x32_bf16 v[96:99], v[190:193], v[206:209], v[96:99]
	v_mfma_f32_16x16x32_bf16 v[84:87], v[182:185], v[218:221], v[84:87]
	v_mfma_f32_16x16x32_bf16 v[80:83], v[190:193], v[218:221], v[80:83]
	v_mfma_f32_16x16x32_bf16 v[68:71], v[182:185], v[226:229], v[68:71]
	v_mfma_f32_16x16x32_bf16 v[64:67], v[190:193], v[226:229], v[64:67]
	v_mfma_f32_16x16x32_bf16 v[116:119], v[186:189], v[202:205], v[116:119]
	v_mfma_f32_16x16x32_bf16 v[112:115], v[194:197], v[202:205], v[112:115]
	v_mfma_f32_16x16x32_bf16 v[100:103], v[186:189], v[214:217], v[100:103]
	v_mfma_f32_16x16x32_bf16 v[96:99], v[194:197], v[214:217], v[96:99]
	v_mfma_f32_16x16x32_bf16 v[84:87], v[186:189], v[222:225], v[84:87]
	v_mfma_f32_16x16x32_bf16 v[80:83], v[194:197], v[222:225], v[80:83]
	v_mfma_f32_16x16x32_bf16 v[68:71], v[186:189], v[230:233], v[68:71]
	v_mfma_f32_16x16x32_bf16 v[64:67], v[194:197], v[230:233], v[64:67]
	s_barrier
	s_setprio 0
	s_add_i32 s85, s79, s19
	v_lshl_add_u64 v[150:151], s[38:39], 0, v[130:131]
	s_mov_b32 m0, s85
	ds_read_b128 v[198:201], v166 offset:16384
	ds_read_b128 v[202:205], v166 offset:17408
	ds_read_b128 v[206:209], v166 offset:18432
	ds_read_b128 v[214:217], v166 offset:19456
	ds_read_b128 v[218:221], v166 offset:20480
	ds_read_b128 v[222:225], v166 offset:21504
	ds_read_b128 v[226:229], v166 offset:22528
	ds_read_b128 v[230:233], v166 offset:23552
	global_load_lds_dwordx4 v[150:151], off
	s_add_i32 m0, s85, 0x2000
	s_add_u32 s90, s38, 0x40000
	v_lshl_add_u64 v[154:155], s[38:39], 0, v[134:135]
	s_addc_u32 s91, s39, 0
	s_add_i32 s85, s80, s19
	global_load_lds_dwordx4 v[154:155], off
	v_lshl_add_u64 v[210:211], s[90:91], 0, v[130:131]
	s_mov_b32 m0, s85
	v_lshl_add_u64 v[234:235], s[40:41], 0, v[132:133]
	global_load_lds_dwordx4 v[210:211], off
	v_lshl_add_u64 v[210:211], s[90:91], 0, v[134:135]
	s_add_i32 m0, s85, 0x2000
	s_nop 0
	global_load_lds_dwordx4 v[210:211], off
	v_lshl_add_u64 v[210:211], s[40:41], 0, v[128:129]
	s_mov_b32 m0, s44
	s_nop 0
	global_load_lds_dwordx4 v[210:211], off
	s_mov_b32 m0, s45
	s_nop 0
	global_load_lds_dwordx4 v[234:235], off
	s_waitcnt vmcnt(8)
	s_waitcnt lgkmcnt(0)
	s_barrier
; #define PG8_STAGE(bufoff, gbase, voff) do { _Pragma("unroll") for (int _i = 0; _i < 2; ++_i) \
;         __builtin_amdgcn_global_load_lds((const unsigned*)((const char*)(gbase) + (voff)[_i]), (PG8_LAS unsigned*)(lds + (bufoff) + ldsw + _i * 8192), 16, 0, 0); } while (0)
; #define PG8_LDA(dst, b, h) do { _Pragma("unroll") for (int m = 0; m < 4; ++m) _Pragma("unroll") for (int k = 0; k < 2; ++k) dst[m][k] = *(const PG8_LAS bf16x8*)(lds + PG8_SA(b, h) + aoff + m * 2048 + k * 1024); } while (0)
; #define PG8_LDB(dst, b, h) do { _Pragma("unroll") for (int n = 0; n < 2; ++n) _Pragma("unroll") for (int k = 0; k < 2; ++k) dst[n][k] = *(const PG8_LAS bf16x8*)(lds + PG8_SB(b, h) + boff + n * 2048 + k * 1024); } while (0)
; #define PG8_MMA(ai, bj, At, Bt) do { __builtin_amdgcn_s_setprio(1); _Pragma("unroll") for (int m = 0; m < 4; ++m) _Pragma("unroll") for (int n = 0; n < 2; ++n) _Pragma("unroll") for (int k = 0; k < 2; ++k) \
;         acc[ai][bj][m][n] = __builtin_amdgcn_mfma_f32_16x16x32_bf16(Bt[n][k], At[m][k], acc[ai][bj][m][n], 0, 0, 0); __builtin_amdgcn_s_setprio(0); } while (0)
; #define PG8_WAIT_V(n) asm volatile("s_waitcnt vmcnt(" #n ")" ::: "memory")
; #define PG8_WAIT_L(n) asm volatile("s_waitcnt lgkmcnt(" #n ")" ::: "memory")
; #define PG8_BAR __builtin_amdgcn_s_barrier()
; #define PG8_SCHED __builtin_amdgcn_sched_barrier(0)
; template <class Epi, class Sched, bool ALIGN_EPI = false, bool SP2 = false>
; __device__ __forceinline__ void gemm_phase(PG8_LAS unsigned char* lds, const Gemm g, const Sched& S, const Epi& E) {
;     ...
;             PG8_WAIT_V(8); PG8_WAIT_L(0); PG8_BAR; PG8_MMA(1, 0, At, B0); PG8_MMA(1, 1, At, B1); PG8_BAR; PG8_SCHED;
;             PG8_LDB(B0, 1, 0); PG8_LDB(B1, 1, 1); PG8_SCHED; PG8_LDA(At, 1, 0); PG8_STAGE(PG8_SA(0, 1), a2 + hstep, voffA);
;             PG8_WAIT_V(8); PG8_WAIT_L(0); PG8_BAR; PG8_MMA(0, 0, At, B0); PG8_MMA(0, 1, At, B1); PG8_BAR; PG8_SCHED;
	s_setprio 1
	v_mfma_f32_16x16x32_bf16 v[60:63], v[146:149], v[198:201], v[60:63]
	v_mfma_f32_16x16x32_bf16 v[56:59], v[174:177], v[198:201], v[56:59]
	v_mfma_f32_16x16x32_bf16 v[44:47], v[146:149], v[206:209], v[44:47]
	v_mfma_f32_16x16x32_bf16 v[40:43], v[174:177], v[206:209], v[40:43]
	v_mfma_f32_16x16x32_bf16 v[28:31], v[146:149], v[218:221], v[28:31]
	v_mfma_f32_16x16x32_bf16 v[24:27], v[174:177], v[218:221], v[24:27]
	v_mfma_f32_16x16x32_bf16 v[12:15], v[146:149], v[226:229], v[12:15]
	v_mfma_f32_16x16x32_bf16 v[8:11], v[174:177], v[226:229], v[8:11]
	v_mfma_f32_16x16x32_bf16 v[60:63], v[170:173], v[202:205], v[60:63]
	v_mfma_f32_16x16x32_bf16 v[56:59], v[178:181], v[202:205], v[56:59]
	v_mfma_f32_16x16x32_bf16 v[44:47], v[170:173], v[214:217], v[44:47]
	v_mfma_f32_16x16x32_bf16 v[40:43], v[178:181], v[214:217], v[40:43]
	v_mfma_f32_16x16x32_bf16 v[28:31], v[170:173], v[222:225], v[28:31]
	v_mfma_f32_16x16x32_bf16 v[24:27], v[178:181], v[222:225], v[24:27]
	v_mfma_f32_16x16x32_bf16 v[12:15], v[170:173], v[230:233], v[12:15]
	v_mfma_f32_16x16x32_bf16 v[8:11], v[178:181], v[230:233], v[8:11]
	s_setprio 0
	s_setprio 1
	v_mfma_f32_16x16x32_bf16 v[52:55], v[182:185], v[198:201], v[52:55]
	v_mfma_f32_16x16x32_bf16 v[48:51], v[190:193], v[198:201], v[48:51]
	v_mfma_f32_16x16x32_bf16 v[36:39], v[182:185], v[206:209], v[36:39]
	v_mfma_f32_16x16x32_bf16 v[32:35], v[190:193], v[206:209], v[32:35]
	v_mfma_f32_16x16x32_bf16 v[20:23], v[182:185], v[218:221], v[20:23]
	v_mfma_f32_16x16x32_bf16 v[16:19], v[190:193], v[218:221], v[16:19]
	v_mfma_f32_16x16x32_bf16 v[4:7], v[182:185], v[226:229], v[4:7]
	v_mfma_f32_16x16x32_bf16 v[0:3], v[190:193], v[226:229], v[0:3]
	v_mfma_f32_16x16x32_bf16 v[52:55], v[186:189], v[202:205], v[52:55]
	v_mfma_f32_16x16x32_bf16 v[48:51], v[194:197], v[202:205], v[48:51]
	v_mfma_f32_16x16x32_bf16 v[36:39], v[186:189], v[214:217], v[36:39]
	v_mfma_f32_16x16x32_bf16 v[32:35], v[194:197], v[214:217], v[32:35]
	v_mfma_f32_16x16x32_bf16 v[20:23], v[186:189], v[222:225], v[20:23]
	v_mfma_f32_16x16x32_bf16 v[16:19], v[194:197], v[222:225], v[16:19]
	v_mfma_f32_16x16x32_bf16 v[4:7], v[186:189], v[230:233], v[4:7]
	v_mfma_f32_16x16x32_bf16 v[0:3], v[194:197], v[230:233], v[0:3]
	s_barrier
	s_setprio 0
	s_add_i32 s85, 0, 0x18000
	v_add_u32_e32 v136, s85, v159
	s_add_i32 s86, 0, 0x1c000
	ds_read_b128 v[146:149], v136
	ds_read_b128 v[170:173], v136 offset:1024
	ds_read_b128 v[174:177], v136 offset:2048
	ds_read_b128 v[178:181], v136 offset:3072
	v_add_u32_e32 v136, s86, v159
	ds_read_b128 v[182:185], v136
	ds_read_b128 v[186:189], v136 offset:1024
	ds_read_b128 v[190:193], v136 offset:2048
	ds_read_b128 v[194:197], v136 offset:3072
	s_add_u32 s40, s40, 0x40000
	s_addc_u32 s41, s41, 0
	s_mov_b32 m0, s46
	v_lshl_add_u64 v[236:237], s[40:41], 0, v[128:129]
	ds_read_b128 v[198:201], v166 offset:32768
	ds_read_b128 v[202:205], v166 offset:33792
	ds_read_b128 v[206:209], v166 offset:34816
	ds_read_b128 v[214:217], v166 offset:35840
	ds_read_b128 v[218:221], v166 offset:36864
	ds_read_b128 v[222:225], v166 offset:37888
	ds_read_b128 v[226:229], v166 offset:38912
	ds_read_b128 v[230:233], v166 offset:39936
	global_load_lds_dwordx4 v[236:237], off
	v_lshl_add_u64 v[236:237], s[40:41], 0, v[132:133]
	s_mov_b32 m0, s47
	s_nop 0
	global_load_lds_dwordx4 v[236:237], off
	s_waitcnt vmcnt(8)
	s_waitcnt lgkmcnt(0)
	s_barrier
	s_setprio 1
	v_mfma_f32_16x16x32_bf16 v[124:127], v[146:149], v[198:201], v[124:127]
	v_mfma_f32_16x16x32_bf16 v[120:123], v[174:177], v[198:201], v[120:123]
	v_mfma_f32_16x16x32_bf16 v[108:111], v[146:149], v[206:209], v[108:111]
	v_mfma_f32_16x16x32_bf16 v[104:107], v[174:177], v[206:209], v[104:107]
	v_mfma_f32_16x16x32_bf16 v[92:95], v[146:149], v[218:221], v[92:95]
	v_mfma_f32_16x16x32_bf16 v[88:91], v[174:177], v[218:221], v[88:91]
	v_mfma_f32_16x16x32_bf16 v[76:79], v[146:149], v[226:229], v[76:79]
	v_mfma_f32_16x16x32_bf16 v[72:75], v[174:177], v[226:229], v[72:75]
	v_mfma_f32_16x16x32_bf16 v[124:127], v[170:173], v[202:205], v[124:127]
	v_mfma_f32_16x16x32_bf16 v[120:123], v[178:181], v[202:205], v[120:123]
	v_mfma_f32_16x16x32_bf16 v[108:111], v[170:173], v[214:217], v[108:111]
	v_mfma_f32_16x16x32_bf16 v[104:107], v[178:181], v[214:217], v[104:107]
	v_mfma_f32_16x16x32_bf16 v[92:95], v[170:173], v[222:225], v[92:95]
	v_mfma_f32_16x16x32_bf16 v[88:91], v[178:181], v[222:225], v[88:91]
	v_mfma_f32_16x16x32_bf16 v[76:79], v[170:173], v[230:233], v[76:79]
	v_mfma_f32_16x16x32_bf16 v[72:75], v[178:181], v[230:233], v[72:75]
	s_setprio 0
	s_setprio 1
	v_mfma_f32_16x16x32_bf16 v[116:119], v[182:185], v[198:201], v[116:119]
	v_mfma_f32_16x16x32_bf16 v[112:115], v[190:193], v[198:201], v[112:115]
	v_mfma_f32_16x16x32_bf16 v[100:103], v[182:185], v[206:209], v[100:103]
	v_mfma_f32_16x16x32_bf16 v[96:99], v[190:193], v[206:209], v[96:99]
	v_mfma_f32_16x16x32_bf16 v[84:87], v[182:185], v[218:221], v[84:87]
	v_mfma_f32_16x16x32_bf16 v[80:83], v[190:193], v[218:221], v[80:83]
	v_mfma_f32_16x16x32_bf16 v[68:71], v[182:185], v[226:229], v[68:71]
	v_mfma_f32_16x16x32_bf16 v[64:67], v[190:193], v[226:229], v[64:67]
	v_mfma_f32_16x16x32_bf16 v[116:119], v[186:189], v[202:205], v[116:119]
	v_mfma_f32_16x16x32_bf16 v[112:115], v[194:197], v[202:205], v[112:115]
	v_mfma_f32_16x16x32_bf16 v[100:103], v[186:189], v[214:217], v[100:103]
	v_mfma_f32_16x16x32_bf16 v[96:99], v[194:197], v[214:217], v[96:99]
	v_mfma_f32_16x16x32_bf16 v[84:87], v[186:189], v[222:225], v[84:87]
	v_mfma_f32_16x16x32_bf16 v[80:83], v[194:197], v[222:225], v[80:83]
	v_mfma_f32_16x16x32_bf16 v[68:71], v[186:189], v[230:233], v[68:71]
	v_mfma_f32_16x16x32_bf16 v[64:67], v[194:197], v[230:233], v[64:67]
	s_barrier
; #define PG8_STAGE(bufoff, gbase, voff) do { _Pragma("unroll") for (int _i = 0; _i < 2; ++_i) \
;         __builtin_amdgcn_global_load_lds((const unsigned*)((const char*)(gbase) + (voff)[_i]), (PG8_LAS unsigned*)(lds + (bufoff) + ldsw + _i * 8192), 16, 0, 0); } while (0)
; #define PG8_LDA(dst, b, h) do { _Pragma("unroll") for (int m = 0; m < 4; ++m) _Pragma("unroll") for (int k = 0; k < 2; ++k) dst[m][k] = *(const PG8_LAS bf16x8*)(lds + PG8_SA(b, h) + aoff + m * 2048 + k * 1024); } while (0)
; #define PG8_MMA(ai, bj, At, Bt) do { __builtin_amdgcn_s_setprio(1); _Pragma("unroll") for (int m = 0; m < 4; ++m) _Pragma("unroll") for (int n = 0; n < 2; ++n) _Pragma("unroll") for (int k = 0; k < 2; ++k) \
;         acc[ai][bj][m][n] = __builtin_amdgcn_mfma_f32_16x16x32_bf16(Bt[n][k], At[m][k], acc[ai][bj][m][n], 0, 0, 0); __builtin_amdgcn_s_setprio(0); } while (0)
; #define PG8_WAIT_V(n) asm volatile("s_waitcnt vmcnt(" #n ")" ::: "memory")
; #define PG8_WAIT_L(n) asm volatile("s_waitcnt lgkmcnt(" #n ")" ::: "memory")
; #define PG8_BAR __builtin_amdgcn_s_barrier()
; #define PG8_SCHED __builtin_amdgcn_sched_barrier(0)
; template <class Epi, class Sched, bool ALIGN_EPI = false, bool SP2 = false>
; __device__ __forceinline__ void gemm_phase(PG8_LAS unsigned char* lds, const Gemm g, const Sched& S, const Epi& E) {
;     ...
;             PG8_LDA(At, 1, 1); PG8_STAGE(PG8_SB(1, 0), b3, voffB); PG8_STAGE(PG8_SB(1, 1), b3 + hstep, voffB); PG8_STAGE(PG8_SA(1, 0), a3, voffA);
;             PG8_WAIT_V(8); PG8_WAIT_L(0); PG8_BAR; PG8_MMA(1, 0, At, B0); PG8_MMA(1, 1, At, B1); PG8_BAR; PG8_SCHED;
	s_setprio 0
	s_add_i32 s40, s85, s19
	v_lshl_add_u64 v[150:151], v[150:151], 0, s[14:15]
	s_mov_b32 m0, s40
	ds_read_b128 v[198:201], v166 offset:49152
	ds_read_b128 v[202:205], v166 offset:50176
	ds_read_b128 v[206:209], v166 offset:51200
	ds_read_b128 v[214:217], v166 offset:52224
	ds_read_b128 v[218:221], v166 offset:53248
	ds_read_b128 v[222:225], v166 offset:54272
	ds_read_b128 v[226:229], v166 offset:55296
	ds_read_b128 v[230:233], v166 offset:56320
	global_load_lds_dwordx4 v[150:151], off
	s_add_i32 m0, s40, 0x2000
	s_add_u32 s38, s38, 0x40080
	v_lshl_add_u64 v[150:151], v[154:155], 0, s[14:15]
	s_addc_u32 s39, s39, 0
	s_add_i32 s40, s86, s19
	global_load_lds_dwordx4 v[150:151], off
	v_lshl_add_u64 v[150:151], s[38:39], 0, v[130:131]
	s_mov_b32 m0, s40
	s_nop 0
	global_load_lds_dwordx4 v[150:151], off
	v_lshl_add_u64 v[150:151], s[38:39], 0, v[134:135]
	s_add_i32 m0, s40, 0x2000
	s_nop 0
	global_load_lds_dwordx4 v[150:151], off
	v_lshl_add_u64 v[150:151], v[210:211], 0, s[14:15]
	s_mov_b32 m0, s53
	s_nop 0
	global_load_lds_dwordx4 v[150:151], off
	v_lshl_add_u64 v[150:151], v[234:235], 0, s[14:15]
	s_mov_b32 m0, s72
	s_nop 0
	global_load_lds_dwordx4 v[150:151], off
	s_waitcnt vmcnt(8)
	s_waitcnt lgkmcnt(0)
	s_barrier
	s_setprio 1
	v_mfma_f32_16x16x32_bf16 v[60:63], v[146:149], v[198:201], v[60:63]
	v_mfma_f32_16x16x32_bf16 v[56:59], v[174:177], v[198:201], v[56:59]
	v_mfma_f32_16x16x32_bf16 v[44:47], v[146:149], v[206:209], v[44:47]
	v_mfma_f32_16x16x32_bf16 v[40:43], v[174:177], v[206:209], v[40:43]
	v_mfma_f32_16x16x32_bf16 v[28:31], v[146:149], v[218:221], v[28:31]
	v_mfma_f32_16x16x32_bf16 v[24:27], v[174:177], v[218:221], v[24:27]
	v_mfma_f32_16x16x32_bf16 v[12:15], v[146:149], v[226:229], v[12:15]
	v_mfma_f32_16x16x32_bf16 v[8:11], v[174:177], v[226:229], v[8:11]
	v_mfma_f32_16x16x32_bf16 v[60:63], v[170:173], v[202:205], v[60:63]
	v_mfma_f32_16x16x32_bf16 v[56:59], v[178:181], v[202:205], v[56:59]
	v_mfma_f32_16x16x32_bf16 v[44:47], v[170:173], v[214:217], v[44:47]
	v_mfma_f32_16x16x32_bf16 v[40:43], v[178:181], v[214:217], v[40:43]
	v_mfma_f32_16x16x32_bf16 v[28:31], v[170:173], v[222:225], v[28:31]
	v_mfma_f32_16x16x32_bf16 v[24:27], v[178:181], v[222:225], v[24:27]
	v_mfma_f32_16x16x32_bf16 v[12:15], v[170:173], v[230:233], v[12:15]
	v_mfma_f32_16x16x32_bf16 v[8:11], v[178:181], v[230:233], v[8:11]
	s_setprio 0
	s_setprio 1
	v_mfma_f32_16x16x32_bf16 v[52:55], v[182:185], v[198:201], v[52:55]
	v_mfma_f32_16x16x32_bf16 v[48:51], v[190:193], v[198:201], v[48:51]
	v_mfma_f32_16x16x32_bf16 v[36:39], v[182:185], v[206:209], v[36:39]
	v_mfma_f32_16x16x32_bf16 v[32:35], v[190:193], v[206:209], v[32:35]
	v_mfma_f32_16x16x32_bf16 v[20:23], v[182:185], v[218:221], v[20:23]
	v_mfma_f32_16x16x32_bf16 v[16:19], v[190:193], v[218:221], v[16:19]
	v_mfma_f32_16x16x32_bf16 v[4:7], v[182:185], v[226:229], v[4:7]
	v_mfma_f32_16x16x32_bf16 v[0:3], v[190:193], v[226:229], v[0:3]
	v_mfma_f32_16x16x32_bf16 v[52:55], v[186:189], v[202:205], v[52:55]
	v_mfma_f32_16x16x32_bf16 v[48:51], v[194:197], v[202:205], v[48:51]
	v_mfma_f32_16x16x32_bf16 v[36:39], v[186:189], v[214:217], v[36:39]
	v_mfma_f32_16x16x32_bf16 v[32:35], v[194:197], v[214:217], v[32:35]
	v_mfma_f32_16x16x32_bf16 v[20:23], v[186:189], v[222:225], v[20:23]
	v_mfma_f32_16x16x32_bf16 v[16:19], v[194:197], v[222:225], v[16:19]
	v_mfma_f32_16x16x32_bf16 v[4:7], v[186:189], v[230:233], v[4:7]
	v_mfma_f32_16x16x32_bf16 v[0:3], v[194:197], v[230:233], v[0:3]
	s_barrier
	s_setprio 0
	s_add_i32 s84, s84, 2
	s_add_u32 s6, s6, 0x100
	s_addc_u32 s7, s7, 0
	s_add_u32 s82, s82, 0x100
	s_addc_u32 s83, s83, 0
	s_cmp_gt_u32 s84, 13
	s_cbranch_scc0 .LBB0_148
	s_and_b64 vcc, exec, s[16:17]
	s_cbranch_vccz .LBB0_151
	s_barrier

; #define PG8_STAGE(bufoff, gbase, voff) do { _Pragma("unroll") for (int _i = 0; _i < 2; ++_i) \
;         __builtin_amdgcn_global_load_lds((const unsigned*)((const char*)(gbase) + (voff)[_i]), (PG8_LAS unsigned*)(lds + (bufoff) + ldsw + _i * 8192), 16, 0, 0); } while (0)
; #define PG8_LDA(dst, b, h) do { _Pragma("unroll") for (int m = 0; m < 4; ++m) _Pragma("unroll") for (int k = 0; k < 2; ++k) dst[m][k] = *(const PG8_LAS bf16x8*)(lds + PG8_SA(b, h) + aoff + m * 2048 + k * 1024); } while (0)
; #define PG8_LDB(dst, b, h) do { _Pragma("unroll") for (int n = 0; n < 2; ++n) _Pragma("unroll") for (int k = 0; k < 2; ++k) dst[n][k] = *(const PG8_LAS bf16x8*)(lds + PG8_SB(b, h) + boff + n * 2048 + k * 1024); } while (0)
; #define PG8_MMA(ai, bj, At, Bt) do { __builtin_amdgcn_s_setprio(1); _Pragma("unroll") for (int m = 0; m < 4; ++m) _Pragma("unroll") for (int n = 0; n < 2; ++n) _Pragma("unroll") for (int k = 0; k < 2; ++k) \
;         acc[ai][bj][m][n] = __builtin_amdgcn_mfma_f32_16x16x32_bf16(Bt[n][k], At[m][k], acc[ai][bj][m][n], 0, 0, 0); __builtin_amdgcn_s_setprio(0); } while (0)
; #define PG8_WAIT_V(n) asm volatile("s_waitcnt vmcnt(" #n ")" ::: "memory")
; #define PG8_WAIT_L(n) asm volatile("s_waitcnt lgkmcnt(" #n ")" ::: "memory")
; #define PG8_BAR __builtin_amdgcn_s_barrier()
; #define PG8_SCHED __builtin_amdgcn_sched_barrier(0)
; template <class Epi, class Sched, bool ALIGN_EPI = false, bool SP2 = false>
; __device__ __forceinline__ void gemm_phase(PG8_LAS unsigned char* lds, const Gemm g, const Sched& S, const Epi& E) {
;     ...
;             const char* a2 = last ? nA : cA + (size_t)(t + 2) * kstep; const char* b2 = last ? nB : cB + (size_t)(t + 2) * kstep;
;             const char* a3 = a2 + kstep; const char* b3 = b2 + kstep;
;             if (last && has_next) S.a_ready(nxt);
;             if constexpr (SP2) {
;             PG8_LDB(B0, 0, 0); PG8_LDB(B1, 0, 1); PG8_SCHED; PG8_LDA(At, 0, 0); PG8_STAGE(PG8_SA(1, 1), a1 + hstep, voffA);
;             PG8_WAIT_V(8); PG8_WAIT_L(0); PG8_BAR; PG8_MMA(0, 0, At, B0); PG8_MMA(0, 1, At, B1); PG8_BAR; PG8_SCHED;
;             PG8_LDA(At, 0, 1); PG8_STAGE(PG8_SB(0, 0), b2, voffB); PG8_STAGE(PG8_SB(0, 1), b2 + hstep, voffB); PG8_STAGE(PG8_SA(0, 0), a2, voffA);
.LBB0_378:
	ds_read_b128 v[128:131], v178
	ds_read_b128 v[132:135], v178 offset:1024
	ds_read_b128 v[136:139], v178 offset:2048
	ds_read_b128 v[140:143], v178 offset:3072
	ds_read_b128 v[170:173], v179
	ds_read_b128 v[174:177], v179 offset:1024
	ds_read_b128 v[182:185], v179 offset:2048
	ds_read_b128 v[186:189], v179 offset:3072
	s_add_u32 s4, s44, 0xfffc0080
	s_addc_u32 s5, s45, -1
	s_cmp_eq_u32 s86, 12
	s_cselect_b32 s73, s35, s5
	s_cselect_b32 s72, s41, s4
	s_cselect_b32 s47, s31, s94
	s_cselect_b32 s46, s92, s93
	v_lshl_add_u64 v[210:211], s[44:45], 0, v[154:155]
	s_add_i32 m0, s53, 0xc000
	ds_read_b128 v[190:193], v180
	ds_read_b128 v[194:197], v180 offset:1024
	ds_read_b128 v[198:201], v180 offset:2048
	ds_read_b128 v[202:205], v180 offset:3072
	ds_read_b128 v[206:209], v180 offset:4096
	ds_read_b128 v[214:217], v180 offset:5120
	ds_read_b128 v[218:221], v180 offset:6144
	ds_read_b128 v[222:225], v180 offset:7168
	global_load_lds_dwordx4 v[210:211], off
	v_lshl_add_u64 v[210:211], s[44:45], 0, v[164:165]
	s_add_i32 m0, s53, 0xe000
	s_nop 0
	global_load_lds_dwordx4 v[210:211], off
	s_waitcnt vmcnt(8)
	s_waitcnt lgkmcnt(0)
	s_barrier
	s_setprio 1
	v_mfma_f32_16x16x32_bf16 v[124:127], v[128:131], v[190:193], v[124:127]
	v_mfma_f32_16x16x32_bf16 v[120:123], v[136:139], v[190:193], v[120:123]
	v_mfma_f32_16x16x32_bf16 v[108:111], v[128:131], v[198:201], v[108:111]
	v_mfma_f32_16x16x32_bf16 v[104:107], v[136:139], v[198:201], v[104:107]
	v_mfma_f32_16x16x32_bf16 v[92:95], v[128:131], v[206:209], v[92:95]
	v_mfma_f32_16x16x32_bf16 v[88:91], v[136:139], v[206:209], v[88:91]
	v_mfma_f32_16x16x32_bf16 v[76:79], v[128:131], v[218:221], v[76:79]
	v_mfma_f32_16x16x32_bf16 v[72:75], v[136:139], v[218:221], v[72:75]
	v_mfma_f32_16x16x32_bf16 v[124:127], v[132:135], v[194:197], v[124:127]
	v_mfma_f32_16x16x32_bf16 v[120:123], v[140:143], v[194:197], v[120:123]
	v_mfma_f32_16x16x32_bf16 v[108:111], v[132:135], v[202:205], v[108:111]
	v_mfma_f32_16x16x32_bf16 v[104:107], v[140:143], v[202:205], v[104:107]
	v_mfma_f32_16x16x32_bf16 v[92:95], v[132:135], v[214:217], v[92:95]
	v_mfma_f32_16x16x32_bf16 v[88:91], v[140:143], v[214:217], v[88:91]
	v_mfma_f32_16x16x32_bf16 v[76:79], v[132:135], v[222:225], v[76:79]
	v_mfma_f32_16x16x32_bf16 v[72:75], v[140:143], v[222:225], v[72:75]
	s_setprio 0
	s_setprio 1
	v_mfma_f32_16x16x32_bf16 v[116:119], v[170:173], v[190:193], v[116:119]
	v_mfma_f32_16x16x32_bf16 v[112:115], v[182:185], v[190:193], v[112:115]
	v_mfma_f32_16x16x32_bf16 v[100:103], v[170:173], v[198:201], v[100:103]
	v_mfma_f32_16x16x32_bf16 v[96:99], v[182:185], v[198:201], v[96:99]
	v_mfma_f32_16x16x32_bf16 v[84:87], v[170:173], v[206:209], v[84:87]
	v_mfma_f32_16x16x32_bf16 v[80:83], v[182:185], v[206:209], v[80:83]
	v_mfma_f32_16x16x32_bf16 v[68:71], v[170:173], v[218:221], v[68:71]
	v_mfma_f32_16x16x32_bf16 v[64:67], v[182:185], v[218:221], v[64:67]
	v_mfma_f32_16x16x32_bf16 v[116:119], v[174:177], v[194:197], v[116:119]
	v_mfma_f32_16x16x32_bf16 v[112:115], v[186:189], v[194:197], v[112:115]
	v_mfma_f32_16x16x32_bf16 v[100:103], v[174:177], v[202:205], v[100:103]
	v_mfma_f32_16x16x32_bf16 v[96:99], v[186:189], v[202:205], v[96:99]
	v_mfma_f32_16x16x32_bf16 v[84:87], v[174:177], v[214:217], v[84:87]
	v_mfma_f32_16x16x32_bf16 v[80:83], v[186:189], v[214:217], v[80:83]
	v_mfma_f32_16x16x32_bf16 v[68:71], v[174:177], v[222:225], v[68:71]
	v_mfma_f32_16x16x32_bf16 v[64:67], v[186:189], v[222:225], v[64:67]
	s_barrier
	s_setprio 0
	s_add_i32 s4, s85, s49
	v_lshl_add_u64 v[210:211], s[46:47], 0, v[146:147]
	s_mov_b32 m0, s4
	ds_read_b128 v[190:193], v180 offset:16384
	ds_read_b128 v[194:197], v180 offset:17408
	ds_read_b128 v[198:201], v180 offset:18432
	ds_read_b128 v[202:205], v180 offset:19456
	ds_read_b128 v[206:209], v180 offset:20480
	ds_read_b128 v[214:217], v180 offset:21504
	ds_read_b128 v[218:221], v180 offset:22528
	ds_read_b128 v[222:225], v180 offset:23552
	global_load_lds_dwordx4 v[210:211], off
	s_add_i32 m0, s4, 0x2000
	s_add_u32 s4, s46, 0x40000
	v_lshl_add_u64 v[226:227], s[46:47], 0, v[150:151]
	s_addc_u32 s5, s47, 0
	s_add_i32 s95, s89, s49
	global_load_lds_dwordx4 v[226:227], off
	v_lshl_add_u64 v[228:229], s[4:5], 0, v[146:147]
	s_mov_b32 m0, s95
	v_lshl_add_u64 v[230:231], s[72:73], 0, v[148:149]
	global_load_lds_dwordx4 v[228:229], off
	v_lshl_add_u64 v[228:229], s[4:5], 0, v[150:151]
	s_add_i32 m0, s95, 0x2000
	s_nop 0
	global_load_lds_dwordx4 v[228:229], off
	v_lshl_add_u64 v[228:229], s[72:73], 0, v[144:145]
	s_mov_b32 m0, s53
	s_nop 0
	global_load_lds_dwordx4 v[228:229], off
	s_mov_b32 m0, s74
	s_nop 0
	global_load_lds_dwordx4 v[230:231], off
	s_waitcnt vmcnt(8)
	s_waitcnt lgkmcnt(0)
	s_barrier
; #define PG8_STAGE(bufoff, gbase, voff) do { _Pragma("unroll") for (int _i = 0; _i < 2; ++_i) \
;         __builtin_amdgcn_global_load_lds((const unsigned*)((const char*)(gbase) + (voff)[_i]), (PG8_LAS unsigned*)(lds + (bufoff) + ldsw + _i * 8192), 16, 0, 0); } while (0)
; #define PG8_LDA(dst, b, h) do { _Pragma("unroll") for (int m = 0; m < 4; ++m) _Pragma("unroll") for (int k = 0; k < 2; ++k) dst[m][k] = *(const PG8_LAS bf16x8*)(lds + PG8_SA(b, h) + aoff + m * 2048 + k * 1024); } while (0)
; #define PG8_LDB(dst, b, h) do { _Pragma("unroll") for (int n = 0; n < 2; ++n) _Pragma("unroll") for (int k = 0; k < 2; ++k) dst[n][k] = *(const PG8_LAS bf16x8*)(lds + PG8_SB(b, h) + boff + n * 2048 + k * 1024); } while (0)
; #define PG8_MMA(ai, bj, At, Bt) do { __builtin_amdgcn_s_setprio(1); _Pragma("unroll") for (int m = 0; m < 4; ++m) _Pragma("unroll") for (int n = 0; n < 2; ++n) _Pragma("unroll") for (int k = 0; k < 2; ++k) \
;         acc[ai][bj][m][n] = __builtin_amdgcn_mfma_f32_16x16x32_bf16(Bt[n][k], At[m][k], acc[ai][bj][m][n], 0, 0, 0); __builtin_amdgcn_s_setprio(0); } while (0)
; #define PG8_WAIT_V(n) asm volatile("s_waitcnt vmcnt(" #n ")" ::: "memory")
; #define PG8_WAIT_L(n) asm volatile("s_waitcnt lgkmcnt(" #n ")" ::: "memory")
; #define PG8_BAR __builtin_amdgcn_s_barrier()
; #define PG8_SCHED __builtin_amdgcn_sched_barrier(0)
; template <class Epi, class Sched, bool ALIGN_EPI = false, bool SP2 = false>
; __device__ __forceinline__ void gemm_phase(PG8_LAS unsigned char* lds, const Gemm g, const Sched& S, const Epi& E) {
;     ...
;             PG8_WAIT_V(8); PG8_WAIT_L(0); PG8_BAR; PG8_MMA(1, 0, At, B0); PG8_MMA(1, 1, At, B1); PG8_BAR; PG8_SCHED;
;             PG8_LDB(B0, 1, 0); PG8_LDB(B1, 1, 1); PG8_SCHED; PG8_LDA(At, 1, 0); PG8_STAGE(PG8_SA(0, 1), a2 + hstep, voffA);
;             PG8_WAIT_V(8); PG8_WAIT_L(0); PG8_BAR; PG8_MMA(0, 0, At, B0); PG8_MMA(0, 1, At, B1); PG8_BAR; PG8_SCHED;
	s_setprio 1
	v_mfma_f32_16x16x32_bf16 v[60:63], v[128:131], v[190:193], v[60:63]
	v_mfma_f32_16x16x32_bf16 v[56:59], v[136:139], v[190:193], v[56:59]
	v_mfma_f32_16x16x32_bf16 v[44:47], v[128:131], v[198:201], v[44:47]
	v_mfma_f32_16x16x32_bf16 v[40:43], v[136:139], v[198:201], v[40:43]
	v_mfma_f32_16x16x32_bf16 v[28:31], v[128:131], v[206:209], v[28:31]
	v_mfma_f32_16x16x32_bf16 v[24:27], v[136:139], v[206:209], v[24:27]
	v_mfma_f32_16x16x32_bf16 v[12:15], v[128:131], v[218:221], v[12:15]
	v_mfma_f32_16x16x32_bf16 v[8:11], v[136:139], v[218:221], v[8:11]
	v_mfma_f32_16x16x32_bf16 v[60:63], v[132:135], v[194:197], v[60:63]
	v_mfma_f32_16x16x32_bf16 v[56:59], v[140:143], v[194:197], v[56:59]
	v_mfma_f32_16x16x32_bf16 v[44:47], v[132:135], v[202:205], v[44:47]
	v_mfma_f32_16x16x32_bf16 v[40:43], v[140:143], v[202:205], v[40:43]
	v_mfma_f32_16x16x32_bf16 v[28:31], v[132:135], v[214:217], v[28:31]
	v_mfma_f32_16x16x32_bf16 v[24:27], v[140:143], v[214:217], v[24:27]
	v_mfma_f32_16x16x32_bf16 v[12:15], v[132:135], v[222:225], v[12:15]
	v_mfma_f32_16x16x32_bf16 v[8:11], v[140:143], v[222:225], v[8:11]
	s_setprio 0
	s_setprio 1
	v_mfma_f32_16x16x32_bf16 v[52:55], v[170:173], v[190:193], v[52:55]
	v_mfma_f32_16x16x32_bf16 v[48:51], v[182:185], v[190:193], v[48:51]
	v_mfma_f32_16x16x32_bf16 v[36:39], v[170:173], v[198:201], v[36:39]
	v_mfma_f32_16x16x32_bf16 v[32:35], v[182:185], v[198:201], v[32:35]
	v_mfma_f32_16x16x32_bf16 v[20:23], v[170:173], v[206:209], v[20:23]
	v_mfma_f32_16x16x32_bf16 v[16:19], v[182:185], v[206:209], v[16:19]
	v_mfma_f32_16x16x32_bf16 v[4:7], v[170:173], v[218:221], v[4:7]
	v_mfma_f32_16x16x32_bf16 v[0:3], v[182:185], v[218:221], v[0:3]
	v_mfma_f32_16x16x32_bf16 v[52:55], v[174:177], v[194:197], v[52:55]
	v_mfma_f32_16x16x32_bf16 v[48:51], v[186:189], v[194:197], v[48:51]
	v_mfma_f32_16x16x32_bf16 v[36:39], v[174:177], v[202:205], v[36:39]
	v_mfma_f32_16x16x32_bf16 v[32:35], v[186:189], v[202:205], v[32:35]
	v_mfma_f32_16x16x32_bf16 v[20:23], v[174:177], v[214:217], v[20:23]
	v_mfma_f32_16x16x32_bf16 v[16:19], v[186:189], v[214:217], v[16:19]
	v_mfma_f32_16x16x32_bf16 v[4:7], v[174:177], v[222:225], v[4:7]
	v_mfma_f32_16x16x32_bf16 v[0:3], v[186:189], v[222:225], v[0:3]
	s_barrier
	s_setprio 0
	s_add_i32 s95, 0, 0x18000
	s_add_i32 s96, 0, 0x1c000
	v_add_u32_e32 v140, s95, v159
	v_add_u32_e32 v186, s96, v159
	ds_read_b128 v[128:131], v140
	ds_read_b128 v[132:135], v140 offset:1024
	ds_read_b128 v[136:139], v140 offset:2048
	ds_read_b128 v[140:143], v140 offset:3072
	ds_read_b128 v[170:173], v186
	ds_read_b128 v[174:177], v186 offset:1024
	ds_read_b128 v[182:185], v186 offset:2048
	ds_read_b128 v[186:189], v186 offset:3072
	s_add_u32 s4, s72, 0x40000
	s_addc_u32 s5, s73, 0
	s_mov_b32 m0, s75
	v_lshl_add_u64 v[232:233], s[4:5], 0, v[144:145]
	ds_read_b128 v[190:193], v180 offset:32768
	ds_read_b128 v[194:197], v180 offset:33792
	ds_read_b128 v[198:201], v180 offset:34816
	ds_read_b128 v[202:205], v180 offset:35840
	ds_read_b128 v[206:209], v180 offset:36864
	ds_read_b128 v[214:217], v180 offset:37888
	ds_read_b128 v[218:221], v180 offset:38912
	ds_read_b128 v[222:225], v180 offset:39936
	global_load_lds_dwordx4 v[232:233], off
	v_lshl_add_u64 v[232:233], s[4:5], 0, v[148:149]
	s_mov_b32 m0, s76
	s_nop 0
	global_load_lds_dwordx4 v[232:233], off
	s_waitcnt vmcnt(8)
	s_waitcnt lgkmcnt(0)
	s_barrier
	s_setprio 1
	v_mfma_f32_16x16x32_bf16 v[124:127], v[128:131], v[190:193], v[124:127]
	v_mfma_f32_16x16x32_bf16 v[120:123], v[136:139], v[190:193], v[120:123]
	v_mfma_f32_16x16x32_bf16 v[108:111], v[128:131], v[198:201], v[108:111]
	v_mfma_f32_16x16x32_bf16 v[104:107], v[136:139], v[198:201], v[104:107]
	v_mfma_f32_16x16x32_bf16 v[92:95], v[128:131], v[206:209], v[92:95]
	v_mfma_f32_16x16x32_bf16 v[88:91], v[136:139], v[206:209], v[88:91]
	v_mfma_f32_16x16x32_bf16 v[76:79], v[128:131], v[218:221], v[76:79]
	v_mfma_f32_16x16x32_bf16 v[72:75], v[136:139], v[218:221], v[72:75]
	v_mfma_f32_16x16x32_bf16 v[124:127], v[132:135], v[194:197], v[124:127]
	v_mfma_f32_16x16x32_bf16 v[120:123], v[140:143], v[194:197], v[120:123]
	v_mfma_f32_16x16x32_bf16 v[108:111], v[132:135], v[202:205], v[108:111]
	v_mfma_f32_16x16x32_bf16 v[104:107], v[140:143], v[202:205], v[104:107]
	v_mfma_f32_16x16x32_bf16 v[92:95], v[132:135], v[214:217], v[92:95]
	v_mfma_f32_16x16x32_bf16 v[88:91], v[140:143], v[214:217], v[88:91]
	v_mfma_f32_16x16x32_bf16 v[76:79], v[132:135], v[222:225], v[76:79]
	v_mfma_f32_16x16x32_bf16 v[72:75], v[140:143], v[222:225], v[72:75]
	s_setprio 0
	s_setprio 1
	v_mfma_f32_16x16x32_bf16 v[116:119], v[170:173], v[190:193], v[116:119]
	v_mfma_f32_16x16x32_bf16 v[112:115], v[182:185], v[190:193], v[112:115]
	v_mfma_f32_16x16x32_bf16 v[100:103], v[170:173], v[198:201], v[100:103]
	v_mfma_f32_16x16x32_bf16 v[96:99], v[182:185], v[198:201], v[96:99]
	v_mfma_f32_16x16x32_bf16 v[84:87], v[170:173], v[206:209], v[84:87]
	v_mfma_f32_16x16x32_bf16 v[80:83], v[182:185], v[206:209], v[80:83]
	v_mfma_f32_16x16x32_bf16 v[68:71], v[170:173], v[218:221], v[68:71]
	v_mfma_f32_16x16x32_bf16 v[64:67], v[182:185], v[218:221], v[64:67]
	v_mfma_f32_16x16x32_bf16 v[116:119], v[174:177], v[194:197], v[116:119]
	v_mfma_f32_16x16x32_bf16 v[112:115], v[186:189], v[194:197], v[112:115]
	v_mfma_f32_16x16x32_bf16 v[100:103], v[174:177], v[202:205], v[100:103]
	v_mfma_f32_16x16x32_bf16 v[96:99], v[186:189], v[202:205], v[96:99]
	v_mfma_f32_16x16x32_bf16 v[84:87], v[174:177], v[214:217], v[84:87]
	v_mfma_f32_16x16x32_bf16 v[80:83], v[186:189], v[214:217], v[80:83]
	v_mfma_f32_16x16x32_bf16 v[68:71], v[174:177], v[222:225], v[68:71]
	v_mfma_f32_16x16x32_bf16 v[64:67], v[186:189], v[222:225], v[64:67]
	s_barrier
; #define PG8_STAGE(bufoff, gbase, voff) do { _Pragma("unroll") for (int _i = 0; _i < 2; ++_i) \
;         __builtin_amdgcn_global_load_lds((const unsigned*)((const char*)(gbase) + (voff)[_i]), (PG8_LAS unsigned*)(lds + (bufoff) + ldsw + _i * 8192), 16, 0, 0); } while (0)
; #define PG8_LDA(dst, b, h) do { _Pragma("unroll") for (int m = 0; m < 4; ++m) _Pragma("unroll") for (int k = 0; k < 2; ++k) dst[m][k] = *(const PG8_LAS bf16x8*)(lds + PG8_SA(b, h) + aoff + m * 2048 + k * 1024); } while (0)
; #define PG8_MMA(ai, bj, At, Bt) do { __builtin_amdgcn_s_setprio(1); _Pragma("unroll") for (int m = 0; m < 4; ++m) _Pragma("unroll") for (int n = 0; n < 2; ++n) _Pragma("unroll") for (int k = 0; k < 2; ++k) \
;         acc[ai][bj][m][n] = __builtin_amdgcn_mfma_f32_16x16x32_bf16(Bt[n][k], At[m][k], acc[ai][bj][m][n], 0, 0, 0); __builtin_amdgcn_s_setprio(0); } while (0)
; #define PG8_WAIT_V(n) asm volatile("s_waitcnt vmcnt(" #n ")" ::: "memory")
; #define PG8_WAIT_L(n) asm volatile("s_waitcnt lgkmcnt(" #n ")" ::: "memory")
; #define PG8_BAR __builtin_amdgcn_s_barrier()
; #define PG8_SCHED __builtin_amdgcn_sched_barrier(0)
; template <class Epi, class Sched, bool ALIGN_EPI = false, bool SP2 = false>
; __device__ __forceinline__ void gemm_phase(PG8_LAS unsigned char* lds, const Gemm g, const Sched& S, const Epi& E) {
;     ...
;             PG8_LDA(At, 1, 1); PG8_STAGE(PG8_SB(1, 0), b3, voffB); PG8_STAGE(PG8_SB(1, 1), b3 + hstep, voffB); PG8_STAGE(PG8_SA(1, 0), a3, voffA);
;             PG8_WAIT_V(8); PG8_WAIT_L(0); PG8_BAR; PG8_MMA(1, 0, At, B0); PG8_MMA(1, 1, At, B1); PG8_BAR; PG8_SCHED;
	s_setprio 0
	s_add_i32 s4, s95, s49
	v_lshl_add_u64 v[210:211], v[210:211], 0, s[26:27]
	s_mov_b32 m0, s4
	ds_read_b128 v[190:193], v180 offset:49152
	ds_read_b128 v[194:197], v180 offset:50176
	ds_read_b128 v[198:201], v180 offset:51200
	ds_read_b128 v[202:205], v180 offset:52224
	ds_read_b128 v[206:209], v180 offset:53248
	ds_read_b128 v[214:217], v180 offset:54272
	ds_read_b128 v[218:221], v180 offset:55296
	ds_read_b128 v[222:225], v180 offset:56320
	global_load_lds_dwordx4 v[210:211], off
	s_add_i32 m0, s4, 0x2000
	s_add_u32 s4, s46, 0x40080
	v_lshl_add_u64 v[210:211], v[226:227], 0, s[26:27]
	s_addc_u32 s5, s47, 0
	s_add_i32 s46, s96, s49
	global_load_lds_dwordx4 v[210:211], off
	v_lshl_add_u64 v[210:211], s[4:5], 0, v[146:147]
	s_mov_b32 m0, s46
	s_nop 0
	global_load_lds_dwordx4 v[210:211], off
	v_lshl_add_u64 v[210:211], s[4:5], 0, v[150:151]
	s_add_i32 m0, s46, 0x2000
	s_nop 0
	global_load_lds_dwordx4 v[210:211], off
	v_lshl_add_u64 v[210:211], v[228:229], 0, s[26:27]
	s_mov_b32 m0, s78
	s_nop 0
	global_load_lds_dwordx4 v[210:211], off
	v_lshl_add_u64 v[210:211], v[230:231], 0, s[26:27]
	s_mov_b32 m0, s79
	s_nop 0
	global_load_lds_dwordx4 v[210:211], off
	s_waitcnt vmcnt(8)
	s_waitcnt lgkmcnt(0)
	s_barrier
	s_setprio 1
	v_mfma_f32_16x16x32_bf16 v[60:63], v[128:131], v[190:193], v[60:63]
	v_mfma_f32_16x16x32_bf16 v[56:59], v[136:139], v[190:193], v[56:59]
	v_mfma_f32_16x16x32_bf16 v[44:47], v[128:131], v[198:201], v[44:47]
	v_mfma_f32_16x16x32_bf16 v[40:43], v[136:139], v[198:201], v[40:43]
	v_mfma_f32_16x16x32_bf16 v[28:31], v[128:131], v[206:209], v[28:31]
	v_mfma_f32_16x16x32_bf16 v[24:27], v[136:139], v[206:209], v[24:27]
	v_mfma_f32_16x16x32_bf16 v[12:15], v[128:131], v[218:221], v[12:15]
	v_mfma_f32_16x16x32_bf16 v[8:11], v[136:139], v[218:221], v[8:11]
	v_mfma_f32_16x16x32_bf16 v[60:63], v[132:135], v[194:197], v[60:63]
	v_mfma_f32_16x16x32_bf16 v[56:59], v[140:143], v[194:197], v[56:59]
	v_mfma_f32_16x16x32_bf16 v[44:47], v[132:135], v[202:205], v[44:47]
	v_mfma_f32_16x16x32_bf16 v[40:43], v[140:143], v[202:205], v[40:43]
	v_mfma_f32_16x16x32_bf16 v[28:31], v[132:135], v[214:217], v[28:31]
	v_mfma_f32_16x16x32_bf16 v[24:27], v[140:143], v[214:217], v[24:27]
	v_mfma_f32_16x16x32_bf16 v[12:15], v[132:135], v[222:225], v[12:15]
	v_mfma_f32_16x16x32_bf16 v[8:11], v[140:143], v[222:225], v[8:11]
	s_setprio 0
	s_setprio 1
	v_mfma_f32_16x16x32_bf16 v[52:55], v[170:173], v[190:193], v[52:55]
	v_mfma_f32_16x16x32_bf16 v[48:51], v[182:185], v[190:193], v[48:51]
	v_mfma_f32_16x16x32_bf16 v[36:39], v[170:173], v[198:201], v[36:39]
	v_mfma_f32_16x16x32_bf16 v[32:35], v[182:185], v[198:201], v[32:35]
	v_mfma_f32_16x16x32_bf16 v[20:23], v[170:173], v[206:209], v[20:23]
	v_mfma_f32_16x16x32_bf16 v[16:19], v[182:185], v[206:209], v[16:19]
	v_mfma_f32_16x16x32_bf16 v[4:7], v[170:173], v[218:221], v[4:7]
	v_mfma_f32_16x16x32_bf16 v[0:3], v[182:185], v[218:221], v[0:3]
	v_mfma_f32_16x16x32_bf16 v[52:55], v[174:177], v[194:197], v[52:55]
	v_mfma_f32_16x16x32_bf16 v[48:51], v[186:189], v[194:197], v[48:51]
	v_mfma_f32_16x16x32_bf16 v[36:39], v[174:177], v[202:205], v[36:39]
	v_mfma_f32_16x16x32_bf16 v[32:35], v[186:189], v[202:205], v[32:35]
	v_mfma_f32_16x16x32_bf16 v[20:23], v[174:177], v[214:217], v[20:23]
	v_mfma_f32_16x16x32_bf16 v[16:19], v[186:189], v[214:217], v[16:19]
	v_mfma_f32_16x16x32_bf16 v[4:7], v[174:177], v[222:225], v[4:7]
	v_mfma_f32_16x16x32_bf16 v[0:3], v[186:189], v[222:225], v[0:3]
	s_barrier
	s_setprio 0
	s_add_i32 s86, s86, 2
	s_add_u32 s44, s44, 0x100
	s_addc_u32 s45, s45, 0
	s_add_u32 s93, s93, 0x100
	s_addc_u32 s94, s94, 0
	s_cmp_gt_u32 s86, 13
	s_cbranch_scc0 .LBB0_378
	s_and_b64 vcc, exec, s[28:29]
	s_cbranch_vccz .LBB0_381
	s_barrier

; #define PG8_STAGE(bufoff, gbase, voff) do { _Pragma("unroll") for (int _i = 0; _i < 2; ++_i) \
;         __builtin_amdgcn_global_load_lds((const unsigned*)((const char*)(gbase) + (voff)[_i]), (PG8_LAS unsigned*)(lds + (bufoff) + ldsw + _i * 8192), 16, 0, 0); } while (0)
; #define PG8_LDA(dst, b, h) do { _Pragma("unroll") for (int m = 0; m < 4; ++m) _Pragma("unroll") for (int k = 0; k < 2; ++k) dst[m][k] = *(const PG8_LAS bf16x8*)(lds + PG8_SA(b, h) + aoff + m * 2048 + k * 1024); } while (0)
; #define PG8_LDB(dst, b, h) do { _Pragma("unroll") for (int n = 0; n < 2; ++n) _Pragma("unroll") for (int k = 0; k < 2; ++k) dst[n][k] = *(const PG8_LAS bf16x8*)(lds + PG8_SB(b, h) + boff + n * 2048 + k * 1024); } while (0)
; #define PG8_MMA(ai, bj, At, Bt) do { __builtin_amdgcn_s_setprio(1); _Pragma("unroll") for (int m = 0; m < 4; ++m) _Pragma("unroll") for (int n = 0; n < 2; ++n) _Pragma("unroll") for (int k = 0; k < 2; ++k) \
;         acc[ai][bj][m][n] = __builtin_amdgcn_mfma_f32_16x16x32_bf16(Bt[n][k], At[m][k], acc[ai][bj][m][n], 0, 0, 0); __builtin_amdgcn_s_setprio(0); } while (0)
; #define PG8_WAIT_V(n) asm volatile("s_waitcnt vmcnt(" #n ")" ::: "memory")
; #define PG8_WAIT_L(n) asm volatile("s_waitcnt lgkmcnt(" #n ")" ::: "memory")
; #define PG8_BAR __builtin_amdgcn_s_barrier()
; #define PG8_SCHED __builtin_amdgcn_sched_barrier(0)
; template <class Epi, class Sched, bool ALIGN_EPI = false, bool SP2 = false>
; __device__ __forceinline__ void gemm_phase(PG8_LAS unsigned char* lds, const Gemm g, const Sched& S, const Epi& E) {
;     ...
;             const char* a2 = last ? nA : cA + (size_t)(t + 2) * kstep; const char* b2 = last ? nB : cB + (size_t)(t + 2) * kstep;
;             const char* a3 = a2 + kstep; const char* b3 = b2 + kstep;
;             if (last && has_next) S.a_ready(nxt);
;             if constexpr (SP2) {
;             PG8_LDB(B0, 0, 0); PG8_LDB(B1, 0, 1); PG8_SCHED; PG8_LDA(At, 0, 0); PG8_STAGE(PG8_SA(1, 1), a1 + hstep, voffA);
;             PG8_WAIT_V(8); PG8_WAIT_L(0); PG8_BAR; PG8_MMA(0, 0, At, B0); PG8_MMA(0, 1, At, B1); PG8_BAR; PG8_SCHED;
;             PG8_LDA(At, 0, 1); PG8_STAGE(PG8_SB(0, 0), b2, voffB); PG8_STAGE(PG8_SB(0, 1), b2 + hstep, voffB); PG8_STAGE(PG8_SA(0, 0), a2, voffA);
.LBB0_469:
	ds_read_b128 v[146:149], v179
	ds_read_b128 v[164:167], v179 offset:1024
	ds_read_b128 v[168:171], v179 offset:2048
	ds_read_b128 v[172:175], v179 offset:3072
	ds_read_b128 v[184:187], v180
	ds_read_b128 v[188:191], v180 offset:1024
	ds_read_b128 v[192:195], v180 offset:2048
	ds_read_b128 v[196:199], v180 offset:3072
	s_add_u32 s4, s34, 0xfffc0080
	s_addc_u32 s5, s35, -1
	s_cmp_eq_u32 s86, 12
	s_cselect_b32 s39, s9, s5
	s_cselect_b32 s38, s27, s4
	s_cselect_b32 s37, s25, s89
	s_cselect_b32 s36, s84, s85
	v_lshl_add_u64 v[150:151], s[34:35], 0, v[138:139]
	s_add_i32 m0, s47, 0xc000
	ds_read_b128 v[200:203], v181
	ds_read_b128 v[204:207], v181 offset:1024
	ds_read_b128 v[208:211], v181 offset:2048
	ds_read_b128 v[214:217], v181 offset:3072
	ds_read_b128 v[218:221], v181 offset:4096
	ds_read_b128 v[222:225], v181 offset:5120
	ds_read_b128 v[226:229], v181 offset:6144
	ds_read_b128 v[230:233], v181 offset:7168
	global_load_lds_dwordx4 v[150:151], off
	v_lshl_add_u64 v[150:151], s[34:35], 0, v[140:141]
	s_add_i32 m0, s47, 0xe000
	s_nop 0
	global_load_lds_dwordx4 v[150:151], off
	s_waitcnt vmcnt(8)
	s_waitcnt lgkmcnt(0)
	s_barrier
	s_setprio 1
	v_mfma_f32_16x16x32_bf16 v[124:127], v[146:149], v[200:203], v[124:127]
	v_mfma_f32_16x16x32_bf16 v[116:119], v[168:171], v[200:203], v[116:119]
	v_mfma_f32_16x16x32_bf16 v[108:111], v[146:149], v[208:211], v[108:111]
	v_mfma_f32_16x16x32_bf16 v[100:103], v[168:171], v[208:211], v[100:103]
	v_mfma_f32_16x16x32_bf16 v[92:95], v[146:149], v[218:221], v[92:95]
	v_mfma_f32_16x16x32_bf16 v[84:87], v[168:171], v[218:221], v[84:87]
	v_mfma_f32_16x16x32_bf16 v[76:79], v[146:149], v[226:229], v[76:79]
	v_mfma_f32_16x16x32_bf16 v[68:71], v[168:171], v[226:229], v[68:71]
	v_mfma_f32_16x16x32_bf16 v[124:127], v[164:167], v[204:207], v[124:127]
	v_mfma_f32_16x16x32_bf16 v[116:119], v[172:175], v[204:207], v[116:119]
	v_mfma_f32_16x16x32_bf16 v[108:111], v[164:167], v[214:217], v[108:111]
	v_mfma_f32_16x16x32_bf16 v[100:103], v[172:175], v[214:217], v[100:103]
	v_mfma_f32_16x16x32_bf16 v[92:95], v[164:167], v[222:225], v[92:95]
	v_mfma_f32_16x16x32_bf16 v[84:87], v[172:175], v[222:225], v[84:87]
	v_mfma_f32_16x16x32_bf16 v[76:79], v[164:167], v[230:233], v[76:79]
	v_mfma_f32_16x16x32_bf16 v[68:71], v[172:175], v[230:233], v[68:71]
	s_setprio 0
	s_setprio 1
	v_mfma_f32_16x16x32_bf16 v[120:123], v[184:187], v[200:203], v[120:123]
	v_mfma_f32_16x16x32_bf16 v[112:115], v[192:195], v[200:203], v[112:115]
	v_mfma_f32_16x16x32_bf16 v[104:107], v[184:187], v[208:211], v[104:107]
	v_mfma_f32_16x16x32_bf16 v[96:99], v[192:195], v[208:211], v[96:99]
	v_mfma_f32_16x16x32_bf16 v[88:91], v[184:187], v[218:221], v[88:91]
	v_mfma_f32_16x16x32_bf16 v[80:83], v[192:195], v[218:221], v[80:83]
	v_mfma_f32_16x16x32_bf16 v[72:75], v[184:187], v[226:229], v[72:75]
	v_mfma_f32_16x16x32_bf16 v[64:67], v[192:195], v[226:229], v[64:67]
	v_mfma_f32_16x16x32_bf16 v[120:123], v[188:191], v[204:207], v[120:123]
	v_mfma_f32_16x16x32_bf16 v[112:115], v[196:199], v[204:207], v[112:115]
	v_mfma_f32_16x16x32_bf16 v[104:107], v[188:191], v[214:217], v[104:107]
	v_mfma_f32_16x16x32_bf16 v[96:99], v[196:199], v[214:217], v[96:99]
	v_mfma_f32_16x16x32_bf16 v[88:91], v[188:191], v[222:225], v[88:91]
	v_mfma_f32_16x16x32_bf16 v[80:83], v[196:199], v[222:225], v[80:83]
	v_mfma_f32_16x16x32_bf16 v[72:75], v[188:191], v[230:233], v[72:75]
	v_mfma_f32_16x16x32_bf16 v[64:67], v[196:199], v[230:233], v[64:67]
	s_barrier
	s_setprio 0
	s_add_i32 s4, s79, s44
	v_lshl_add_u64 v[150:151], s[36:37], 0, v[132:133]
	s_mov_b32 m0, s4
	ds_read_b128 v[200:203], v181 offset:16384
	ds_read_b128 v[204:207], v181 offset:17408
	ds_read_b128 v[208:211], v181 offset:18432
	ds_read_b128 v[214:217], v181 offset:19456
	ds_read_b128 v[218:221], v181 offset:20480
	ds_read_b128 v[222:225], v181 offset:21504
	ds_read_b128 v[226:229], v181 offset:22528
	ds_read_b128 v[230:233], v181 offset:23552
	global_load_lds_dwordx4 v[150:151], off
	s_add_i32 m0, s4, 0x2000
	s_add_u32 s4, s36, 0x40000
	v_lshl_add_u64 v[154:155], s[36:37], 0, v[128:129]
	s_addc_u32 s5, s37, 0
	s_add_i32 s90, s80, s44
	global_load_lds_dwordx4 v[154:155], off
	v_lshl_add_u64 v[176:177], s[4:5], 0, v[132:133]
	s_mov_b32 m0, s90
	v_lshl_add_u64 v[234:235], s[38:39], 0, v[130:131]
	global_load_lds_dwordx4 v[176:177], off
	v_lshl_add_u64 v[176:177], s[4:5], 0, v[128:129]
	s_add_i32 m0, s90, 0x2000
	s_nop 0
	global_load_lds_dwordx4 v[176:177], off
	v_lshl_add_u64 v[176:177], s[38:39], 0, v[134:135]
	s_mov_b32 m0, s47
	s_nop 0
	global_load_lds_dwordx4 v[176:177], off
	s_mov_b32 m0, s49
	s_nop 0
	global_load_lds_dwordx4 v[234:235], off
	s_waitcnt vmcnt(8)
	s_waitcnt lgkmcnt(0)
	s_barrier
; #define PG8_STAGE(bufoff, gbase, voff) do { _Pragma("unroll") for (int _i = 0; _i < 2; ++_i) \
;         __builtin_amdgcn_global_load_lds((const unsigned*)((const char*)(gbase) + (voff)[_i]), (PG8_LAS unsigned*)(lds + (bufoff) + ldsw + _i * 8192), 16, 0, 0); } while (0)
; #define PG8_LDA(dst, b, h) do { _Pragma("unroll") for (int m = 0; m < 4; ++m) _Pragma("unroll") for (int k = 0; k < 2; ++k) dst[m][k] = *(const PG8_LAS bf16x8*)(lds + PG8_SA(b, h) + aoff + m * 2048 + k * 1024); } while (0)
; #define PG8_LDB(dst, b, h) do { _Pragma("unroll") for (int n = 0; n < 2; ++n) _Pragma("unroll") for (int k = 0; k < 2; ++k) dst[n][k] = *(const PG8_LAS bf16x8*)(lds + PG8_SB(b, h) + boff + n * 2048 + k * 1024); } while (0)
; #define PG8_MMA(ai, bj, At, Bt) do { __builtin_amdgcn_s_setprio(1); _Pragma("unroll") for (int m = 0; m < 4; ++m) _Pragma("unroll") for (int n = 0; n < 2; ++n) _Pragma("unroll") for (int k = 0; k < 2; ++k) \
;         acc[ai][bj][m][n] = __builtin_amdgcn_mfma_f32_16x16x32_bf16(Bt[n][k], At[m][k], acc[ai][bj][m][n], 0, 0, 0); __builtin_amdgcn_s_setprio(0); } while (0)
; #define PG8_WAIT_V(n) asm volatile("s_waitcnt vmcnt(" #n ")" ::: "memory")
; #define PG8_WAIT_L(n) asm volatile("s_waitcnt lgkmcnt(" #n ")" ::: "memory")
; #define PG8_BAR __builtin_amdgcn_s_barrier()
; #define PG8_SCHED __builtin_amdgcn_sched_barrier(0)
; template <class Epi, class Sched, bool ALIGN_EPI = false, bool SP2 = false>
; __device__ __forceinline__ void gemm_phase(PG8_LAS unsigned char* lds, const Gemm g, const Sched& S, const Epi& E) {
;     ...
;             PG8_WAIT_V(8); PG8_WAIT_L(0); PG8_BAR; PG8_MMA(1, 0, At, B0); PG8_MMA(1, 1, At, B1); PG8_BAR; PG8_SCHED;
;             PG8_LDB(B0, 1, 0); PG8_LDB(B1, 1, 1); PG8_SCHED; PG8_LDA(At, 1, 0); PG8_STAGE(PG8_SA(0, 1), a2 + hstep, voffA);
;             PG8_WAIT_V(8); PG8_WAIT_L(0); PG8_BAR; PG8_MMA(0, 0, At, B0); PG8_MMA(0, 1, At, B1); PG8_BAR; PG8_SCHED;
	s_setprio 1
	v_mfma_f32_16x16x32_bf16 v[60:63], v[146:149], v[200:203], v[60:63]
	v_mfma_f32_16x16x32_bf16 v[52:55], v[168:171], v[200:203], v[52:55]
	v_mfma_f32_16x16x32_bf16 v[44:47], v[146:149], v[208:211], v[44:47]
	v_mfma_f32_16x16x32_bf16 v[36:39], v[168:171], v[208:211], v[36:39]
	v_mfma_f32_16x16x32_bf16 v[28:31], v[146:149], v[218:221], v[28:31]
	v_mfma_f32_16x16x32_bf16 v[20:23], v[168:171], v[218:221], v[20:23]
	v_mfma_f32_16x16x32_bf16 v[12:15], v[146:149], v[226:229], v[12:15]
	v_mfma_f32_16x16x32_bf16 v[4:7], v[168:171], v[226:229], v[4:7]
	v_mfma_f32_16x16x32_bf16 v[60:63], v[164:167], v[204:207], v[60:63]
	v_mfma_f32_16x16x32_bf16 v[52:55], v[172:175], v[204:207], v[52:55]
	v_mfma_f32_16x16x32_bf16 v[44:47], v[164:167], v[214:217], v[44:47]
	v_mfma_f32_16x16x32_bf16 v[36:39], v[172:175], v[214:217], v[36:39]
	v_mfma_f32_16x16x32_bf16 v[28:31], v[164:167], v[222:225], v[28:31]
	v_mfma_f32_16x16x32_bf16 v[20:23], v[172:175], v[222:225], v[20:23]
	v_mfma_f32_16x16x32_bf16 v[12:15], v[164:167], v[230:233], v[12:15]
	v_mfma_f32_16x16x32_bf16 v[4:7], v[172:175], v[230:233], v[4:7]
	s_setprio 0
	s_setprio 1
	v_mfma_f32_16x16x32_bf16 v[56:59], v[184:187], v[200:203], v[56:59]
	v_mfma_f32_16x16x32_bf16 v[48:51], v[192:195], v[200:203], v[48:51]
	v_mfma_f32_16x16x32_bf16 v[40:43], v[184:187], v[208:211], v[40:43]
	v_mfma_f32_16x16x32_bf16 v[32:35], v[192:195], v[208:211], v[32:35]
	v_mfma_f32_16x16x32_bf16 v[24:27], v[184:187], v[218:221], v[24:27]
	v_mfma_f32_16x16x32_bf16 v[16:19], v[192:195], v[218:221], v[16:19]
	v_mfma_f32_16x16x32_bf16 v[8:11], v[184:187], v[226:229], v[8:11]
	v_mfma_f32_16x16x32_bf16 v[0:3], v[192:195], v[226:229], v[0:3]
	v_mfma_f32_16x16x32_bf16 v[56:59], v[188:191], v[204:207], v[56:59]
	v_mfma_f32_16x16x32_bf16 v[48:51], v[196:199], v[204:207], v[48:51]
	v_mfma_f32_16x16x32_bf16 v[40:43], v[188:191], v[214:217], v[40:43]
	v_mfma_f32_16x16x32_bf16 v[32:35], v[196:199], v[214:217], v[32:35]
	v_mfma_f32_16x16x32_bf16 v[24:27], v[188:191], v[222:225], v[24:27]
	v_mfma_f32_16x16x32_bf16 v[16:19], v[196:199], v[222:225], v[16:19]
	v_mfma_f32_16x16x32_bf16 v[8:11], v[188:191], v[230:233], v[8:11]
	v_mfma_f32_16x16x32_bf16 v[0:3], v[196:199], v[230:233], v[0:3]
	s_barrier
	s_setprio 0
	s_add_i32 s90, 0, 0x18000
	v_add_u32_e32 v136, s90, v163
	s_add_i32 s91, 0, 0x1c000
	ds_read_b128 v[146:149], v136
	ds_read_b128 v[164:167], v136 offset:1024
	ds_read_b128 v[168:171], v136 offset:2048
	ds_read_b128 v[172:175], v136 offset:3072
	v_add_u32_e32 v136, s91, v163
	ds_read_b128 v[184:187], v136
	ds_read_b128 v[188:191], v136 offset:1024
	ds_read_b128 v[192:195], v136 offset:2048
	ds_read_b128 v[196:199], v136 offset:3072
	s_add_u32 s4, s38, 0x40000
	s_addc_u32 s5, s39, 0
	s_mov_b32 m0, s53
	v_lshl_add_u64 v[236:237], s[4:5], 0, v[134:135]
	ds_read_b128 v[200:203], v181 offset:32768
	ds_read_b128 v[204:207], v181 offset:33792
	ds_read_b128 v[208:211], v181 offset:34816
	ds_read_b128 v[214:217], v181 offset:35840
	ds_read_b128 v[218:221], v181 offset:36864
	ds_read_b128 v[222:225], v181 offset:37888
	ds_read_b128 v[226:229], v181 offset:38912
	ds_read_b128 v[230:233], v181 offset:39936
	global_load_lds_dwordx4 v[236:237], off
	v_lshl_add_u64 v[236:237], s[4:5], 0, v[130:131]
	s_mov_b32 m0, s72
	s_nop 0
	global_load_lds_dwordx4 v[236:237], off
	s_waitcnt vmcnt(8)
	s_waitcnt lgkmcnt(0)
	s_barrier
	s_setprio 1
	v_mfma_f32_16x16x32_bf16 v[124:127], v[146:149], v[200:203], v[124:127]
	v_mfma_f32_16x16x32_bf16 v[116:119], v[168:171], v[200:203], v[116:119]
	v_mfma_f32_16x16x32_bf16 v[108:111], v[146:149], v[208:211], v[108:111]
	v_mfma_f32_16x16x32_bf16 v[100:103], v[168:171], v[208:211], v[100:103]
	v_mfma_f32_16x16x32_bf16 v[92:95], v[146:149], v[218:221], v[92:95]
	v_mfma_f32_16x16x32_bf16 v[84:87], v[168:171], v[218:221], v[84:87]
	v_mfma_f32_16x16x32_bf16 v[76:79], v[146:149], v[226:229], v[76:79]
	v_mfma_f32_16x16x32_bf16 v[68:71], v[168:171], v[226:229], v[68:71]
	v_mfma_f32_16x16x32_bf16 v[124:127], v[164:167], v[204:207], v[124:127]
	v_mfma_f32_16x16x32_bf16 v[116:119], v[172:175], v[204:207], v[116:119]
	v_mfma_f32_16x16x32_bf16 v[108:111], v[164:167], v[214:217], v[108:111]
	v_mfma_f32_16x16x32_bf16 v[100:103], v[172:175], v[214:217], v[100:103]
	v_mfma_f32_16x16x32_bf16 v[92:95], v[164:167], v[222:225], v[92:95]
	v_mfma_f32_16x16x32_bf16 v[84:87], v[172:175], v[222:225], v[84:87]
	v_mfma_f32_16x16x32_bf16 v[76:79], v[164:167], v[230:233], v[76:79]
	v_mfma_f32_16x16x32_bf16 v[68:71], v[172:175], v[230:233], v[68:71]
	s_setprio 0
	s_setprio 1
	v_mfma_f32_16x16x32_bf16 v[120:123], v[184:187], v[200:203], v[120:123]
	v_mfma_f32_16x16x32_bf16 v[112:115], v[192:195], v[200:203], v[112:115]
	v_mfma_f32_16x16x32_bf16 v[104:107], v[184:187], v[208:211], v[104:107]
	v_mfma_f32_16x16x32_bf16 v[96:99], v[192:195], v[208:211], v[96:99]
	v_mfma_f32_16x16x32_bf16 v[88:91], v[184:187], v[218:221], v[88:91]
	v_mfma_f32_16x16x32_bf16 v[80:83], v[192:195], v[218:221], v[80:83]
	v_mfma_f32_16x16x32_bf16 v[72:75], v[184:187], v[226:229], v[72:75]
	v_mfma_f32_16x16x32_bf16 v[64:67], v[192:195], v[226:229], v[64:67]
	v_mfma_f32_16x16x32_bf16 v[120:123], v[188:191], v[204:207], v[120:123]
	v_mfma_f32_16x16x32_bf16 v[112:115], v[196:199], v[204:207], v[112:115]
	v_mfma_f32_16x16x32_bf16 v[104:107], v[188:191], v[214:217], v[104:107]
	v_mfma_f32_16x16x32_bf16 v[96:99], v[196:199], v[214:217], v[96:99]
	v_mfma_f32_16x16x32_bf16 v[88:91], v[188:191], v[222:225], v[88:91]
	v_mfma_f32_16x16x32_bf16 v[80:83], v[196:199], v[222:225], v[80:83]
	v_mfma_f32_16x16x32_bf16 v[72:75], v[188:191], v[230:233], v[72:75]
	v_mfma_f32_16x16x32_bf16 v[64:67], v[196:199], v[230:233], v[64:67]
	s_barrier
; #define PG8_STAGE(bufoff, gbase, voff) do { _Pragma("unroll") for (int _i = 0; _i < 2; ++_i) \
;         __builtin_amdgcn_global_load_lds((const unsigned*)((const char*)(gbase) + (voff)[_i]), (PG8_LAS unsigned*)(lds + (bufoff) + ldsw + _i * 8192), 16, 0, 0); } while (0)
; #define PG8_LDA(dst, b, h) do { _Pragma("unroll") for (int m = 0; m < 4; ++m) _Pragma("unroll") for (int k = 0; k < 2; ++k) dst[m][k] = *(const PG8_LAS bf16x8*)(lds + PG8_SA(b, h) + aoff + m * 2048 + k * 1024); } while (0)
; #define PG8_MMA(ai, bj, At, Bt) do { __builtin_amdgcn_s_setprio(1); _Pragma("unroll") for (int m = 0; m < 4; ++m) _Pragma("unroll") for (int n = 0; n < 2; ++n) _Pragma("unroll") for (int k = 0; k < 2; ++k) \
;         acc[ai][bj][m][n] = __builtin_amdgcn_mfma_f32_16x16x32_bf16(Bt[n][k], At[m][k], acc[ai][bj][m][n], 0, 0, 0); __builtin_amdgcn_s_setprio(0); } while (0)
; #define PG8_WAIT_V(n) asm volatile("s_waitcnt vmcnt(" #n ")" ::: "memory")
; #define PG8_WAIT_L(n) asm volatile("s_waitcnt lgkmcnt(" #n ")" ::: "memory")
; #define PG8_BAR __builtin_amdgcn_s_barrier()
; #define PG8_SCHED __builtin_amdgcn_sched_barrier(0)
; template <class Epi, class Sched, bool ALIGN_EPI = false, bool SP2 = false>
; __device__ __forceinline__ void gemm_phase(PG8_LAS unsigned char* lds, const Gemm g, const Sched& S, const Epi& E) {
;     ...
;             PG8_LDA(At, 1, 1); PG8_STAGE(PG8_SB(1, 0), b3, voffB); PG8_STAGE(PG8_SB(1, 1), b3 + hstep, voffB); PG8_STAGE(PG8_SA(1, 0), a3, voffA);
;             PG8_WAIT_V(8); PG8_WAIT_L(0); PG8_BAR; PG8_MMA(1, 0, At, B0); PG8_MMA(1, 1, At, B1); PG8_BAR; PG8_SCHED;
	s_setprio 0
	s_add_i32 s4, s90, s44
	v_lshl_add_u64 v[150:151], v[150:151], 0, s[12:13]
	s_mov_b32 m0, s4
	ds_read_b128 v[200:203], v181 offset:49152
	ds_read_b128 v[204:207], v181 offset:50176
	ds_read_b128 v[208:211], v181 offset:51200
	ds_read_b128 v[214:217], v181 offset:52224
	ds_read_b128 v[218:221], v181 offset:53248
	ds_read_b128 v[222:225], v181 offset:54272
	ds_read_b128 v[226:229], v181 offset:55296
	ds_read_b128 v[230:233], v181 offset:56320
	global_load_lds_dwordx4 v[150:151], off
	s_add_i32 m0, s4, 0x2000
	s_add_u32 s4, s36, 0x40080
	v_lshl_add_u64 v[150:151], v[154:155], 0, s[12:13]
	s_addc_u32 s5, s37, 0
	s_add_i32 s36, s91, s44
	global_load_lds_dwordx4 v[150:151], off
	v_lshl_add_u64 v[150:151], s[4:5], 0, v[132:133]
	s_mov_b32 m0, s36
	s_nop 0
	global_load_lds_dwordx4 v[150:151], off
	v_lshl_add_u64 v[150:151], s[4:5], 0, v[128:129]
	s_add_i32 m0, s36, 0x2000
	s_nop 0
	global_load_lds_dwordx4 v[150:151], off
	v_lshl_add_u64 v[150:151], v[176:177], 0, s[12:13]
	s_mov_b32 m0, s75
	s_nop 0
	global_load_lds_dwordx4 v[150:151], off
	v_lshl_add_u64 v[150:151], v[234:235], 0, s[12:13]
	s_mov_b32 m0, s76
	s_nop 0
	global_load_lds_dwordx4 v[150:151], off
	s_waitcnt vmcnt(8)
	s_waitcnt lgkmcnt(0)
	s_barrier
	s_setprio 1
	v_mfma_f32_16x16x32_bf16 v[60:63], v[146:149], v[200:203], v[60:63]
	v_mfma_f32_16x16x32_bf16 v[52:55], v[168:171], v[200:203], v[52:55]
	v_mfma_f32_16x16x32_bf16 v[44:47], v[146:149], v[208:211], v[44:47]
	v_mfma_f32_16x16x32_bf16 v[36:39], v[168:171], v[208:211], v[36:39]
	v_mfma_f32_16x16x32_bf16 v[28:31], v[146:149], v[218:221], v[28:31]
	v_mfma_f32_16x16x32_bf16 v[20:23], v[168:171], v[218:221], v[20:23]
	v_mfma_f32_16x16x32_bf16 v[12:15], v[146:149], v[226:229], v[12:15]
	v_mfma_f32_16x16x32_bf16 v[4:7], v[168:171], v[226:229], v[4:7]
	v_mfma_f32_16x16x32_bf16 v[60:63], v[164:167], v[204:207], v[60:63]
	v_mfma_f32_16x16x32_bf16 v[52:55], v[172:175], v[204:207], v[52:55]
	v_mfma_f32_16x16x32_bf16 v[44:47], v[164:167], v[214:217], v[44:47]
	v_mfma_f32_16x16x32_bf16 v[36:39], v[172:175], v[214:217], v[36:39]
	v_mfma_f32_16x16x32_bf16 v[28:31], v[164:167], v[222:225], v[28:31]
	v_mfma_f32_16x16x32_bf16 v[20:23], v[172:175], v[222:225], v[20:23]
	v_mfma_f32_16x16x32_bf16 v[12:15], v[164:167], v[230:233], v[12:15]
	v_mfma_f32_16x16x32_bf16 v[4:7], v[172:175], v[230:233], v[4:7]
	s_setprio 0
	s_setprio 1
	v_mfma_f32_16x16x32_bf16 v[56:59], v[184:187], v[200:203], v[56:59]
	v_mfma_f32_16x16x32_bf16 v[48:51], v[192:195], v[200:203], v[48:51]
	v_mfma_f32_16x16x32_bf16 v[40:43], v[184:187], v[208:211], v[40:43]
	v_mfma_f32_16x16x32_bf16 v[32:35], v[192:195], v[208:211], v[32:35]
	v_mfma_f32_16x16x32_bf16 v[24:27], v[184:187], v[218:221], v[24:27]
	v_mfma_f32_16x16x32_bf16 v[16:19], v[192:195], v[218:221], v[16:19]
	v_mfma_f32_16x16x32_bf16 v[8:11], v[184:187], v[226:229], v[8:11]
	v_mfma_f32_16x16x32_bf16 v[0:3], v[192:195], v[226:229], v[0:3]
	v_mfma_f32_16x16x32_bf16 v[56:59], v[188:191], v[204:207], v[56:59]
	v_mfma_f32_16x16x32_bf16 v[48:51], v[196:199], v[204:207], v[48:51]
	v_mfma_f32_16x16x32_bf16 v[40:43], v[188:191], v[214:217], v[40:43]
	v_mfma_f32_16x16x32_bf16 v[32:35], v[196:199], v[214:217], v[32:35]
	v_mfma_f32_16x16x32_bf16 v[24:27], v[188:191], v[222:225], v[24:27]
	v_mfma_f32_16x16x32_bf16 v[16:19], v[196:199], v[222:225], v[16:19]
	v_mfma_f32_16x16x32_bf16 v[8:11], v[188:191], v[230:233], v[8:11]
	v_mfma_f32_16x16x32_bf16 v[0:3], v[196:199], v[230:233], v[0:3]
	s_barrier
	s_setprio 0
	s_add_i32 s86, s86, 2
	s_add_u32 s34, s34, 0x100
	s_addc_u32 s35, s35, 0
	s_add_u32 s85, s85, 0x100
	s_addc_u32 s89, s89, 0
	s_cmp_gt_u32 s86, 13
	s_cbranch_scc0 .LBB0_469
	s_and_b64 vcc, exec, s[22:23]
	s_cbranch_vccz .LBB0_472
	s_barrier

; #define PG8_STAGE(bufoff, gbase, voff) do { _Pragma("unroll") for (int _i = 0; _i < 2; ++_i) \
;         __builtin_amdgcn_global_load_lds((const unsigned*)((const char*)(gbase) + (voff)[_i]), (PG8_LAS unsigned*)(lds + (bufoff) + ldsw + _i * 8192), 16, 0, 0); } while (0)
; #define PG8_LDA(dst, b, h) do { _Pragma("unroll") for (int m = 0; m < 4; ++m) _Pragma("unroll") for (int k = 0; k < 2; ++k) dst[m][k] = *(const PG8_LAS bf16x8*)(lds + PG8_SA(b, h) + aoff + m * 2048 + k * 1024); } while (0)
; #define PG8_LDB(dst, b, h) do { _Pragma("unroll") for (int n = 0; n < 2; ++n) _Pragma("unroll") for (int k = 0; k < 2; ++k) dst[n][k] = *(const PG8_LAS bf16x8*)(lds + PG8_SB(b, h) + boff + n * 2048 + k * 1024); } while (0)
; #define PG8_MMA(ai, bj, At, Bt) do { __builtin_amdgcn_s_setprio(1); _Pragma("unroll") for (int m = 0; m < 4; ++m) _Pragma("unroll") for (int n = 0; n < 2; ++n) _Pragma("unroll") for (int k = 0; k < 2; ++k) \
;         acc[ai][bj][m][n] = __builtin_amdgcn_mfma_f32_16x16x32_bf16(Bt[n][k], At[m][k], acc[ai][bj][m][n], 0, 0, 0); __builtin_amdgcn_s_setprio(0); } while (0)
; #define PG8_WAIT_V(n) asm volatile("s_waitcnt vmcnt(" #n ")" ::: "memory")
; #define PG8_WAIT_L(n) asm volatile("s_waitcnt lgkmcnt(" #n ")" ::: "memory")
; #define PG8_BAR __builtin_amdgcn_s_barrier()
; #define PG8_SCHED __builtin_amdgcn_sched_barrier(0)
; template <class Epi, class Sched, bool ALIGN_EPI = false, bool SP2 = false>
; __device__ __forceinline__ void gemm_phase(PG8_LAS unsigned char* lds, const Gemm g, const Sched& S, const Epi& E) {
;     ...
;             const char* a1 = cA + (size_t)(t + 1) * kstep;
;             const char* a2 = last ? nA : cA + (size_t)(t + 2) * kstep; const char* b2 = last ? nB : cB + (size_t)(t + 2) * kstep;
;             const char* a3 = a2 + kstep; const char* b3 = b2 + kstep;
;             if (last && has_next) S.a_ready(nxt);
;             if constexpr (SP2) {
;             PG8_LDB(B0, 0, 0); PG8_LDB(B1, 0, 1); PG8_SCHED; PG8_LDA(At, 0, 0); PG8_STAGE(PG8_SA(1, 1), a1 + hstep, voffA);
;             PG8_WAIT_V(8); PG8_WAIT_L(0); PG8_BAR; PG8_MMA(0, 0, At, B0); PG8_MMA(0, 1, At, B1); PG8_BAR; PG8_SCHED;
;             PG8_LDA(At, 0, 1); PG8_STAGE(PG8_SB(0, 0), b2, voffB); PG8_STAGE(PG8_SB(0, 1), b2 + hstep, voffB); PG8_STAGE(PG8_SA(0, 0), a2, voffA);
.LBB0_568:
	s_waitcnt lgkmcnt(0)
	ds_read_b128 v[128:131], v196
	ds_read_b128 v[132:135], v196 offset:1024
	ds_read_b128 v[136:139], v196 offset:2048
	ds_read_b128 v[140:143], v196 offset:3072
	ds_read_b128 v[144:147], v197
	ds_read_b128 v[148:151], v197 offset:1024
	ds_read_b128 v[176:179], v197 offset:2048
	ds_read_b128 v[180:183], v197 offset:3072
	s_add_i32 s4, s38, 2
	s_add_u32 s36, s34, 0x100
	s_addc_u32 s37, s35, 0
	s_cmp_eq_u32 vcc_lo, s38
	s_cselect_b32 s38, s30, vcc_hi
	s_cselect_b32 s41, s29, s37
	s_cselect_b32 s40, s28, s36
	s_cselect_b32 s39, s31, s86
	v_lshl_add_u64 v[222:223], s[34:35], 0, v[170:171]
	s_add_i32 m0, s47, 0xc000
	ds_read_b128 v[184:187], v198
	ds_read_b128 v[188:191], v198 offset:1024
	ds_read_b128 v[192:195], v198 offset:2048
	ds_read_b128 v[200:203], v198 offset:3072
	ds_read_b128 v[204:207], v198 offset:4096
	ds_read_b128 v[208:211], v198 offset:5120
	ds_read_b128 v[214:217], v198 offset:6144
	ds_read_b128 v[218:221], v198 offset:7168
	global_load_lds_dwordx4 v[222:223], off
	v_lshl_add_u64 v[222:223], s[34:35], 0, v[172:173]
	s_add_i32 m0, s47, 0xe000
	s_nop 0
	global_load_lds_dwordx4 v[222:223], off
	s_waitcnt vmcnt(8)
	s_waitcnt lgkmcnt(0)
	s_barrier
	s_setprio 1
	v_mfma_f32_16x16x32_bf16 v[124:127], v[128:131], v[184:187], v[124:127]
	v_mfma_f32_16x16x32_bf16 v[120:123], v[136:139], v[184:187], v[120:123]
	v_mfma_f32_16x16x32_bf16 v[116:119], v[128:131], v[192:195], v[116:119]
	v_mfma_f32_16x16x32_bf16 v[108:111], v[136:139], v[192:195], v[108:111]
	v_mfma_f32_16x16x32_bf16 v[100:103], v[128:131], v[204:207], v[100:103]
	v_mfma_f32_16x16x32_bf16 v[92:95], v[136:139], v[204:207], v[92:95]
	v_mfma_f32_16x16x32_bf16 v[84:87], v[128:131], v[214:217], v[84:87]
	v_mfma_f32_16x16x32_bf16 v[76:79], v[136:139], v[214:217], v[76:79]
	v_mfma_f32_16x16x32_bf16 v[124:127], v[132:135], v[188:191], v[124:127]
	v_mfma_f32_16x16x32_bf16 v[120:123], v[140:143], v[188:191], v[120:123]
	v_mfma_f32_16x16x32_bf16 v[116:119], v[132:135], v[200:203], v[116:119]
	v_mfma_f32_16x16x32_bf16 v[108:111], v[140:143], v[200:203], v[108:111]
	v_mfma_f32_16x16x32_bf16 v[100:103], v[132:135], v[208:211], v[100:103]
	v_mfma_f32_16x16x32_bf16 v[92:95], v[140:143], v[208:211], v[92:95]
	v_mfma_f32_16x16x32_bf16 v[84:87], v[132:135], v[218:221], v[84:87]
	v_mfma_f32_16x16x32_bf16 v[76:79], v[140:143], v[218:221], v[76:79]
	s_setprio 0
	s_setprio 1
	v_mfma_f32_16x16x32_bf16 v[112:115], v[144:147], v[184:187], v[112:115]
	v_mfma_f32_16x16x32_bf16 v[104:107], v[176:179], v[184:187], v[104:107]
	v_mfma_f32_16x16x32_bf16 v[96:99], v[144:147], v[192:195], v[96:99]
	v_mfma_f32_16x16x32_bf16 v[88:91], v[176:179], v[192:195], v[88:91]
	v_mfma_f32_16x16x32_bf16 v[80:83], v[144:147], v[204:207], v[80:83]
	v_mfma_f32_16x16x32_bf16 v[72:75], v[176:179], v[204:207], v[72:75]
	v_mfma_f32_16x16x32_bf16 v[68:71], v[144:147], v[214:217], v[68:71]
	v_mfma_f32_16x16x32_bf16 v[64:67], v[176:179], v[214:217], v[64:67]
	v_mfma_f32_16x16x32_bf16 v[112:115], v[148:151], v[188:191], v[112:115]
	v_mfma_f32_16x16x32_bf16 v[104:107], v[180:183], v[188:191], v[104:107]
	v_mfma_f32_16x16x32_bf16 v[96:99], v[148:151], v[200:203], v[96:99]
	v_mfma_f32_16x16x32_bf16 v[88:91], v[180:183], v[200:203], v[88:91]
	v_mfma_f32_16x16x32_bf16 v[80:83], v[148:151], v[208:211], v[80:83]
	v_mfma_f32_16x16x32_bf16 v[72:75], v[180:183], v[208:211], v[72:75]
	v_mfma_f32_16x16x32_bf16 v[68:71], v[148:151], v[218:221], v[68:71]
	v_mfma_f32_16x16x32_bf16 v[64:67], v[180:183], v[218:221], v[64:67]
	s_barrier
	s_setprio 0
	s_add_i32 s5, s79, s46
	v_lshl_add_u64 v[222:223], s[38:39], 0, v[164:165]
	s_mov_b32 m0, s5
	ds_read_b128 v[184:187], v198 offset:16384
	ds_read_b128 v[188:191], v198 offset:17408
	ds_read_b128 v[192:195], v198 offset:18432
	ds_read_b128 v[200:203], v198 offset:19456
	ds_read_b128 v[204:207], v198 offset:20480
	ds_read_b128 v[208:211], v198 offset:21504
	ds_read_b128 v[214:217], v198 offset:22528
	ds_read_b128 v[218:221], v198 offset:23552
	global_load_lds_dwordx4 v[222:223], off
	s_add_i32 m0, s5, 0x2000
	s_add_u32 s34, s38, 0xb0000
	v_lshl_add_u64 v[224:225], s[38:39], 0, v[168:169]
	s_addc_u32 s35, s39, 0
	s_add_i32 s5, s80, s46
	global_load_lds_dwordx4 v[224:225], off
	v_lshl_add_u64 v[226:227], s[34:35], 0, v[164:165]
	s_mov_b32 m0, s5
	v_lshl_add_u64 v[228:229], s[40:41], 0, v[166:167]
	global_load_lds_dwordx4 v[226:227], off
	v_lshl_add_u64 v[226:227], s[34:35], 0, v[168:169]
	s_add_i32 m0, s5, 0x2000
	s_nop 0
	global_load_lds_dwordx4 v[226:227], off
	v_lshl_add_u64 v[226:227], s[40:41], 0, v[154:155]
	s_mov_b32 m0, s47
	s_nop 0
	global_load_lds_dwordx4 v[226:227], off
	s_mov_b32 m0, s49
	s_nop 0
	global_load_lds_dwordx4 v[228:229], off
	s_waitcnt vmcnt(8)
	s_waitcnt lgkmcnt(0)
	s_barrier
; #define PG8_STAGE(bufoff, gbase, voff) do { _Pragma("unroll") for (int _i = 0; _i < 2; ++_i) \
;         __builtin_amdgcn_global_load_lds((const unsigned*)((const char*)(gbase) + (voff)[_i]), (PG8_LAS unsigned*)(lds + (bufoff) + ldsw + _i * 8192), 16, 0, 0); } while (0)
; #define PG8_LDA(dst, b, h) do { _Pragma("unroll") for (int m = 0; m < 4; ++m) _Pragma("unroll") for (int k = 0; k < 2; ++k) dst[m][k] = *(const PG8_LAS bf16x8*)(lds + PG8_SA(b, h) + aoff + m * 2048 + k * 1024); } while (0)
; #define PG8_LDB(dst, b, h) do { _Pragma("unroll") for (int n = 0; n < 2; ++n) _Pragma("unroll") for (int k = 0; k < 2; ++k) dst[n][k] = *(const PG8_LAS bf16x8*)(lds + PG8_SB(b, h) + boff + n * 2048 + k * 1024); } while (0)
; #define PG8_MMA(ai, bj, At, Bt) do { __builtin_amdgcn_s_setprio(1); _Pragma("unroll") for (int m = 0; m < 4; ++m) _Pragma("unroll") for (int n = 0; n < 2; ++n) _Pragma("unroll") for (int k = 0; k < 2; ++k) \
;         acc[ai][bj][m][n] = __builtin_amdgcn_mfma_f32_16x16x32_bf16(Bt[n][k], At[m][k], acc[ai][bj][m][n], 0, 0, 0); __builtin_amdgcn_s_setprio(0); } while (0)
; #define PG8_WAIT_V(n) asm volatile("s_waitcnt vmcnt(" #n ")" ::: "memory")
; #define PG8_WAIT_L(n) asm volatile("s_waitcnt lgkmcnt(" #n ")" ::: "memory")
; #define PG8_BAR __builtin_amdgcn_s_barrier()
; #define PG8_SCHED __builtin_amdgcn_sched_barrier(0)
; template <class Epi, class Sched, bool ALIGN_EPI = false, bool SP2 = false>
; __device__ __forceinline__ void gemm_phase(PG8_LAS unsigned char* lds, const Gemm g, const Sched& S, const Epi& E) {
;     ...
;             PG8_WAIT_V(8); PG8_WAIT_L(0); PG8_BAR; PG8_MMA(1, 0, At, B0); PG8_MMA(1, 1, At, B1); PG8_BAR; PG8_SCHED;
;             PG8_LDB(B0, 1, 0); PG8_LDB(B1, 1, 1); PG8_SCHED; PG8_LDA(At, 1, 0); PG8_STAGE(PG8_SA(0, 1), a2 + hstep, voffA);
;             PG8_WAIT_V(8); PG8_WAIT_L(0); PG8_BAR; PG8_MMA(0, 0, At, B0); PG8_MMA(0, 1, At, B1); PG8_BAR; PG8_SCHED;
	s_setprio 1
	v_mfma_f32_16x16x32_bf16 v[60:63], v[128:131], v[184:187], v[60:63]
	v_mfma_f32_16x16x32_bf16 v[56:59], v[136:139], v[184:187], v[56:59]
	v_mfma_f32_16x16x32_bf16 v[52:55], v[128:131], v[192:195], v[52:55]
	v_mfma_f32_16x16x32_bf16 v[44:47], v[136:139], v[192:195], v[44:47]
	v_mfma_f32_16x16x32_bf16 v[36:39], v[128:131], v[204:207], v[36:39]
	v_mfma_f32_16x16x32_bf16 v[28:31], v[136:139], v[204:207], v[28:31]
	v_mfma_f32_16x16x32_bf16 v[20:23], v[128:131], v[214:217], v[20:23]
	v_mfma_f32_16x16x32_bf16 v[12:15], v[136:139], v[214:217], v[12:15]
	v_mfma_f32_16x16x32_bf16 v[60:63], v[132:135], v[188:191], v[60:63]
	v_mfma_f32_16x16x32_bf16 v[56:59], v[140:143], v[188:191], v[56:59]
	v_mfma_f32_16x16x32_bf16 v[52:55], v[132:135], v[200:203], v[52:55]
	v_mfma_f32_16x16x32_bf16 v[44:47], v[140:143], v[200:203], v[44:47]
	v_mfma_f32_16x16x32_bf16 v[36:39], v[132:135], v[208:211], v[36:39]
	v_mfma_f32_16x16x32_bf16 v[28:31], v[140:143], v[208:211], v[28:31]
	v_mfma_f32_16x16x32_bf16 v[20:23], v[132:135], v[218:221], v[20:23]
	v_mfma_f32_16x16x32_bf16 v[12:15], v[140:143], v[218:221], v[12:15]
	s_setprio 0
	s_setprio 1
	v_mfma_f32_16x16x32_bf16 v[48:51], v[144:147], v[184:187], v[48:51]
	v_mfma_f32_16x16x32_bf16 v[40:43], v[176:179], v[184:187], v[40:43]
	v_mfma_f32_16x16x32_bf16 v[32:35], v[144:147], v[192:195], v[32:35]
	v_mfma_f32_16x16x32_bf16 v[24:27], v[176:179], v[192:195], v[24:27]
	v_mfma_f32_16x16x32_bf16 v[16:19], v[144:147], v[204:207], v[16:19]
	v_mfma_f32_16x16x32_bf16 v[8:11], v[176:179], v[204:207], v[8:11]
	v_mfma_f32_16x16x32_bf16 v[4:7], v[144:147], v[214:217], v[4:7]
	v_mfma_f32_16x16x32_bf16 v[0:3], v[176:179], v[214:217], v[0:3]
	v_mfma_f32_16x16x32_bf16 v[48:51], v[148:151], v[188:191], v[48:51]
	v_mfma_f32_16x16x32_bf16 v[40:43], v[180:183], v[188:191], v[40:43]
	v_mfma_f32_16x16x32_bf16 v[32:35], v[148:151], v[200:203], v[32:35]
	v_mfma_f32_16x16x32_bf16 v[24:27], v[180:183], v[200:203], v[24:27]
	v_mfma_f32_16x16x32_bf16 v[16:19], v[148:151], v[208:211], v[16:19]
	v_mfma_f32_16x16x32_bf16 v[8:11], v[180:183], v[208:211], v[8:11]
	v_mfma_f32_16x16x32_bf16 v[4:7], v[148:151], v[218:221], v[4:7]
	v_mfma_f32_16x16x32_bf16 v[0:3], v[180:183], v[218:221], v[0:3]
	s_barrier
	s_setprio 0
	s_add_i32 s5, 0, 0x18000
	s_add_i32 s14, 0, 0x1c000
	v_add_u32_e32 v140, s5, v159
	v_add_u32_e32 v180, s14, v159
	ds_read_b128 v[128:131], v140
	ds_read_b128 v[132:135], v140 offset:1024
	ds_read_b128 v[136:139], v140 offset:2048
	ds_read_b128 v[140:143], v140 offset:3072
	ds_read_b128 v[144:147], v180
	ds_read_b128 v[148:151], v180 offset:1024
	ds_read_b128 v[176:179], v180 offset:2048
	ds_read_b128 v[180:183], v180 offset:3072
	s_add_u32 s34, s40, 0xb0000
	s_addc_u32 s35, s41, 0
	s_mov_b32 m0, s53
	v_lshl_add_u64 v[230:231], s[34:35], 0, v[154:155]
	ds_read_b128 v[184:187], v198 offset:32768
	ds_read_b128 v[188:191], v198 offset:33792
	ds_read_b128 v[192:195], v198 offset:34816
	ds_read_b128 v[200:203], v198 offset:35840
	ds_read_b128 v[204:207], v198 offset:36864
	ds_read_b128 v[208:211], v198 offset:37888
	ds_read_b128 v[214:217], v198 offset:38912
	ds_read_b128 v[218:221], v198 offset:39936
	global_load_lds_dwordx4 v[230:231], off
	v_lshl_add_u64 v[230:231], s[34:35], 0, v[166:167]
	s_mov_b32 m0, s72
	s_nop 0
	global_load_lds_dwordx4 v[230:231], off
	s_waitcnt vmcnt(8)
	s_waitcnt lgkmcnt(0)
	s_barrier
	s_setprio 1
	v_mfma_f32_16x16x32_bf16 v[124:127], v[128:131], v[184:187], v[124:127]
	v_mfma_f32_16x16x32_bf16 v[120:123], v[136:139], v[184:187], v[120:123]
	v_mfma_f32_16x16x32_bf16 v[116:119], v[128:131], v[192:195], v[116:119]
	v_mfma_f32_16x16x32_bf16 v[108:111], v[136:139], v[192:195], v[108:111]
	v_mfma_f32_16x16x32_bf16 v[100:103], v[128:131], v[204:207], v[100:103]
	v_mfma_f32_16x16x32_bf16 v[92:95], v[136:139], v[204:207], v[92:95]
	v_mfma_f32_16x16x32_bf16 v[84:87], v[128:131], v[214:217], v[84:87]
	v_mfma_f32_16x16x32_bf16 v[76:79], v[136:139], v[214:217], v[76:79]
	v_mfma_f32_16x16x32_bf16 v[124:127], v[132:135], v[188:191], v[124:127]
	v_mfma_f32_16x16x32_bf16 v[120:123], v[140:143], v[188:191], v[120:123]
	v_mfma_f32_16x16x32_bf16 v[116:119], v[132:135], v[200:203], v[116:119]
	v_mfma_f32_16x16x32_bf16 v[108:111], v[140:143], v[200:203], v[108:111]
	v_mfma_f32_16x16x32_bf16 v[100:103], v[132:135], v[208:211], v[100:103]
	v_mfma_f32_16x16x32_bf16 v[92:95], v[140:143], v[208:211], v[92:95]
	v_mfma_f32_16x16x32_bf16 v[84:87], v[132:135], v[218:221], v[84:87]
	v_mfma_f32_16x16x32_bf16 v[76:79], v[140:143], v[218:221], v[76:79]
	s_setprio 0
	s_setprio 1
	v_mfma_f32_16x16x32_bf16 v[112:115], v[144:147], v[184:187], v[112:115]
	v_mfma_f32_16x16x32_bf16 v[104:107], v[176:179], v[184:187], v[104:107]
	v_mfma_f32_16x16x32_bf16 v[96:99], v[144:147], v[192:195], v[96:99]
	v_mfma_f32_16x16x32_bf16 v[88:91], v[176:179], v[192:195], v[88:91]
	v_mfma_f32_16x16x32_bf16 v[80:83], v[144:147], v[204:207], v[80:83]
	v_mfma_f32_16x16x32_bf16 v[72:75], v[176:179], v[204:207], v[72:75]
	v_mfma_f32_16x16x32_bf16 v[68:71], v[144:147], v[214:217], v[68:71]
	v_mfma_f32_16x16x32_bf16 v[64:67], v[176:179], v[214:217], v[64:67]
	v_mfma_f32_16x16x32_bf16 v[112:115], v[148:151], v[188:191], v[112:115]
	v_mfma_f32_16x16x32_bf16 v[104:107], v[180:183], v[188:191], v[104:107]
	v_mfma_f32_16x16x32_bf16 v[96:99], v[148:151], v[200:203], v[96:99]
	v_mfma_f32_16x16x32_bf16 v[88:91], v[180:183], v[200:203], v[88:91]
	v_mfma_f32_16x16x32_bf16 v[80:83], v[148:151], v[208:211], v[80:83]
	v_mfma_f32_16x16x32_bf16 v[72:75], v[180:183], v[208:211], v[72:75]
	v_mfma_f32_16x16x32_bf16 v[68:71], v[148:151], v[218:221], v[68:71]
	v_mfma_f32_16x16x32_bf16 v[64:67], v[180:183], v[218:221], v[64:67]
	s_barrier
; #define PG8_STAGE(bufoff, gbase, voff) do { _Pragma("unroll") for (int _i = 0; _i < 2; ++_i) \
;         __builtin_amdgcn_global_load_lds((const unsigned*)((const char*)(gbase) + (voff)[_i]), (PG8_LAS unsigned*)(lds + (bufoff) + ldsw + _i * 8192), 16, 0, 0); } while (0)
; #define PG8_LDA(dst, b, h) do { _Pragma("unroll") for (int m = 0; m < 4; ++m) _Pragma("unroll") for (int k = 0; k < 2; ++k) dst[m][k] = *(const PG8_LAS bf16x8*)(lds + PG8_SA(b, h) + aoff + m * 2048 + k * 1024); } while (0)
; #define PG8_MMA(ai, bj, At, Bt) do { __builtin_amdgcn_s_setprio(1); _Pragma("unroll") for (int m = 0; m < 4; ++m) _Pragma("unroll") for (int n = 0; n < 2; ++n) _Pragma("unroll") for (int k = 0; k < 2; ++k) \
;         acc[ai][bj][m][n] = __builtin_amdgcn_mfma_f32_16x16x32_bf16(Bt[n][k], At[m][k], acc[ai][bj][m][n], 0, 0, 0); __builtin_amdgcn_s_setprio(0); } while (0)
; #define PG8_WAIT_V(n) asm volatile("s_waitcnt vmcnt(" #n ")" ::: "memory")
; #define PG8_WAIT_L(n) asm volatile("s_waitcnt lgkmcnt(" #n ")" ::: "memory")
; #define PG8_BAR __builtin_amdgcn_s_barrier()
; #define PG8_SCHED __builtin_amdgcn_sched_barrier(0)
; template <class Epi, class Sched, bool ALIGN_EPI = false, bool SP2 = false>
; __device__ __forceinline__ void gemm_phase(PG8_LAS unsigned char* lds, const Gemm g, const Sched& S, const Epi& E) {
;     ...
;             PG8_LDA(At, 1, 1); PG8_STAGE(PG8_SB(1, 0), b3, voffB); PG8_STAGE(PG8_SB(1, 1), b3 + hstep, voffB); PG8_STAGE(PG8_SA(1, 0), a3, voffA);
;             PG8_WAIT_V(8); PG8_WAIT_L(0); PG8_BAR; PG8_MMA(1, 0, At, B0); PG8_MMA(1, 1, At, B1); PG8_BAR; PG8_SCHED;
	s_setprio 0
	s_add_i32 s5, s5, s46
	v_lshl_add_u64 v[222:223], v[222:223], 0, s[24:25]
	s_mov_b32 m0, s5
	ds_read_b128 v[184:187], v198 offset:49152
	ds_read_b128 v[188:191], v198 offset:50176
	ds_read_b128 v[192:195], v198 offset:51200
	ds_read_b128 v[200:203], v198 offset:52224
	ds_read_b128 v[204:207], v198 offset:53248
	ds_read_b128 v[208:211], v198 offset:54272
	ds_read_b128 v[214:217], v198 offset:55296
	ds_read_b128 v[218:221], v198 offset:56320
	global_load_lds_dwordx4 v[222:223], off
	s_add_i32 m0, s5, 0x2000
	s_add_u32 s34, s38, 0xb0080
	v_lshl_add_u64 v[222:223], v[224:225], 0, s[24:25]
	s_addc_u32 s35, s39, 0
	s_add_i32 s5, s14, s46
	global_load_lds_dwordx4 v[222:223], off
	v_lshl_add_u64 v[222:223], s[34:35], 0, v[164:165]
	s_mov_b32 m0, s5
	s_nop 0
	global_load_lds_dwordx4 v[222:223], off
	v_lshl_add_u64 v[222:223], s[34:35], 0, v[168:169]
	s_add_i32 m0, s5, 0x2000
	s_nop 0
	global_load_lds_dwordx4 v[222:223], off
	v_lshl_add_u64 v[222:223], v[226:227], 0, s[24:25]
	s_mov_b32 m0, s74
	s_nop 0
	global_load_lds_dwordx4 v[222:223], off
	v_lshl_add_u64 v[222:223], v[228:229], 0, s[24:25]
	s_mov_b32 m0, s75
	s_nop 0
	global_load_lds_dwordx4 v[222:223], off
	s_waitcnt vmcnt(8)
	s_waitcnt lgkmcnt(0)
	s_barrier
	s_setprio 1
	v_mfma_f32_16x16x32_bf16 v[60:63], v[128:131], v[184:187], v[60:63]
	v_mfma_f32_16x16x32_bf16 v[56:59], v[136:139], v[184:187], v[56:59]
	v_mfma_f32_16x16x32_bf16 v[52:55], v[128:131], v[192:195], v[52:55]
	v_mfma_f32_16x16x32_bf16 v[44:47], v[136:139], v[192:195], v[44:47]
	v_mfma_f32_16x16x32_bf16 v[36:39], v[128:131], v[204:207], v[36:39]
	v_mfma_f32_16x16x32_bf16 v[28:31], v[136:139], v[204:207], v[28:31]
	v_mfma_f32_16x16x32_bf16 v[20:23], v[128:131], v[214:217], v[20:23]
	v_mfma_f32_16x16x32_bf16 v[12:15], v[136:139], v[214:217], v[12:15]
	v_mfma_f32_16x16x32_bf16 v[60:63], v[132:135], v[188:191], v[60:63]
	v_mfma_f32_16x16x32_bf16 v[56:59], v[140:143], v[188:191], v[56:59]
	v_mfma_f32_16x16x32_bf16 v[52:55], v[132:135], v[200:203], v[52:55]
	v_mfma_f32_16x16x32_bf16 v[44:47], v[140:143], v[200:203], v[44:47]
	v_mfma_f32_16x16x32_bf16 v[36:39], v[132:135], v[208:211], v[36:39]
	v_mfma_f32_16x16x32_bf16 v[28:31], v[140:143], v[208:211], v[28:31]
	v_mfma_f32_16x16x32_bf16 v[20:23], v[132:135], v[218:221], v[20:23]
	v_mfma_f32_16x16x32_bf16 v[12:15], v[140:143], v[218:221], v[12:15]
	s_setprio 0
	s_setprio 1
	v_mfma_f32_16x16x32_bf16 v[48:51], v[144:147], v[184:187], v[48:51]
	v_mfma_f32_16x16x32_bf16 v[40:43], v[176:179], v[184:187], v[40:43]
	v_mfma_f32_16x16x32_bf16 v[32:35], v[144:147], v[192:195], v[32:35]
	v_mfma_f32_16x16x32_bf16 v[24:27], v[176:179], v[192:195], v[24:27]
	v_mfma_f32_16x16x32_bf16 v[16:19], v[144:147], v[204:207], v[16:19]
	v_mfma_f32_16x16x32_bf16 v[8:11], v[176:179], v[204:207], v[8:11]
	v_mfma_f32_16x16x32_bf16 v[4:7], v[144:147], v[214:217], v[4:7]
	v_mfma_f32_16x16x32_bf16 v[0:3], v[176:179], v[214:217], v[0:3]
	v_mfma_f32_16x16x32_bf16 v[48:51], v[148:151], v[188:191], v[48:51]
	v_mfma_f32_16x16x32_bf16 v[40:43], v[180:183], v[188:191], v[40:43]
	v_mfma_f32_16x16x32_bf16 v[32:35], v[148:151], v[200:203], v[32:35]
	v_mfma_f32_16x16x32_bf16 v[24:27], v[180:183], v[200:203], v[24:27]
	v_mfma_f32_16x16x32_bf16 v[16:19], v[148:151], v[208:211], v[16:19]
	v_mfma_f32_16x16x32_bf16 v[8:11], v[180:183], v[208:211], v[8:11]
	v_mfma_f32_16x16x32_bf16 v[4:7], v[148:151], v[218:221], v[4:7]
	v_mfma_f32_16x16x32_bf16 v[0:3], v[180:183], v[218:221], v[0:3]
	s_barrier
	s_setprio 0
	s_add_u32 vcc_hi, vcc_hi, 0x100
	s_addc_u32 s86, s86, 0
	s_cmp_ge_i32 s4, s97
	s_mov_b64 s[34:35], s[36:37]
	s_mov_b32 s38, s4
	s_cbranch_scc0 .LBB0_568
	s_and_b64 vcc, exec, s[26:27]
	s_cbranch_vccz .LBB0_571
	s_barrier

; #define PG8_STAGE(bufoff, gbase, voff) do { _Pragma("unroll") for (int _i = 0; _i < 2; ++_i) \
;         __builtin_amdgcn_global_load_lds((const unsigned*)((const char*)(gbase) + (voff)[_i]), (PG8_LAS unsigned*)(lds + (bufoff) + ldsw + _i * 8192), 16, 0, 0); } while (0)
; #define PG8_LDA(dst, b, h) do { _Pragma("unroll") for (int m = 0; m < 4; ++m) _Pragma("unroll") for (int k = 0; k < 2; ++k) dst[m][k] = *(const PG8_LAS bf16x8*)(lds + PG8_SA(b, h) + aoff + m * 2048 + k * 1024); } while (0)
; #define PG8_LDB(dst, b, h) do { _Pragma("unroll") for (int n = 0; n < 2; ++n) _Pragma("unroll") for (int k = 0; k < 2; ++k) dst[n][k] = *(const PG8_LAS bf16x8*)(lds + PG8_SB(b, h) + boff + n * 2048 + k * 1024); } while (0)
; #define PG8_MMA(ai, bj, At, Bt) do { __builtin_amdgcn_s_setprio(1); _Pragma("unroll") for (int m = 0; m < 4; ++m) _Pragma("unroll") for (int n = 0; n < 2; ++n) _Pragma("unroll") for (int k = 0; k < 2; ++k) \
;         acc[ai][bj][m][n] = __builtin_amdgcn_mfma_f32_16x16x32_bf16(Bt[n][k], At[m][k], acc[ai][bj][m][n], 0, 0, 0); __builtin_amdgcn_s_setprio(0); } while (0)
; #define PG8_WAIT_V(n) asm volatile("s_waitcnt vmcnt(" #n ")" ::: "memory")
; #define PG8_WAIT_L(n) asm volatile("s_waitcnt lgkmcnt(" #n ")" ::: "memory")
; #define PG8_BAR __builtin_amdgcn_s_barrier()
; #define PG8_SCHED __builtin_amdgcn_sched_barrier(0)
; template <class Epi, class Sched, bool ALIGN_EPI = false, bool SP2 = false>
; __device__ __forceinline__ void gemm_phase(PG8_LAS unsigned char* lds, const Gemm g, const Sched& S, const Epi& E) {
;     ...
;             const char* a2 = last ? nA : cA + (size_t)(t + 2) * kstep; const char* b2 = last ? nB : cB + (size_t)(t + 2) * kstep;
;             const char* a3 = a2 + kstep; const char* b3 = b2 + kstep;
;             if (last && has_next) S.a_ready(nxt);
;             if constexpr (SP2) {
;             PG8_LDB(B0, 0, 0); PG8_LDB(B1, 0, 1); PG8_SCHED; PG8_LDA(At, 0, 0); PG8_STAGE(PG8_SA(1, 1), a1 + hstep, voffA);
;             PG8_WAIT_V(8); PG8_WAIT_L(0); PG8_BAR; PG8_MMA(0, 0, At, B0); PG8_MMA(0, 1, At, B1); PG8_BAR; PG8_SCHED;
;             PG8_LDA(At, 0, 1); PG8_STAGE(PG8_SB(0, 0), b2, voffB); PG8_STAGE(PG8_SB(0, 1), b2 + hstep, voffB); PG8_STAGE(PG8_SA(0, 0), a2, voffA);
.LBB0_817:
	ds_read_b128 v[108:111], v214
	ds_read_b128 v[124:127], v214 offset:1024
	ds_read_b128 v[136:139], v214 offset:2048
	ds_read_b128 v[140:143], v214 offset:3072
	ds_read_b128 v[144:147], v215
	ds_read_b128 v[148:151], v215 offset:1024
	ds_read_b128 v[152:155], v215 offset:2048
	ds_read_b128 v[180:183], v215 offset:3072
	s_add_u32 s4, s46, 0xfffc0080
	s_addc_u32 s5, s47, -1
	s_cmp_eq_u32 s83, 12
	s_cselect_b32 s67, s37, s5
	s_cselect_b32 s66, s45, s4
	s_cselect_b32 s65, s35, s82
	s_cselect_b32 s64, s80, s81
	v_lshl_add_u64 v[222:223], s[46:47], 0, v[172:173]
	s_add_i32 m0, s53, 0xc000
	ds_read_b128 v[184:187], v216
	ds_read_b128 v[188:191], v216 offset:1024
	ds_read_b128 v[192:195], v216 offset:2048
	ds_read_b128 v[196:199], v216 offset:3072
	ds_read_b128 v[200:203], v216 offset:4096
	ds_read_b128 v[204:207], v216 offset:5120
	ds_read_b128 v[208:211], v216 offset:6144
	ds_read_b128 v[218:221], v216 offset:7168
	global_load_lds_dwordx4 v[222:223], off
	v_lshl_add_u64 v[222:223], s[46:47], 0, v[174:175]
	s_add_i32 m0, s53, 0xe000
	s_nop 0
	global_load_lds_dwordx4 v[222:223], off
	s_waitcnt vmcnt(8)
	s_waitcnt lgkmcnt(0)
	s_barrier
	s_setprio 1
	v_mfma_f32_16x16x32_bf16 v[128:131], v[108:111], v[184:187], v[128:131]
	v_mfma_f32_16x16x32_bf16 v[120:123], v[136:139], v[184:187], v[120:123]
	v_mfma_f32_16x16x32_bf16 v[112:115], v[108:111], v[192:195], v[112:115]
	v_mfma_f32_16x16x32_bf16 v[100:103], v[136:139], v[192:195], v[100:103]
	v_mfma_f32_16x16x32_bf16 v[92:95], v[108:111], v[200:203], v[92:95]
	v_mfma_f32_16x16x32_bf16 v[84:87], v[136:139], v[200:203], v[84:87]
	v_mfma_f32_16x16x32_bf16 v[76:79], v[108:111], v[208:211], v[76:79]
	v_mfma_f32_16x16x32_bf16 v[68:71], v[136:139], v[208:211], v[68:71]
	v_mfma_f32_16x16x32_bf16 v[128:131], v[124:127], v[188:191], v[128:131]
	v_mfma_f32_16x16x32_bf16 v[120:123], v[140:143], v[188:191], v[120:123]
	v_mfma_f32_16x16x32_bf16 v[112:115], v[124:127], v[196:199], v[112:115]
	v_mfma_f32_16x16x32_bf16 v[100:103], v[140:143], v[196:199], v[100:103]
	v_mfma_f32_16x16x32_bf16 v[92:95], v[124:127], v[204:207], v[92:95]
	v_mfma_f32_16x16x32_bf16 v[84:87], v[140:143], v[204:207], v[84:87]
	v_mfma_f32_16x16x32_bf16 v[76:79], v[124:127], v[218:221], v[76:79]
	v_mfma_f32_16x16x32_bf16 v[68:71], v[140:143], v[218:221], v[68:71]
	s_setprio 0
	s_setprio 1
	v_mfma_f32_16x16x32_bf16 v[132:135], v[144:147], v[184:187], v[132:135]
	v_mfma_f32_16x16x32_bf16 v[116:119], v[152:155], v[184:187], v[116:119]
	v_mfma_f32_16x16x32_bf16 v[104:107], v[144:147], v[192:195], v[104:107]
	v_mfma_f32_16x16x32_bf16 v[96:99], v[152:155], v[192:195], v[96:99]
	v_mfma_f32_16x16x32_bf16 v[88:91], v[144:147], v[200:203], v[88:91]
	v_mfma_f32_16x16x32_bf16 v[80:83], v[152:155], v[200:203], v[80:83]
	v_mfma_f32_16x16x32_bf16 v[72:75], v[144:147], v[208:211], v[72:75]
	v_mfma_f32_16x16x32_bf16 v[64:67], v[152:155], v[208:211], v[64:67]
	v_mfma_f32_16x16x32_bf16 v[132:135], v[148:151], v[188:191], v[132:135]
	v_mfma_f32_16x16x32_bf16 v[116:119], v[180:183], v[188:191], v[116:119]
	v_mfma_f32_16x16x32_bf16 v[104:107], v[148:151], v[196:199], v[104:107]
	v_mfma_f32_16x16x32_bf16 v[96:99], v[180:183], v[196:199], v[96:99]
	v_mfma_f32_16x16x32_bf16 v[88:91], v[148:151], v[204:207], v[88:91]
	v_mfma_f32_16x16x32_bf16 v[80:83], v[180:183], v[204:207], v[80:83]
	v_mfma_f32_16x16x32_bf16 v[72:75], v[148:151], v[218:221], v[72:75]
	v_mfma_f32_16x16x32_bf16 v[64:67], v[180:183], v[218:221], v[64:67]
	s_barrier
	s_setprio 0
	s_add_i32 s4, s77, s49
	v_lshl_add_u64 v[222:223], s[64:65], 0, v[166:167]
	s_mov_b32 m0, s4
	ds_read_b128 v[184:187], v216 offset:16384
	ds_read_b128 v[188:191], v216 offset:17408
	ds_read_b128 v[192:195], v216 offset:18432
	ds_read_b128 v[196:199], v216 offset:19456
	ds_read_b128 v[200:203], v216 offset:20480
	ds_read_b128 v[204:207], v216 offset:21504
	ds_read_b128 v[208:211], v216 offset:22528
	ds_read_b128 v[218:221], v216 offset:23552
	global_load_lds_dwordx4 v[222:223], off
	s_add_i32 m0, s4, 0x2000
	s_add_u32 s4, s64, 0x40000
	v_lshl_add_u64 v[224:225], s[64:65], 0, v[170:171]
	s_addc_u32 s5, s65, 0
	s_add_i32 s14, s78, s49
	global_load_lds_dwordx4 v[224:225], off
	v_lshl_add_u64 v[226:227], s[4:5], 0, v[166:167]
	s_mov_b32 m0, s14
	v_lshl_add_u64 v[228:229], s[66:67], 0, v[168:169]
	global_load_lds_dwordx4 v[226:227], off
	v_lshl_add_u64 v[226:227], s[4:5], 0, v[170:171]
	s_add_i32 m0, s14, 0x2000
	s_nop 0
	global_load_lds_dwordx4 v[226:227], off
	v_lshl_add_u64 v[226:227], s[66:67], 0, v[164:165]
	s_mov_b32 m0, s53
	s_nop 0
	global_load_lds_dwordx4 v[226:227], off
	s_mov_b32 m0, s68
	s_nop 0
	global_load_lds_dwordx4 v[228:229], off
	s_waitcnt vmcnt(8)
	s_waitcnt lgkmcnt(0)
	s_barrier
; #define PG8_STAGE(bufoff, gbase, voff) do { _Pragma("unroll") for (int _i = 0; _i < 2; ++_i) \
;         __builtin_amdgcn_global_load_lds((const unsigned*)((const char*)(gbase) + (voff)[_i]), (PG8_LAS unsigned*)(lds + (bufoff) + ldsw + _i * 8192), 16, 0, 0); } while (0)
; #define PG8_LDA(dst, b, h) do { _Pragma("unroll") for (int m = 0; m < 4; ++m) _Pragma("unroll") for (int k = 0; k < 2; ++k) dst[m][k] = *(const PG8_LAS bf16x8*)(lds + PG8_SA(b, h) + aoff + m * 2048 + k * 1024); } while (0)
; #define PG8_LDB(dst, b, h) do { _Pragma("unroll") for (int n = 0; n < 2; ++n) _Pragma("unroll") for (int k = 0; k < 2; ++k) dst[n][k] = *(const PG8_LAS bf16x8*)(lds + PG8_SB(b, h) + boff + n * 2048 + k * 1024); } while (0)
; #define PG8_MMA(ai, bj, At, Bt) do { __builtin_amdgcn_s_setprio(1); _Pragma("unroll") for (int m = 0; m < 4; ++m) _Pragma("unroll") for (int n = 0; n < 2; ++n) _Pragma("unroll") for (int k = 0; k < 2; ++k) \
;         acc[ai][bj][m][n] = __builtin_amdgcn_mfma_f32_16x16x32_bf16(Bt[n][k], At[m][k], acc[ai][bj][m][n], 0, 0, 0); __builtin_amdgcn_s_setprio(0); } while (0)
; #define PG8_WAIT_V(n) asm volatile("s_waitcnt vmcnt(" #n ")" ::: "memory")
; #define PG8_WAIT_L(n) asm volatile("s_waitcnt lgkmcnt(" #n ")" ::: "memory")
; #define PG8_BAR __builtin_amdgcn_s_barrier()
; #define PG8_SCHED __builtin_amdgcn_sched_barrier(0)
; template <class Epi, class Sched, bool ALIGN_EPI = false, bool SP2 = false>
; __device__ __forceinline__ void gemm_phase(PG8_LAS unsigned char* lds, const Gemm g, const Sched& S, const Epi& E) {
;     ...
;             PG8_WAIT_V(8); PG8_WAIT_L(0); PG8_BAR; PG8_MMA(1, 0, At, B0); PG8_MMA(1, 1, At, B1); PG8_BAR; PG8_SCHED;
;             PG8_LDB(B0, 1, 0); PG8_LDB(B1, 1, 1); PG8_SCHED; PG8_LDA(At, 1, 0); PG8_STAGE(PG8_SA(0, 1), a2 + hstep, voffA);
;             PG8_WAIT_V(8); PG8_WAIT_L(0); PG8_BAR; PG8_MMA(0, 0, At, B0); PG8_MMA(0, 1, At, B1); PG8_BAR; PG8_SCHED;
	s_setprio 1
	v_mfma_f32_16x16x32_bf16 v[60:63], v[108:111], v[184:187], v[60:63]
	v_mfma_f32_16x16x32_bf16 v[52:55], v[136:139], v[184:187], v[52:55]
	v_mfma_f32_16x16x32_bf16 v[44:47], v[108:111], v[192:195], v[44:47]
	v_mfma_f32_16x16x32_bf16 v[36:39], v[136:139], v[192:195], v[36:39]
	v_mfma_f32_16x16x32_bf16 v[28:31], v[108:111], v[200:203], v[28:31]
	v_mfma_f32_16x16x32_bf16 v[20:23], v[136:139], v[200:203], v[20:23]
	v_mfma_f32_16x16x32_bf16 v[12:15], v[108:111], v[208:211], v[12:15]
	v_mfma_f32_16x16x32_bf16 v[4:7], v[136:139], v[208:211], v[4:7]
	v_mfma_f32_16x16x32_bf16 v[60:63], v[124:127], v[188:191], v[60:63]
	v_mfma_f32_16x16x32_bf16 v[52:55], v[140:143], v[188:191], v[52:55]
	v_mfma_f32_16x16x32_bf16 v[44:47], v[124:127], v[196:199], v[44:47]
	v_mfma_f32_16x16x32_bf16 v[36:39], v[140:143], v[196:199], v[36:39]
	v_mfma_f32_16x16x32_bf16 v[28:31], v[124:127], v[204:207], v[28:31]
	v_mfma_f32_16x16x32_bf16 v[20:23], v[140:143], v[204:207], v[20:23]
	v_mfma_f32_16x16x32_bf16 v[12:15], v[124:127], v[218:221], v[12:15]
	v_mfma_f32_16x16x32_bf16 v[4:7], v[140:143], v[218:221], v[4:7]
	s_setprio 0
	s_setprio 1
	v_mfma_f32_16x16x32_bf16 v[56:59], v[144:147], v[184:187], v[56:59]
	v_mfma_f32_16x16x32_bf16 v[48:51], v[152:155], v[184:187], v[48:51]
	v_mfma_f32_16x16x32_bf16 v[40:43], v[144:147], v[192:195], v[40:43]
	v_mfma_f32_16x16x32_bf16 v[32:35], v[152:155], v[192:195], v[32:35]
	v_mfma_f32_16x16x32_bf16 v[24:27], v[144:147], v[200:203], v[24:27]
	v_mfma_f32_16x16x32_bf16 v[16:19], v[152:155], v[200:203], v[16:19]
	v_mfma_f32_16x16x32_bf16 v[8:11], v[144:147], v[208:211], v[8:11]
	v_mfma_f32_16x16x32_bf16 v[0:3], v[152:155], v[208:211], v[0:3]
	v_mfma_f32_16x16x32_bf16 v[56:59], v[148:151], v[188:191], v[56:59]
	v_mfma_f32_16x16x32_bf16 v[48:51], v[180:183], v[188:191], v[48:51]
	v_mfma_f32_16x16x32_bf16 v[40:43], v[148:151], v[196:199], v[40:43]
	v_mfma_f32_16x16x32_bf16 v[32:35], v[180:183], v[196:199], v[32:35]
	v_mfma_f32_16x16x32_bf16 v[24:27], v[148:151], v[204:207], v[24:27]
	v_mfma_f32_16x16x32_bf16 v[16:19], v[180:183], v[204:207], v[16:19]
	v_mfma_f32_16x16x32_bf16 v[8:11], v[148:151], v[218:221], v[8:11]
	v_mfma_f32_16x16x32_bf16 v[0:3], v[180:183], v[218:221], v[0:3]
	s_barrier
	s_setprio 0
	s_add_i32 s14, 0, 0x18000
	s_add_i32 s15, 0, 0x1c000
	v_add_u32_e32 v140, s14, v159
	v_add_u32_e32 v180, s15, v159
	ds_read_b128 v[108:111], v140
	ds_read_b128 v[124:127], v140 offset:1024
	ds_read_b128 v[136:139], v140 offset:2048
	ds_read_b128 v[140:143], v140 offset:3072
	ds_read_b128 v[144:147], v180
	ds_read_b128 v[148:151], v180 offset:1024
	ds_read_b128 v[152:155], v180 offset:2048
	ds_read_b128 v[180:183], v180 offset:3072
	s_add_u32 s4, s66, 0x40000
	s_addc_u32 s5, s67, 0
	s_mov_b32 m0, s69
	v_lshl_add_u64 v[230:231], s[4:5], 0, v[164:165]
	ds_read_b128 v[184:187], v216 offset:32768
	ds_read_b128 v[188:191], v216 offset:33792
	ds_read_b128 v[192:195], v216 offset:34816
	ds_read_b128 v[196:199], v216 offset:35840
	ds_read_b128 v[200:203], v216 offset:36864
	ds_read_b128 v[204:207], v216 offset:37888
	ds_read_b128 v[208:211], v216 offset:38912
	ds_read_b128 v[218:221], v216 offset:39936
	global_load_lds_dwordx4 v[230:231], off
	v_lshl_add_u64 v[230:231], s[4:5], 0, v[168:169]
	s_mov_b32 m0, s70
	s_nop 0
	global_load_lds_dwordx4 v[230:231], off
	s_waitcnt vmcnt(8)
	s_waitcnt lgkmcnt(0)
	s_barrier
	s_setprio 1
	v_mfma_f32_16x16x32_bf16 v[128:131], v[108:111], v[184:187], v[128:131]
	v_mfma_f32_16x16x32_bf16 v[120:123], v[136:139], v[184:187], v[120:123]
	v_mfma_f32_16x16x32_bf16 v[112:115], v[108:111], v[192:195], v[112:115]
	v_mfma_f32_16x16x32_bf16 v[100:103], v[136:139], v[192:195], v[100:103]
	v_mfma_f32_16x16x32_bf16 v[92:95], v[108:111], v[200:203], v[92:95]
	v_mfma_f32_16x16x32_bf16 v[84:87], v[136:139], v[200:203], v[84:87]
	v_mfma_f32_16x16x32_bf16 v[76:79], v[108:111], v[208:211], v[76:79]
	v_mfma_f32_16x16x32_bf16 v[68:71], v[136:139], v[208:211], v[68:71]
	v_mfma_f32_16x16x32_bf16 v[128:131], v[124:127], v[188:191], v[128:131]
	v_mfma_f32_16x16x32_bf16 v[120:123], v[140:143], v[188:191], v[120:123]
	v_mfma_f32_16x16x32_bf16 v[112:115], v[124:127], v[196:199], v[112:115]
	v_mfma_f32_16x16x32_bf16 v[100:103], v[140:143], v[196:199], v[100:103]
	v_mfma_f32_16x16x32_bf16 v[92:95], v[124:127], v[204:207], v[92:95]
	v_mfma_f32_16x16x32_bf16 v[84:87], v[140:143], v[204:207], v[84:87]
	v_mfma_f32_16x16x32_bf16 v[76:79], v[124:127], v[218:221], v[76:79]
	v_mfma_f32_16x16x32_bf16 v[68:71], v[140:143], v[218:221], v[68:71]
	s_setprio 0
	s_setprio 1
	v_mfma_f32_16x16x32_bf16 v[132:135], v[144:147], v[184:187], v[132:135]
	v_mfma_f32_16x16x32_bf16 v[116:119], v[152:155], v[184:187], v[116:119]
	v_mfma_f32_16x16x32_bf16 v[104:107], v[144:147], v[192:195], v[104:107]
	v_mfma_f32_16x16x32_bf16 v[96:99], v[152:155], v[192:195], v[96:99]
	v_mfma_f32_16x16x32_bf16 v[88:91], v[144:147], v[200:203], v[88:91]
	v_mfma_f32_16x16x32_bf16 v[80:83], v[152:155], v[200:203], v[80:83]
	v_mfma_f32_16x16x32_bf16 v[72:75], v[144:147], v[208:211], v[72:75]
	v_mfma_f32_16x16x32_bf16 v[64:67], v[152:155], v[208:211], v[64:67]
	v_mfma_f32_16x16x32_bf16 v[132:135], v[148:151], v[188:191], v[132:135]
	v_mfma_f32_16x16x32_bf16 v[116:119], v[180:183], v[188:191], v[116:119]
	v_mfma_f32_16x16x32_bf16 v[104:107], v[148:151], v[196:199], v[104:107]
	v_mfma_f32_16x16x32_bf16 v[96:99], v[180:183], v[196:199], v[96:99]
	v_mfma_f32_16x16x32_bf16 v[88:91], v[148:151], v[204:207], v[88:91]
	v_mfma_f32_16x16x32_bf16 v[80:83], v[180:183], v[204:207], v[80:83]
	v_mfma_f32_16x16x32_bf16 v[72:75], v[148:151], v[218:221], v[72:75]
	v_mfma_f32_16x16x32_bf16 v[64:67], v[180:183], v[218:221], v[64:67]
	s_barrier
; #define PG8_STAGE(bufoff, gbase, voff) do { _Pragma("unroll") for (int _i = 0; _i < 2; ++_i) \
;         __builtin_amdgcn_global_load_lds((const unsigned*)((const char*)(gbase) + (voff)[_i]), (PG8_LAS unsigned*)(lds + (bufoff) + ldsw + _i * 8192), 16, 0, 0); } while (0)
; #define PG8_LDA(dst, b, h) do { _Pragma("unroll") for (int m = 0; m < 4; ++m) _Pragma("unroll") for (int k = 0; k < 2; ++k) dst[m][k] = *(const PG8_LAS bf16x8*)(lds + PG8_SA(b, h) + aoff + m * 2048 + k * 1024); } while (0)
; #define PG8_MMA(ai, bj, At, Bt) do { __builtin_amdgcn_s_setprio(1); _Pragma("unroll") for (int m = 0; m < 4; ++m) _Pragma("unroll") for (int n = 0; n < 2; ++n) _Pragma("unroll") for (int k = 0; k < 2; ++k) \
;         acc[ai][bj][m][n] = __builtin_amdgcn_mfma_f32_16x16x32_bf16(Bt[n][k], At[m][k], acc[ai][bj][m][n], 0, 0, 0); __builtin_amdgcn_s_setprio(0); } while (0)
; #define PG8_WAIT_V(n) asm volatile("s_waitcnt vmcnt(" #n ")" ::: "memory")
; #define PG8_WAIT_L(n) asm volatile("s_waitcnt lgkmcnt(" #n ")" ::: "memory")
; #define PG8_BAR __builtin_amdgcn_s_barrier()
; #define PG8_SCHED __builtin_amdgcn_sched_barrier(0)
; template <class Epi, class Sched, bool ALIGN_EPI = false, bool SP2 = false>
; __device__ __forceinline__ void gemm_phase(PG8_LAS unsigned char* lds, const Gemm g, const Sched& S, const Epi& E) {
;     ...
;             PG8_LDA(At, 1, 1); PG8_STAGE(PG8_SB(1, 0), b3, voffB); PG8_STAGE(PG8_SB(1, 1), b3 + hstep, voffB); PG8_STAGE(PG8_SA(1, 0), a3, voffA);
;             PG8_WAIT_V(8); PG8_WAIT_L(0); PG8_BAR; PG8_MMA(1, 0, At, B0); PG8_MMA(1, 1, At, B1); PG8_BAR; PG8_SCHED;
	s_setprio 0
	s_add_i32 s4, s14, s49
	v_lshl_add_u64 v[222:223], v[222:223], 0, s[28:29]
	s_mov_b32 m0, s4
	ds_read_b128 v[184:187], v216 offset:49152
	ds_read_b128 v[188:191], v216 offset:50176
	ds_read_b128 v[192:195], v216 offset:51200
	ds_read_b128 v[196:199], v216 offset:52224
	ds_read_b128 v[200:203], v216 offset:53248
	ds_read_b128 v[204:207], v216 offset:54272
	ds_read_b128 v[208:211], v216 offset:55296
	ds_read_b128 v[218:221], v216 offset:56320
	global_load_lds_dwordx4 v[222:223], off
	s_add_i32 m0, s4, 0x2000
	s_add_u32 s4, s64, 0x40080
	v_lshl_add_u64 v[222:223], v[224:225], 0, s[28:29]
	s_addc_u32 s5, s65, 0
	s_add_i32 s14, s15, s49
	global_load_lds_dwordx4 v[222:223], off
	v_lshl_add_u64 v[222:223], s[4:5], 0, v[166:167]
	s_mov_b32 m0, s14
	s_nop 0
	global_load_lds_dwordx4 v[222:223], off
	v_lshl_add_u64 v[222:223], s[4:5], 0, v[170:171]
	s_add_i32 m0, s14, 0x2000
	s_nop 0
	global_load_lds_dwordx4 v[222:223], off
	v_lshl_add_u64 v[222:223], v[226:227], 0, s[28:29]
	s_mov_b32 m0, s72
	s_nop 0
	global_load_lds_dwordx4 v[222:223], off
	v_lshl_add_u64 v[222:223], v[228:229], 0, s[28:29]
	s_mov_b32 m0, s73
	s_nop 0
	global_load_lds_dwordx4 v[222:223], off
	s_waitcnt vmcnt(8)
	s_waitcnt lgkmcnt(0)
	s_barrier
	s_setprio 1
	v_mfma_f32_16x16x32_bf16 v[60:63], v[108:111], v[184:187], v[60:63]
	v_mfma_f32_16x16x32_bf16 v[52:55], v[136:139], v[184:187], v[52:55]
	v_mfma_f32_16x16x32_bf16 v[44:47], v[108:111], v[192:195], v[44:47]
	v_mfma_f32_16x16x32_bf16 v[36:39], v[136:139], v[192:195], v[36:39]
	v_mfma_f32_16x16x32_bf16 v[28:31], v[108:111], v[200:203], v[28:31]
	v_mfma_f32_16x16x32_bf16 v[20:23], v[136:139], v[200:203], v[20:23]
	v_mfma_f32_16x16x32_bf16 v[12:15], v[108:111], v[208:211], v[12:15]
	v_mfma_f32_16x16x32_bf16 v[4:7], v[136:139], v[208:211], v[4:7]
	v_mfma_f32_16x16x32_bf16 v[60:63], v[124:127], v[188:191], v[60:63]
	v_mfma_f32_16x16x32_bf16 v[52:55], v[140:143], v[188:191], v[52:55]
	v_mfma_f32_16x16x32_bf16 v[44:47], v[124:127], v[196:199], v[44:47]
	v_mfma_f32_16x16x32_bf16 v[36:39], v[140:143], v[196:199], v[36:39]
	v_mfma_f32_16x16x32_bf16 v[28:31], v[124:127], v[204:207], v[28:31]
	v_mfma_f32_16x16x32_bf16 v[20:23], v[140:143], v[204:207], v[20:23]
	v_mfma_f32_16x16x32_bf16 v[12:15], v[124:127], v[218:221], v[12:15]
	v_mfma_f32_16x16x32_bf16 v[4:7], v[140:143], v[218:221], v[4:7]
	s_setprio 0
	s_setprio 1
	v_mfma_f32_16x16x32_bf16 v[56:59], v[144:147], v[184:187], v[56:59]
	v_mfma_f32_16x16x32_bf16 v[48:51], v[152:155], v[184:187], v[48:51]
	v_mfma_f32_16x16x32_bf16 v[40:43], v[144:147], v[192:195], v[40:43]
	v_mfma_f32_16x16x32_bf16 v[32:35], v[152:155], v[192:195], v[32:35]
	v_mfma_f32_16x16x32_bf16 v[24:27], v[144:147], v[200:203], v[24:27]
	v_mfma_f32_16x16x32_bf16 v[16:19], v[152:155], v[200:203], v[16:19]
	v_mfma_f32_16x16x32_bf16 v[8:11], v[144:147], v[208:211], v[8:11]
	v_mfma_f32_16x16x32_bf16 v[0:3], v[152:155], v[208:211], v[0:3]
	v_mfma_f32_16x16x32_bf16 v[56:59], v[148:151], v[188:191], v[56:59]
	v_mfma_f32_16x16x32_bf16 v[48:51], v[180:183], v[188:191], v[48:51]
	v_mfma_f32_16x16x32_bf16 v[40:43], v[148:151], v[196:199], v[40:43]
	v_mfma_f32_16x16x32_bf16 v[32:35], v[180:183], v[196:199], v[32:35]
	v_mfma_f32_16x16x32_bf16 v[24:27], v[148:151], v[204:207], v[24:27]
	v_mfma_f32_16x16x32_bf16 v[16:19], v[180:183], v[204:207], v[16:19]
	v_mfma_f32_16x16x32_bf16 v[8:11], v[148:151], v[218:221], v[8:11]
	v_mfma_f32_16x16x32_bf16 v[0:3], v[180:183], v[218:221], v[0:3]
	s_barrier
	s_setprio 0
	s_add_i32 s83, s83, 2
	s_add_u32 s46, s46, 0x100
	s_addc_u32 s47, s47, 0
	s_add_u32 s81, s81, 0x100
	s_addc_u32 s82, s82, 0
	s_cmp_gt_u32 s83, 13
	s_cbranch_scc0 .LBB0_817
	s_and_b64 vcc, exec, s[30:31]
	s_cbranch_vccz .LBB0_820
	s_barrier

; #define PG8_STAGE(bufoff, gbase, voff) do { _Pragma("unroll") for (int _i = 0; _i < 2; ++_i) \
;         __builtin_amdgcn_global_load_lds((const unsigned*)((const char*)(gbase) + (voff)[_i]), (PG8_LAS unsigned*)(lds + (bufoff) + ldsw + _i * 8192), 16, 0, 0); } while (0)
; #define PG8_LDA(dst, b, h) do { _Pragma("unroll") for (int m = 0; m < 4; ++m) _Pragma("unroll") for (int k = 0; k < 2; ++k) dst[m][k] = *(const PG8_LAS bf16x8*)(lds + PG8_SA(b, h) + aoff + m * 2048 + k * 1024); } while (0)
; #define PG8_LDB(dst, b, h) do { _Pragma("unroll") for (int n = 0; n < 2; ++n) _Pragma("unroll") for (int k = 0; k < 2; ++k) dst[n][k] = *(const PG8_LAS bf16x8*)(lds + PG8_SB(b, h) + boff + n * 2048 + k * 1024); } while (0)
; #define PG8_MMA(ai, bj, At, Bt) do { __builtin_amdgcn_s_setprio(1); _Pragma("unroll") for (int m = 0; m < 4; ++m) _Pragma("unroll") for (int n = 0; n < 2; ++n) _Pragma("unroll") for (int k = 0; k < 2; ++k) \
;         acc[ai][bj][m][n] = __builtin_amdgcn_mfma_f32_16x16x32_bf16(Bt[n][k], At[m][k], acc[ai][bj][m][n], 0, 0, 0); __builtin_amdgcn_s_setprio(0); } while (0)
; #define PG8_WAIT_V(n) asm volatile("s_waitcnt vmcnt(" #n ")" ::: "memory")
; #define PG8_WAIT_L(n) asm volatile("s_waitcnt lgkmcnt(" #n ")" ::: "memory")
; #define PG8_BAR __builtin_amdgcn_s_barrier()
; #define PG8_SCHED __builtin_amdgcn_sched_barrier(0)
; template <class Epi, class Sched, bool ALIGN_EPI = false, bool SP2 = false>
; __device__ __forceinline__ void gemm_phase(PG8_LAS unsigned char* lds, const Gemm g, const Sched& S, const Epi& E) {
;     ...
;             const char* a2 = last ? nA : cA + (size_t)(t + 2) * kstep; const char* b2 = last ? nB : cB + (size_t)(t + 2) * kstep;
;             const char* a3 = a2 + kstep; const char* b3 = b2 + kstep;
;             if (last && has_next) S.a_ready(nxt);
;             if constexpr (SP2) {
;             PG8_LDB(B0, 0, 0); PG8_LDB(B1, 0, 1); PG8_SCHED; PG8_LDA(At, 0, 0); PG8_STAGE(PG8_SA(1, 1), a1 + hstep, voffA);
;             PG8_WAIT_V(8); PG8_WAIT_L(0); PG8_BAR; PG8_MMA(0, 0, At, B0); PG8_MMA(0, 1, At, B1); PG8_BAR; PG8_SCHED;
;             PG8_LDA(At, 0, 1); PG8_STAGE(PG8_SB(0, 0), b2, voffB); PG8_STAGE(PG8_SB(0, 1), b2 + hstep, voffB); PG8_STAGE(PG8_SA(0, 0), a2, voffA);
.LBB0_910:
	ds_read_b128 v[146:149], v159
	ds_read_b128 v[150:153], v159 offset:1024
	ds_read_b128 v[164:167], v159 offset:2048
	ds_read_b128 v[168:171], v159 offset:3072
	ds_read_b128 v[172:175], v160
	ds_read_b128 v[176:179], v160 offset:1024
	ds_read_b128 v[180:183], v160 offset:2048
	ds_read_b128 v[184:187], v160 offset:3072
	s_add_u32 s28, s26, 0xfffc0080
	s_addc_u32 s29, s27, -1
	s_cmp_eq_u32 s70, 12
	s_cselect_b32 s31, s19, s29
	s_cselect_b32 s30, s66, s28
	s_cselect_b32 s29, s11, s69
	s_cselect_b32 s28, s67, s68
	v_lshl_add_u64 v[222:223], s[26:27], 0, v[138:139]
	s_add_i32 m0, s25, 0xc000
	ds_read_b128 v[188:191], v161
	ds_read_b128 v[192:195], v161 offset:1024
	ds_read_b128 v[196:199], v161 offset:2048
	ds_read_b128 v[200:203], v161 offset:3072
	ds_read_b128 v[204:207], v161 offset:4096
	ds_read_b128 v[208:211], v161 offset:5120
	ds_read_b128 v[214:217], v161 offset:6144
	ds_read_b128 v[218:221], v161 offset:7168
	global_load_lds_dwordx4 v[222:223], off
	v_lshl_add_u64 v[222:223], s[26:27], 0, v[140:141]
	s_add_i32 m0, s25, 0xe000
	s_nop 0
	global_load_lds_dwordx4 v[222:223], off
	s_waitcnt vmcnt(8)
	s_waitcnt lgkmcnt(0)
	s_barrier
	s_setprio 1
	v_mfma_f32_16x16x32_bf16 v[124:127], v[146:149], v[188:191], v[124:127]
	v_mfma_f32_16x16x32_bf16 v[116:119], v[164:167], v[188:191], v[116:119]
	v_mfma_f32_16x16x32_bf16 v[108:111], v[146:149], v[196:199], v[108:111]
	v_mfma_f32_16x16x32_bf16 v[100:103], v[164:167], v[196:199], v[100:103]
	v_mfma_f32_16x16x32_bf16 v[92:95], v[146:149], v[204:207], v[92:95]
	v_mfma_f32_16x16x32_bf16 v[84:87], v[164:167], v[204:207], v[84:87]
	v_mfma_f32_16x16x32_bf16 v[76:79], v[146:149], v[214:217], v[76:79]
	v_mfma_f32_16x16x32_bf16 v[68:71], v[164:167], v[214:217], v[68:71]
	v_mfma_f32_16x16x32_bf16 v[124:127], v[150:153], v[192:195], v[124:127]
	v_mfma_f32_16x16x32_bf16 v[116:119], v[168:171], v[192:195], v[116:119]
	v_mfma_f32_16x16x32_bf16 v[108:111], v[150:153], v[200:203], v[108:111]
	v_mfma_f32_16x16x32_bf16 v[100:103], v[168:171], v[200:203], v[100:103]
	v_mfma_f32_16x16x32_bf16 v[92:95], v[150:153], v[208:211], v[92:95]
	v_mfma_f32_16x16x32_bf16 v[84:87], v[168:171], v[208:211], v[84:87]
	v_mfma_f32_16x16x32_bf16 v[76:79], v[150:153], v[218:221], v[76:79]
	v_mfma_f32_16x16x32_bf16 v[68:71], v[168:171], v[218:221], v[68:71]
	s_setprio 0
	s_setprio 1
	v_mfma_f32_16x16x32_bf16 v[120:123], v[172:175], v[188:191], v[120:123]
	v_mfma_f32_16x16x32_bf16 v[112:115], v[180:183], v[188:191], v[112:115]
	v_mfma_f32_16x16x32_bf16 v[104:107], v[172:175], v[196:199], v[104:107]
	v_mfma_f32_16x16x32_bf16 v[96:99], v[180:183], v[196:199], v[96:99]
	v_mfma_f32_16x16x32_bf16 v[88:91], v[172:175], v[204:207], v[88:91]
	v_mfma_f32_16x16x32_bf16 v[80:83], v[180:183], v[204:207], v[80:83]
	v_mfma_f32_16x16x32_bf16 v[72:75], v[172:175], v[214:217], v[72:75]
	v_mfma_f32_16x16x32_bf16 v[64:67], v[180:183], v[214:217], v[64:67]
	v_mfma_f32_16x16x32_bf16 v[120:123], v[176:179], v[192:195], v[120:123]
	v_mfma_f32_16x16x32_bf16 v[112:115], v[184:187], v[192:195], v[112:115]
	v_mfma_f32_16x16x32_bf16 v[104:107], v[176:179], v[200:203], v[104:107]
	v_mfma_f32_16x16x32_bf16 v[96:99], v[184:187], v[200:203], v[96:99]
	v_mfma_f32_16x16x32_bf16 v[88:91], v[176:179], v[208:211], v[88:91]
	v_mfma_f32_16x16x32_bf16 v[80:83], v[184:187], v[208:211], v[80:83]
	v_mfma_f32_16x16x32_bf16 v[72:75], v[176:179], v[218:221], v[72:75]
	v_mfma_f32_16x16x32_bf16 v[64:67], v[184:187], v[218:221], v[64:67]
	s_barrier
	s_setprio 0
	s_add_i32 s71, s49, s35
	v_lshl_add_u64 v[222:223], s[28:29], 0, v[132:133]
	s_mov_b32 m0, s71
	ds_read_b128 v[188:191], v161 offset:16384
	ds_read_b128 v[192:195], v161 offset:17408
	ds_read_b128 v[196:199], v161 offset:18432
	ds_read_b128 v[200:203], v161 offset:19456
	ds_read_b128 v[204:207], v161 offset:20480
	ds_read_b128 v[208:211], v161 offset:21504
	ds_read_b128 v[214:217], v161 offset:22528
	ds_read_b128 v[218:221], v161 offset:23552
	global_load_lds_dwordx4 v[222:223], off
	s_add_i32 m0, s71, 0x2000
	s_add_u32 s72, s28, 0x40000
	v_lshl_add_u64 v[224:225], s[28:29], 0, v[128:129]
	s_addc_u32 s73, s29, 0
	s_add_i32 s71, s53, s35
	global_load_lds_dwordx4 v[224:225], off
	v_lshl_add_u64 v[226:227], s[72:73], 0, v[132:133]
	s_mov_b32 m0, s71
	v_lshl_add_u64 v[228:229], s[30:31], 0, v[130:131]
	global_load_lds_dwordx4 v[226:227], off
	v_lshl_add_u64 v[226:227], s[72:73], 0, v[128:129]
	s_add_i32 m0, s71, 0x2000
	s_nop 0
	global_load_lds_dwordx4 v[226:227], off
	v_lshl_add_u64 v[226:227], s[30:31], 0, v[134:135]
	s_mov_b32 m0, s25
	s_nop 0
	global_load_lds_dwordx4 v[226:227], off
	s_mov_b32 m0, s38
	s_nop 0
	global_load_lds_dwordx4 v[228:229], off
	s_waitcnt vmcnt(8)
	s_waitcnt lgkmcnt(0)
	s_barrier
; #define PG8_STAGE(bufoff, gbase, voff) do { _Pragma("unroll") for (int _i = 0; _i < 2; ++_i) \
;         __builtin_amdgcn_global_load_lds((const unsigned*)((const char*)(gbase) + (voff)[_i]), (PG8_LAS unsigned*)(lds + (bufoff) + ldsw + _i * 8192), 16, 0, 0); } while (0)
; #define PG8_LDA(dst, b, h) do { _Pragma("unroll") for (int m = 0; m < 4; ++m) _Pragma("unroll") for (int k = 0; k < 2; ++k) dst[m][k] = *(const PG8_LAS bf16x8*)(lds + PG8_SA(b, h) + aoff + m * 2048 + k * 1024); } while (0)
; #define PG8_LDB(dst, b, h) do { _Pragma("unroll") for (int n = 0; n < 2; ++n) _Pragma("unroll") for (int k = 0; k < 2; ++k) dst[n][k] = *(const PG8_LAS bf16x8*)(lds + PG8_SB(b, h) + boff + n * 2048 + k * 1024); } while (0)
; #define PG8_MMA(ai, bj, At, Bt) do { __builtin_amdgcn_s_setprio(1); _Pragma("unroll") for (int m = 0; m < 4; ++m) _Pragma("unroll") for (int n = 0; n < 2; ++n) _Pragma("unroll") for (int k = 0; k < 2; ++k) \
;         acc[ai][bj][m][n] = __builtin_amdgcn_mfma_f32_16x16x32_bf16(Bt[n][k], At[m][k], acc[ai][bj][m][n], 0, 0, 0); __builtin_amdgcn_s_setprio(0); } while (0)
; #define PG8_WAIT_V(n) asm volatile("s_waitcnt vmcnt(" #n ")" ::: "memory")
; #define PG8_WAIT_L(n) asm volatile("s_waitcnt lgkmcnt(" #n ")" ::: "memory")
; #define PG8_BAR __builtin_amdgcn_s_barrier()
; #define PG8_SCHED __builtin_amdgcn_sched_barrier(0)
; template <class Epi, class Sched, bool ALIGN_EPI = false, bool SP2 = false>
; __device__ __forceinline__ void gemm_phase(PG8_LAS unsigned char* lds, const Gemm g, const Sched& S, const Epi& E) {
;     ...
;             PG8_WAIT_V(8); PG8_WAIT_L(0); PG8_BAR; PG8_MMA(1, 0, At, B0); PG8_MMA(1, 1, At, B1); PG8_BAR; PG8_SCHED;
;             PG8_LDB(B0, 1, 0); PG8_LDB(B1, 1, 1); PG8_SCHED; PG8_LDA(At, 1, 0); PG8_STAGE(PG8_SA(0, 1), a2 + hstep, voffA);
;             PG8_WAIT_V(8); PG8_WAIT_L(0); PG8_BAR; PG8_MMA(0, 0, At, B0); PG8_MMA(0, 1, At, B1); PG8_BAR; PG8_SCHED;
	s_setprio 1
	v_mfma_f32_16x16x32_bf16 v[60:63], v[146:149], v[188:191], v[60:63]
	v_mfma_f32_16x16x32_bf16 v[52:55], v[164:167], v[188:191], v[52:55]
	v_mfma_f32_16x16x32_bf16 v[44:47], v[146:149], v[196:199], v[44:47]
	v_mfma_f32_16x16x32_bf16 v[36:39], v[164:167], v[196:199], v[36:39]
	v_mfma_f32_16x16x32_bf16 v[28:31], v[146:149], v[204:207], v[28:31]
	v_mfma_f32_16x16x32_bf16 v[20:23], v[164:167], v[204:207], v[20:23]
	v_mfma_f32_16x16x32_bf16 v[12:15], v[146:149], v[214:217], v[12:15]
	v_mfma_f32_16x16x32_bf16 v[4:7], v[164:167], v[214:217], v[4:7]
	v_mfma_f32_16x16x32_bf16 v[60:63], v[150:153], v[192:195], v[60:63]
	v_mfma_f32_16x16x32_bf16 v[52:55], v[168:171], v[192:195], v[52:55]
	v_mfma_f32_16x16x32_bf16 v[44:47], v[150:153], v[200:203], v[44:47]
	v_mfma_f32_16x16x32_bf16 v[36:39], v[168:171], v[200:203], v[36:39]
	v_mfma_f32_16x16x32_bf16 v[28:31], v[150:153], v[208:211], v[28:31]
	v_mfma_f32_16x16x32_bf16 v[20:23], v[168:171], v[208:211], v[20:23]
	v_mfma_f32_16x16x32_bf16 v[12:15], v[150:153], v[218:221], v[12:15]
	v_mfma_f32_16x16x32_bf16 v[4:7], v[168:171], v[218:221], v[4:7]
	s_setprio 0
	s_setprio 1
	v_mfma_f32_16x16x32_bf16 v[56:59], v[172:175], v[188:191], v[56:59]
	v_mfma_f32_16x16x32_bf16 v[48:51], v[180:183], v[188:191], v[48:51]
	v_mfma_f32_16x16x32_bf16 v[40:43], v[172:175], v[196:199], v[40:43]
	v_mfma_f32_16x16x32_bf16 v[32:35], v[180:183], v[196:199], v[32:35]
	v_mfma_f32_16x16x32_bf16 v[24:27], v[172:175], v[204:207], v[24:27]
	v_mfma_f32_16x16x32_bf16 v[16:19], v[180:183], v[204:207], v[16:19]
	v_mfma_f32_16x16x32_bf16 v[8:11], v[172:175], v[214:217], v[8:11]
	v_mfma_f32_16x16x32_bf16 v[0:3], v[180:183], v[214:217], v[0:3]
	v_mfma_f32_16x16x32_bf16 v[56:59], v[176:179], v[192:195], v[56:59]
	v_mfma_f32_16x16x32_bf16 v[48:51], v[184:187], v[192:195], v[48:51]
	v_mfma_f32_16x16x32_bf16 v[40:43], v[176:179], v[200:203], v[40:43]
	v_mfma_f32_16x16x32_bf16 v[32:35], v[184:187], v[200:203], v[32:35]
	v_mfma_f32_16x16x32_bf16 v[24:27], v[176:179], v[208:211], v[24:27]
	v_mfma_f32_16x16x32_bf16 v[16:19], v[184:187], v[208:211], v[16:19]
	v_mfma_f32_16x16x32_bf16 v[8:11], v[176:179], v[218:221], v[8:11]
	v_mfma_f32_16x16x32_bf16 v[0:3], v[184:187], v[218:221], v[0:3]
	s_barrier
	s_setprio 0
	s_add_i32 s71, 0, 0x18000
	s_add_i32 s72, 0, 0x1c000
	v_add_u32_e32 v168, s71, v155
	v_add_u32_e32 v184, s72, v155
	ds_read_b128 v[146:149], v168
	ds_read_b128 v[150:153], v168 offset:1024
	ds_read_b128 v[164:167], v168 offset:2048
	ds_read_b128 v[168:171], v168 offset:3072
	ds_read_b128 v[172:175], v184
	ds_read_b128 v[176:179], v184 offset:1024
	ds_read_b128 v[180:183], v184 offset:2048
	ds_read_b128 v[184:187], v184 offset:3072
	s_add_u32 s30, s30, 0x40000
	s_addc_u32 s31, s31, 0
	s_mov_b32 m0, s39
	v_lshl_add_u64 v[230:231], s[30:31], 0, v[134:135]
	ds_read_b128 v[188:191], v161 offset:32768
	ds_read_b128 v[192:195], v161 offset:33792
	ds_read_b128 v[196:199], v161 offset:34816
	ds_read_b128 v[200:203], v161 offset:35840
	ds_read_b128 v[204:207], v161 offset:36864
	ds_read_b128 v[208:211], v161 offset:37888
	ds_read_b128 v[214:217], v161 offset:38912
	ds_read_b128 v[218:221], v161 offset:39936
	global_load_lds_dwordx4 v[230:231], off
	v_lshl_add_u64 v[230:231], s[30:31], 0, v[130:131]
	s_mov_b32 m0, s40
	s_nop 0
	global_load_lds_dwordx4 v[230:231], off
	s_waitcnt vmcnt(8)
	s_waitcnt lgkmcnt(0)
	s_barrier
	s_setprio 1
	v_mfma_f32_16x16x32_bf16 v[124:127], v[146:149], v[188:191], v[124:127]
	v_mfma_f32_16x16x32_bf16 v[116:119], v[164:167], v[188:191], v[116:119]
	v_mfma_f32_16x16x32_bf16 v[108:111], v[146:149], v[196:199], v[108:111]
	v_mfma_f32_16x16x32_bf16 v[100:103], v[164:167], v[196:199], v[100:103]
	v_mfma_f32_16x16x32_bf16 v[92:95], v[146:149], v[204:207], v[92:95]
	v_mfma_f32_16x16x32_bf16 v[84:87], v[164:167], v[204:207], v[84:87]
	v_mfma_f32_16x16x32_bf16 v[76:79], v[146:149], v[214:217], v[76:79]
	v_mfma_f32_16x16x32_bf16 v[68:71], v[164:167], v[214:217], v[68:71]
	v_mfma_f32_16x16x32_bf16 v[124:127], v[150:153], v[192:195], v[124:127]
	v_mfma_f32_16x16x32_bf16 v[116:119], v[168:171], v[192:195], v[116:119]
	v_mfma_f32_16x16x32_bf16 v[108:111], v[150:153], v[200:203], v[108:111]
	v_mfma_f32_16x16x32_bf16 v[100:103], v[168:171], v[200:203], v[100:103]
	v_mfma_f32_16x16x32_bf16 v[92:95], v[150:153], v[208:211], v[92:95]
	v_mfma_f32_16x16x32_bf16 v[84:87], v[168:171], v[208:211], v[84:87]
	v_mfma_f32_16x16x32_bf16 v[76:79], v[150:153], v[218:221], v[76:79]
	v_mfma_f32_16x16x32_bf16 v[68:71], v[168:171], v[218:221], v[68:71]
	s_setprio 0
	s_setprio 1
	v_mfma_f32_16x16x32_bf16 v[120:123], v[172:175], v[188:191], v[120:123]
	v_mfma_f32_16x16x32_bf16 v[112:115], v[180:183], v[188:191], v[112:115]
	v_mfma_f32_16x16x32_bf16 v[104:107], v[172:175], v[196:199], v[104:107]
	v_mfma_f32_16x16x32_bf16 v[96:99], v[180:183], v[196:199], v[96:99]
	v_mfma_f32_16x16x32_bf16 v[88:91], v[172:175], v[204:207], v[88:91]
	v_mfma_f32_16x16x32_bf16 v[80:83], v[180:183], v[204:207], v[80:83]
	v_mfma_f32_16x16x32_bf16 v[72:75], v[172:175], v[214:217], v[72:75]
	v_mfma_f32_16x16x32_bf16 v[64:67], v[180:183], v[214:217], v[64:67]
	v_mfma_f32_16x16x32_bf16 v[120:123], v[176:179], v[192:195], v[120:123]
	v_mfma_f32_16x16x32_bf16 v[112:115], v[184:187], v[192:195], v[112:115]
	v_mfma_f32_16x16x32_bf16 v[104:107], v[176:179], v[200:203], v[104:107]
	v_mfma_f32_16x16x32_bf16 v[96:99], v[184:187], v[200:203], v[96:99]
	v_mfma_f32_16x16x32_bf16 v[88:91], v[176:179], v[208:211], v[88:91]
	v_mfma_f32_16x16x32_bf16 v[80:83], v[184:187], v[208:211], v[80:83]
	v_mfma_f32_16x16x32_bf16 v[72:75], v[176:179], v[218:221], v[72:75]
	v_mfma_f32_16x16x32_bf16 v[64:67], v[184:187], v[218:221], v[64:67]
	s_barrier
; #define PG8_STAGE(bufoff, gbase, voff) do { _Pragma("unroll") for (int _i = 0; _i < 2; ++_i) \
;         __builtin_amdgcn_global_load_lds((const unsigned*)((const char*)(gbase) + (voff)[_i]), (PG8_LAS unsigned*)(lds + (bufoff) + ldsw + _i * 8192), 16, 0, 0); } while (0)
; #define PG8_LDA(dst, b, h) do { _Pragma("unroll") for (int m = 0; m < 4; ++m) _Pragma("unroll") for (int k = 0; k < 2; ++k) dst[m][k] = *(const PG8_LAS bf16x8*)(lds + PG8_SA(b, h) + aoff + m * 2048 + k * 1024); } while (0)
; #define PG8_MMA(ai, bj, At, Bt) do { __builtin_amdgcn_s_setprio(1); _Pragma("unroll") for (int m = 0; m < 4; ++m) _Pragma("unroll") for (int n = 0; n < 2; ++n) _Pragma("unroll") for (int k = 0; k < 2; ++k) \
;         acc[ai][bj][m][n] = __builtin_amdgcn_mfma_f32_16x16x32_bf16(Bt[n][k], At[m][k], acc[ai][bj][m][n], 0, 0, 0); __builtin_amdgcn_s_setprio(0); } while (0)
; #define PG8_WAIT_V(n) asm volatile("s_waitcnt vmcnt(" #n ")" ::: "memory")
; #define PG8_WAIT_L(n) asm volatile("s_waitcnt lgkmcnt(" #n ")" ::: "memory")
; #define PG8_BAR __builtin_amdgcn_s_barrier()
; #define PG8_SCHED __builtin_amdgcn_sched_barrier(0)
; template <class Epi, class Sched, bool ALIGN_EPI = false, bool SP2 = false>
; __device__ __forceinline__ void gemm_phase(PG8_LAS unsigned char* lds, const Gemm g, const Sched& S, const Epi& E) {
;     ...
;         for (int t = 0; t < nt; t += 2) {
;             const bool last = (t == nt - 2);
;     ...
;             PG8_LDA(At, 1, 1); PG8_STAGE(PG8_SB(1, 0), b3, voffB); PG8_STAGE(PG8_SB(1, 1), b3 + hstep, voffB); PG8_STAGE(PG8_SA(1, 0), a3, voffA);
;             PG8_WAIT_V(8); PG8_WAIT_L(0); PG8_BAR; PG8_MMA(1, 0, At, B0); PG8_MMA(1, 1, At, B1); PG8_BAR; PG8_SCHED;
;     ...
;         if constexpr (ALIGN_EPI) { if (wr == 0) PG8_BAR; }
	s_setprio 0
	s_add_i32 s30, s71, s35
	v_lshl_add_u64 v[222:223], v[222:223], 0, s[8:9]
	s_mov_b32 m0, s30
	ds_read_b128 v[188:191], v161 offset:49152
	ds_read_b128 v[192:195], v161 offset:50176
	ds_read_b128 v[196:199], v161 offset:51200
	ds_read_b128 v[200:203], v161 offset:52224
	ds_read_b128 v[204:207], v161 offset:53248
	ds_read_b128 v[208:211], v161 offset:54272
	ds_read_b128 v[214:217], v161 offset:55296
	ds_read_b128 v[218:221], v161 offset:56320
	global_load_lds_dwordx4 v[222:223], off
	s_add_i32 m0, s30, 0x2000
	s_add_u32 s28, s28, 0x40080
	v_lshl_add_u64 v[222:223], v[224:225], 0, s[8:9]
	s_addc_u32 s29, s29, 0
	s_add_i32 s30, s72, s35
	global_load_lds_dwordx4 v[222:223], off
	v_lshl_add_u64 v[222:223], s[28:29], 0, v[132:133]
	s_mov_b32 m0, s30
	s_nop 0
	global_load_lds_dwordx4 v[222:223], off
	v_lshl_add_u64 v[222:223], s[28:29], 0, v[128:129]
	s_add_i32 m0, s30, 0x2000
	s_nop 0
	global_load_lds_dwordx4 v[222:223], off
	v_lshl_add_u64 v[222:223], v[226:227], 0, s[8:9]
	s_mov_b32 m0, s44
	s_nop 0
	global_load_lds_dwordx4 v[222:223], off
	v_lshl_add_u64 v[222:223], v[228:229], 0, s[8:9]
	s_mov_b32 m0, s45
	s_nop 0
	global_load_lds_dwordx4 v[222:223], off
	s_waitcnt vmcnt(8)
	s_waitcnt lgkmcnt(0)
	s_barrier
	s_setprio 1
	v_mfma_f32_16x16x32_bf16 v[60:63], v[146:149], v[188:191], v[60:63]
	v_mfma_f32_16x16x32_bf16 v[52:55], v[164:167], v[188:191], v[52:55]
	v_mfma_f32_16x16x32_bf16 v[44:47], v[146:149], v[196:199], v[44:47]
	v_mfma_f32_16x16x32_bf16 v[36:39], v[164:167], v[196:199], v[36:39]
	v_mfma_f32_16x16x32_bf16 v[28:31], v[146:149], v[204:207], v[28:31]
	v_mfma_f32_16x16x32_bf16 v[20:23], v[164:167], v[204:207], v[20:23]
	v_mfma_f32_16x16x32_bf16 v[12:15], v[146:149], v[214:217], v[12:15]
	v_mfma_f32_16x16x32_bf16 v[4:7], v[164:167], v[214:217], v[4:7]
	v_mfma_f32_16x16x32_bf16 v[60:63], v[150:153], v[192:195], v[60:63]
	v_mfma_f32_16x16x32_bf16 v[52:55], v[168:171], v[192:195], v[52:55]
	v_mfma_f32_16x16x32_bf16 v[44:47], v[150:153], v[200:203], v[44:47]
	v_mfma_f32_16x16x32_bf16 v[36:39], v[168:171], v[200:203], v[36:39]
	v_mfma_f32_16x16x32_bf16 v[28:31], v[150:153], v[208:211], v[28:31]
	v_mfma_f32_16x16x32_bf16 v[20:23], v[168:171], v[208:211], v[20:23]
	v_mfma_f32_16x16x32_bf16 v[12:15], v[150:153], v[218:221], v[12:15]
	v_mfma_f32_16x16x32_bf16 v[4:7], v[168:171], v[218:221], v[4:7]
	s_setprio 0
	s_setprio 1
	v_mfma_f32_16x16x32_bf16 v[56:59], v[172:175], v[188:191], v[56:59]
	v_mfma_f32_16x16x32_bf16 v[48:51], v[180:183], v[188:191], v[48:51]
	v_mfma_f32_16x16x32_bf16 v[40:43], v[172:175], v[196:199], v[40:43]
	v_mfma_f32_16x16x32_bf16 v[32:35], v[180:183], v[196:199], v[32:35]
	v_mfma_f32_16x16x32_bf16 v[24:27], v[172:175], v[204:207], v[24:27]
	v_mfma_f32_16x16x32_bf16 v[16:19], v[180:183], v[204:207], v[16:19]
	v_mfma_f32_16x16x32_bf16 v[8:11], v[172:175], v[214:217], v[8:11]
	v_mfma_f32_16x16x32_bf16 v[0:3], v[180:183], v[214:217], v[0:3]
	v_mfma_f32_16x16x32_bf16 v[56:59], v[176:179], v[192:195], v[56:59]
	v_mfma_f32_16x16x32_bf16 v[48:51], v[184:187], v[192:195], v[48:51]
	v_mfma_f32_16x16x32_bf16 v[40:43], v[176:179], v[200:203], v[40:43]
	v_mfma_f32_16x16x32_bf16 v[32:35], v[184:187], v[200:203], v[32:35]
	v_mfma_f32_16x16x32_bf16 v[24:27], v[176:179], v[208:211], v[24:27]
	v_mfma_f32_16x16x32_bf16 v[16:19], v[184:187], v[208:211], v[16:19]
	v_mfma_f32_16x16x32_bf16 v[8:11], v[176:179], v[218:221], v[8:11]
	v_mfma_f32_16x16x32_bf16 v[0:3], v[184:187], v[218:221], v[0:3]
	s_barrier
	s_setprio 0
	s_add_i32 s70, s70, 2
	s_add_u32 s26, s26, 0x100
	s_addc_u32 s27, s27, 0
	s_add_u32 s68, s68, 0x100
	s_addc_u32 s69, s69, 0
	s_cmp_gt_u32 s70, 13
	s_cbranch_scc0 .LBB0_910
	s_and_b64 vcc, exec, s[14:15]
	s_cbranch_vccz .LBB0_913
	s_barrier

; #define PG8_STAGE(bufoff, gbase, voff) do { _Pragma("unroll") for (int _i = 0; _i < 2; ++_i) \
;         __builtin_amdgcn_global_load_lds((const unsigned*)((const char*)(gbase) + (voff)[_i]), (PG8_LAS unsigned*)(lds + (bufoff) + ldsw + _i * 8192), 16, 0, 0); } while (0)
; #define PG8_LDA(dst, b, h) do { _Pragma("unroll") for (int m = 0; m < 4; ++m) _Pragma("unroll") for (int k = 0; k < 2; ++k) dst[m][k] = *(const PG8_LAS bf16x8*)(lds + PG8_SA(b, h) + aoff + m * 2048 + k * 1024); } while (0)
; #define PG8_LDB(dst, b, h) do { _Pragma("unroll") for (int n = 0; n < 2; ++n) _Pragma("unroll") for (int k = 0; k < 2; ++k) dst[n][k] = *(const PG8_LAS bf16x8*)(lds + PG8_SB(b, h) + boff + n * 2048 + k * 1024); } while (0)
; #define PG8_MMA(ai, bj, At, Bt) do { __builtin_amdgcn_s_setprio(1); _Pragma("unroll") for (int m = 0; m < 4; ++m) _Pragma("unroll") for (int n = 0; n < 2; ++n) _Pragma("unroll") for (int k = 0; k < 2; ++k) \
;         acc[ai][bj][m][n] = __builtin_amdgcn_mfma_f32_16x16x32_bf16(Bt[n][k], At[m][k], acc[ai][bj][m][n], 0, 0, 0); __builtin_amdgcn_s_setprio(0); } while (0)
; #define PG8_WAIT_V(n) asm volatile("s_waitcnt vmcnt(" #n ")" ::: "memory")
; #define PG8_WAIT_L(n) asm volatile("s_waitcnt lgkmcnt(" #n ")" ::: "memory")
; #define PG8_BAR __builtin_amdgcn_s_barrier()
; #define PG8_SCHED __builtin_amdgcn_sched_barrier(0)
; template <class Epi, class Sched, bool ALIGN_EPI = false, bool SP2 = false>
; __device__ __forceinline__ void gemm_phase(PG8_LAS unsigned char* lds, const Gemm g, const Sched& S, const Epi& E) {
;     ...
;             const bool last = (t == nt - 2);
;             const char* a1 = cA + (size_t)(t + 1) * kstep;
;             const char* a2 = last ? nA : cA + (size_t)(t + 2) * kstep; const char* b2 = last ? nB : cB + (size_t)(t + 2) * kstep;
;             const char* a3 = a2 + kstep; const char* b3 = b2 + kstep;
;     ...
;             PG8_LDB(B0, 0, 0); PG8_LDB(B1, 0, 1); PG8_SCHED; PG8_LDA(At, 0, 0); PG8_STAGE(PG8_SA(1, 1), a1 + hstep, voffA);
;             PG8_WAIT_V(8); PG8_WAIT_L(0); PG8_BAR; PG8_MMA(0, 0, At, B0); PG8_MMA(0, 1, At, B1); PG8_BAR; PG8_SCHED;
;             PG8_LDA(At, 0, 1); PG8_STAGE(PG8_SB(0, 0), b2, voffB); PG8_STAGE(PG8_SB(0, 1), b2 + hstep, voffB); PG8_STAGE(PG8_SA(0, 0), a2, voffA);
;             PG8_WAIT_V(8); PG8_WAIT_L(0); PG8_BAR; PG8_MMA(1, 0, At, B0); PG8_MMA(1, 1, At, B1); PG8_BAR; PG8_SCHED;
.LBB0_1001:
	s_waitcnt lgkmcnt(0)
	ds_read_b128 v[128:131], v191
	ds_read_b128 v[132:135], v191 offset:1024
	ds_read_b128 v[136:139], v191 offset:2048
	ds_read_b128 v[140:143], v191 offset:3072
	ds_read_b128 v[144:147], v192
	ds_read_b128 v[148:151], v192 offset:1024
	ds_read_b128 v[170:173], v192 offset:2048
	ds_read_b128 v[174:177], v192 offset:3072
	s_add_i32 s95, s34, 2
	s_add_u32 s30, s28, 0x100
	s_addc_u32 s31, s29, 0
	s_cmp_eq_u32 s93, s34
	s_cselect_b32 s34, s26, s94
	s_cselect_b32 s37, s25, s31
	s_cselect_b32 s36, s24, s30
	s_cselect_b32 s35, s27, s86
	v_lshl_add_u64 v[218:219], s[28:29], 0, v[164:165]
	s_add_i32 m0, s40, 0xc000
	ds_read_b128 v[178:181], v193
	ds_read_b128 v[182:185], v193 offset:1024
	ds_read_b128 v[186:189], v193 offset:2048
	ds_read_b128 v[196:199], v193 offset:3072
	ds_read_b128 v[200:203], v193 offset:4096
	ds_read_b128 v[204:207], v193 offset:5120
	ds_read_b128 v[208:211], v193 offset:6144
	ds_read_b128 v[214:217], v193 offset:7168
	global_load_lds_dwordx4 v[218:219], off
	v_lshl_add_u64 v[218:219], s[28:29], 0, v[166:167]
	s_add_i32 m0, s40, 0xe000
	s_nop 0
	global_load_lds_dwordx4 v[218:219], off
	s_waitcnt vmcnt(8)
	s_waitcnt lgkmcnt(0)
	s_barrier
	s_setprio 1
	v_mfma_f32_16x16x32_bf16 v[124:127], v[128:131], v[178:181], v[124:127]
	v_mfma_f32_16x16x32_bf16 v[120:123], v[136:139], v[178:181], v[120:123]
	v_mfma_f32_16x16x32_bf16 v[116:119], v[128:131], v[186:189], v[116:119]
	v_mfma_f32_16x16x32_bf16 v[108:111], v[136:139], v[186:189], v[108:111]
	v_mfma_f32_16x16x32_bf16 v[100:103], v[128:131], v[200:203], v[100:103]
	v_mfma_f32_16x16x32_bf16 v[92:95], v[136:139], v[200:203], v[92:95]
	v_mfma_f32_16x16x32_bf16 v[84:87], v[128:131], v[208:211], v[84:87]
	v_mfma_f32_16x16x32_bf16 v[76:79], v[136:139], v[208:211], v[76:79]
	v_mfma_f32_16x16x32_bf16 v[124:127], v[132:135], v[182:185], v[124:127]
	v_mfma_f32_16x16x32_bf16 v[120:123], v[140:143], v[182:185], v[120:123]
	v_mfma_f32_16x16x32_bf16 v[116:119], v[132:135], v[196:199], v[116:119]
	v_mfma_f32_16x16x32_bf16 v[108:111], v[140:143], v[196:199], v[108:111]
	v_mfma_f32_16x16x32_bf16 v[100:103], v[132:135], v[204:207], v[100:103]
	v_mfma_f32_16x16x32_bf16 v[92:95], v[140:143], v[204:207], v[92:95]
	v_mfma_f32_16x16x32_bf16 v[84:87], v[132:135], v[214:217], v[84:87]
	v_mfma_f32_16x16x32_bf16 v[76:79], v[140:143], v[214:217], v[76:79]
	s_setprio 0
	s_setprio 1
	v_mfma_f32_16x16x32_bf16 v[112:115], v[144:147], v[178:181], v[112:115]
	v_mfma_f32_16x16x32_bf16 v[104:107], v[170:173], v[178:181], v[104:107]
	v_mfma_f32_16x16x32_bf16 v[96:99], v[144:147], v[186:189], v[96:99]
	v_mfma_f32_16x16x32_bf16 v[88:91], v[170:173], v[186:189], v[88:91]
	v_mfma_f32_16x16x32_bf16 v[80:83], v[144:147], v[200:203], v[80:83]
	v_mfma_f32_16x16x32_bf16 v[72:75], v[170:173], v[200:203], v[72:75]
	v_mfma_f32_16x16x32_bf16 v[68:71], v[144:147], v[208:211], v[68:71]
	v_mfma_f32_16x16x32_bf16 v[64:67], v[170:173], v[208:211], v[64:67]
	v_mfma_f32_16x16x32_bf16 v[112:115], v[148:151], v[182:185], v[112:115]
	v_mfma_f32_16x16x32_bf16 v[104:107], v[174:177], v[182:185], v[104:107]
	v_mfma_f32_16x16x32_bf16 v[96:99], v[148:151], v[196:199], v[96:99]
	v_mfma_f32_16x16x32_bf16 v[88:91], v[174:177], v[196:199], v[88:91]
	v_mfma_f32_16x16x32_bf16 v[80:83], v[148:151], v[204:207], v[80:83]
	v_mfma_f32_16x16x32_bf16 v[72:75], v[174:177], v[204:207], v[72:75]
	v_mfma_f32_16x16x32_bf16 v[68:71], v[148:151], v[214:217], v[68:71]
	v_mfma_f32_16x16x32_bf16 v[64:67], v[174:177], v[214:217], v[64:67]
	s_barrier
	s_setprio 0
	s_add_i32 s28, s66, s39
	v_lshl_add_u64 v[218:219], s[34:35], 0, v[154:155]
	s_mov_b32 m0, s28
	ds_read_b128 v[178:181], v193 offset:16384
	ds_read_b128 v[182:185], v193 offset:17408
	ds_read_b128 v[186:189], v193 offset:18432
	ds_read_b128 v[196:199], v193 offset:19456
	ds_read_b128 v[200:203], v193 offset:20480
	ds_read_b128 v[204:207], v193 offset:21504
	ds_read_b128 v[208:211], v193 offset:22528
	ds_read_b128 v[214:217], v193 offset:23552
	global_load_lds_dwordx4 v[218:219], off
	s_add_i32 m0, s28, 0x2000
	s_add_u32 s28, s34, 0xb0000
	v_lshl_add_u64 v[220:221], s[34:35], 0, v[162:163]
	s_addc_u32 s29, s35, 0
	s_add_i32 s96, s67, s39
	global_load_lds_dwordx4 v[220:221], off
	v_lshl_add_u64 v[222:223], s[28:29], 0, v[154:155]
	s_mov_b32 m0, s96
	v_lshl_add_u64 v[224:225], s[36:37], 0, v[160:161]
	global_load_lds_dwordx4 v[222:223], off
	v_lshl_add_u64 v[222:223], s[28:29], 0, v[162:163]
	s_add_i32 m0, s96, 0x2000
	s_nop 0
	global_load_lds_dwordx4 v[222:223], off
	v_lshl_add_u64 v[222:223], s[36:37], 0, v[152:153]
	s_mov_b32 m0, s40
	s_nop 0
	global_load_lds_dwordx4 v[222:223], off
	s_mov_b32 m0, s41
	s_nop 0
	global_load_lds_dwordx4 v[224:225], off
	s_waitcnt vmcnt(8)
	s_waitcnt lgkmcnt(0)
	s_barrier
; #define PG8_STAGE(bufoff, gbase, voff) do { _Pragma("unroll") for (int _i = 0; _i < 2; ++_i) \
;         __builtin_amdgcn_global_load_lds((const unsigned*)((const char*)(gbase) + (voff)[_i]), (PG8_LAS unsigned*)(lds + (bufoff) + ldsw + _i * 8192), 16, 0, 0); } while (0)
; #define PG8_LDA(dst, b, h) do { _Pragma("unroll") for (int m = 0; m < 4; ++m) _Pragma("unroll") for (int k = 0; k < 2; ++k) dst[m][k] = *(const PG8_LAS bf16x8*)(lds + PG8_SA(b, h) + aoff + m * 2048 + k * 1024); } while (0)
; #define PG8_LDB(dst, b, h) do { _Pragma("unroll") for (int n = 0; n < 2; ++n) _Pragma("unroll") for (int k = 0; k < 2; ++k) dst[n][k] = *(const PG8_LAS bf16x8*)(lds + PG8_SB(b, h) + boff + n * 2048 + k * 1024); } while (0)
; #define PG8_MMA(ai, bj, At, Bt) do { __builtin_amdgcn_s_setprio(1); _Pragma("unroll") for (int m = 0; m < 4; ++m) _Pragma("unroll") for (int n = 0; n < 2; ++n) _Pragma("unroll") for (int k = 0; k < 2; ++k) \
;         acc[ai][bj][m][n] = __builtin_amdgcn_mfma_f32_16x16x32_bf16(Bt[n][k], At[m][k], acc[ai][bj][m][n], 0, 0, 0); __builtin_amdgcn_s_setprio(0); } while (0)
; #define PG8_WAIT_V(n) asm volatile("s_waitcnt vmcnt(" #n ")" ::: "memory")
; #define PG8_WAIT_L(n) asm volatile("s_waitcnt lgkmcnt(" #n ")" ::: "memory")
; #define PG8_BAR __builtin_amdgcn_s_barrier()
; #define PG8_SCHED __builtin_amdgcn_sched_barrier(0)
; template <class Epi, class Sched, bool ALIGN_EPI = false, bool SP2 = false>
; __device__ __forceinline__ void gemm_phase(PG8_LAS unsigned char* lds, const Gemm g, const Sched& S, const Epi& E) {
;     ...
;             PG8_WAIT_V(8); PG8_WAIT_L(0); PG8_BAR; PG8_MMA(1, 0, At, B0); PG8_MMA(1, 1, At, B1); PG8_BAR; PG8_SCHED;
;             PG8_LDB(B0, 1, 0); PG8_LDB(B1, 1, 1); PG8_SCHED; PG8_LDA(At, 1, 0); PG8_STAGE(PG8_SA(0, 1), a2 + hstep, voffA);
;             PG8_WAIT_V(8); PG8_WAIT_L(0); PG8_BAR; PG8_MMA(0, 0, At, B0); PG8_MMA(0, 1, At, B1); PG8_BAR; PG8_SCHED;
	s_setprio 1
	v_mfma_f32_16x16x32_bf16 v[60:63], v[128:131], v[178:181], v[60:63]
	v_mfma_f32_16x16x32_bf16 v[56:59], v[136:139], v[178:181], v[56:59]
	v_mfma_f32_16x16x32_bf16 v[52:55], v[128:131], v[186:189], v[52:55]
	v_mfma_f32_16x16x32_bf16 v[44:47], v[136:139], v[186:189], v[44:47]
	v_mfma_f32_16x16x32_bf16 v[36:39], v[128:131], v[200:203], v[36:39]
	v_mfma_f32_16x16x32_bf16 v[28:31], v[136:139], v[200:203], v[28:31]
	v_mfma_f32_16x16x32_bf16 v[20:23], v[128:131], v[208:211], v[20:23]
	v_mfma_f32_16x16x32_bf16 v[12:15], v[136:139], v[208:211], v[12:15]
	v_mfma_f32_16x16x32_bf16 v[60:63], v[132:135], v[182:185], v[60:63]
	v_mfma_f32_16x16x32_bf16 v[56:59], v[140:143], v[182:185], v[56:59]
	v_mfma_f32_16x16x32_bf16 v[52:55], v[132:135], v[196:199], v[52:55]
	v_mfma_f32_16x16x32_bf16 v[44:47], v[140:143], v[196:199], v[44:47]
	v_mfma_f32_16x16x32_bf16 v[36:39], v[132:135], v[204:207], v[36:39]
	v_mfma_f32_16x16x32_bf16 v[28:31], v[140:143], v[204:207], v[28:31]
	v_mfma_f32_16x16x32_bf16 v[20:23], v[132:135], v[214:217], v[20:23]
	v_mfma_f32_16x16x32_bf16 v[12:15], v[140:143], v[214:217], v[12:15]
	s_setprio 0
	s_setprio 1
	v_mfma_f32_16x16x32_bf16 v[48:51], v[144:147], v[178:181], v[48:51]
	v_mfma_f32_16x16x32_bf16 v[40:43], v[170:173], v[178:181], v[40:43]
	v_mfma_f32_16x16x32_bf16 v[32:35], v[144:147], v[186:189], v[32:35]
	v_mfma_f32_16x16x32_bf16 v[24:27], v[170:173], v[186:189], v[24:27]
	v_mfma_f32_16x16x32_bf16 v[16:19], v[144:147], v[200:203], v[16:19]
	v_mfma_f32_16x16x32_bf16 v[8:11], v[170:173], v[200:203], v[8:11]
	v_mfma_f32_16x16x32_bf16 v[4:7], v[144:147], v[208:211], v[4:7]
	v_mfma_f32_16x16x32_bf16 v[0:3], v[170:173], v[208:211], v[0:3]
	v_mfma_f32_16x16x32_bf16 v[48:51], v[148:151], v[182:185], v[48:51]
	v_mfma_f32_16x16x32_bf16 v[40:43], v[174:177], v[182:185], v[40:43]
	v_mfma_f32_16x16x32_bf16 v[32:35], v[148:151], v[196:199], v[32:35]
	v_mfma_f32_16x16x32_bf16 v[24:27], v[174:177], v[196:199], v[24:27]
	v_mfma_f32_16x16x32_bf16 v[16:19], v[148:151], v[204:207], v[16:19]
	v_mfma_f32_16x16x32_bf16 v[8:11], v[174:177], v[204:207], v[8:11]
	v_mfma_f32_16x16x32_bf16 v[4:7], v[148:151], v[214:217], v[4:7]
	v_mfma_f32_16x16x32_bf16 v[0:3], v[174:177], v[214:217], v[0:3]
	s_barrier
	s_setprio 0
	s_add_i32 s96, 0, 0x18000
	s_add_i32 s97, 0, 0x1c000
	v_add_u32_e32 v140, s96, v159
	v_add_u32_e32 v174, s97, v159
	ds_read_b128 v[128:131], v140
	ds_read_b128 v[132:135], v140 offset:1024
	ds_read_b128 v[136:139], v140 offset:2048
	ds_read_b128 v[140:143], v140 offset:3072
	ds_read_b128 v[144:147], v174
	ds_read_b128 v[148:151], v174 offset:1024
	ds_read_b128 v[170:173], v174 offset:2048
	ds_read_b128 v[174:177], v174 offset:3072
	s_add_u32 s28, s36, 0xb0000
	s_addc_u32 s29, s37, 0
	s_mov_b32 m0, s44
	v_lshl_add_u64 v[226:227], s[28:29], 0, v[152:153]
	ds_read_b128 v[178:181], v193 offset:32768
	ds_read_b128 v[182:185], v193 offset:33792
	ds_read_b128 v[186:189], v193 offset:34816
	ds_read_b128 v[196:199], v193 offset:35840
	ds_read_b128 v[200:203], v193 offset:36864
	ds_read_b128 v[204:207], v193 offset:37888
	ds_read_b128 v[208:211], v193 offset:38912
	ds_read_b128 v[214:217], v193 offset:39936
	global_load_lds_dwordx4 v[226:227], off
	v_lshl_add_u64 v[226:227], s[28:29], 0, v[160:161]
	s_mov_b32 m0, s45
	s_nop 0
	global_load_lds_dwordx4 v[226:227], off
	s_waitcnt vmcnt(8)
	s_waitcnt lgkmcnt(0)
	s_barrier
	s_setprio 1
	v_mfma_f32_16x16x32_bf16 v[124:127], v[128:131], v[178:181], v[124:127]
	v_mfma_f32_16x16x32_bf16 v[120:123], v[136:139], v[178:181], v[120:123]
	v_mfma_f32_16x16x32_bf16 v[116:119], v[128:131], v[186:189], v[116:119]
	v_mfma_f32_16x16x32_bf16 v[108:111], v[136:139], v[186:189], v[108:111]
	v_mfma_f32_16x16x32_bf16 v[100:103], v[128:131], v[200:203], v[100:103]
	v_mfma_f32_16x16x32_bf16 v[92:95], v[136:139], v[200:203], v[92:95]
	v_mfma_f32_16x16x32_bf16 v[84:87], v[128:131], v[208:211], v[84:87]
	v_mfma_f32_16x16x32_bf16 v[76:79], v[136:139], v[208:211], v[76:79]
	v_mfma_f32_16x16x32_bf16 v[124:127], v[132:135], v[182:185], v[124:127]
	v_mfma_f32_16x16x32_bf16 v[120:123], v[140:143], v[182:185], v[120:123]
	v_mfma_f32_16x16x32_bf16 v[116:119], v[132:135], v[196:199], v[116:119]
	v_mfma_f32_16x16x32_bf16 v[108:111], v[140:143], v[196:199], v[108:111]
	v_mfma_f32_16x16x32_bf16 v[100:103], v[132:135], v[204:207], v[100:103]
	v_mfma_f32_16x16x32_bf16 v[92:95], v[140:143], v[204:207], v[92:95]
	v_mfma_f32_16x16x32_bf16 v[84:87], v[132:135], v[214:217], v[84:87]
	v_mfma_f32_16x16x32_bf16 v[76:79], v[140:143], v[214:217], v[76:79]
	s_setprio 0
	s_setprio 1
	v_mfma_f32_16x16x32_bf16 v[112:115], v[144:147], v[178:181], v[112:115]
	v_mfma_f32_16x16x32_bf16 v[104:107], v[170:173], v[178:181], v[104:107]
	v_mfma_f32_16x16x32_bf16 v[96:99], v[144:147], v[186:189], v[96:99]
	v_mfma_f32_16x16x32_bf16 v[88:91], v[170:173], v[186:189], v[88:91]
	v_mfma_f32_16x16x32_bf16 v[80:83], v[144:147], v[200:203], v[80:83]
	v_mfma_f32_16x16x32_bf16 v[72:75], v[170:173], v[200:203], v[72:75]
	v_mfma_f32_16x16x32_bf16 v[68:71], v[144:147], v[208:211], v[68:71]
	v_mfma_f32_16x16x32_bf16 v[64:67], v[170:173], v[208:211], v[64:67]
	v_mfma_f32_16x16x32_bf16 v[112:115], v[148:151], v[182:185], v[112:115]
	v_mfma_f32_16x16x32_bf16 v[104:107], v[174:177], v[182:185], v[104:107]
	v_mfma_f32_16x16x32_bf16 v[96:99], v[148:151], v[196:199], v[96:99]
	v_mfma_f32_16x16x32_bf16 v[88:91], v[174:177], v[196:199], v[88:91]
	v_mfma_f32_16x16x32_bf16 v[80:83], v[148:151], v[204:207], v[80:83]
	v_mfma_f32_16x16x32_bf16 v[72:75], v[174:177], v[204:207], v[72:75]
	v_mfma_f32_16x16x32_bf16 v[68:71], v[148:151], v[214:217], v[68:71]
	v_mfma_f32_16x16x32_bf16 v[64:67], v[174:177], v[214:217], v[64:67]
	s_barrier
; #define PG8_STAGE(bufoff, gbase, voff) do { _Pragma("unroll") for (int _i = 0; _i < 2; ++_i) \
;         __builtin_amdgcn_global_load_lds((const unsigned*)((const char*)(gbase) + (voff)[_i]), (PG8_LAS unsigned*)(lds + (bufoff) + ldsw + _i * 8192), 16, 0, 0); } while (0)
; #define PG8_LDA(dst, b, h) do { _Pragma("unroll") for (int m = 0; m < 4; ++m) _Pragma("unroll") for (int k = 0; k < 2; ++k) dst[m][k] = *(const PG8_LAS bf16x8*)(lds + PG8_SA(b, h) + aoff + m * 2048 + k * 1024); } while (0)
; #define PG8_MMA(ai, bj, At, Bt) do { __builtin_amdgcn_s_setprio(1); _Pragma("unroll") for (int m = 0; m < 4; ++m) _Pragma("unroll") for (int n = 0; n < 2; ++n) _Pragma("unroll") for (int k = 0; k < 2; ++k) \
;         acc[ai][bj][m][n] = __builtin_amdgcn_mfma_f32_16x16x32_bf16(Bt[n][k], At[m][k], acc[ai][bj][m][n], 0, 0, 0); __builtin_amdgcn_s_setprio(0); } while (0)
; #define PG8_WAIT_V(n) asm volatile("s_waitcnt vmcnt(" #n ")" ::: "memory")
; #define PG8_WAIT_L(n) asm volatile("s_waitcnt lgkmcnt(" #n ")" ::: "memory")
; #define PG8_BAR __builtin_amdgcn_s_barrier()
; #define PG8_SCHED __builtin_amdgcn_sched_barrier(0)
; template <class Epi, class Sched, bool ALIGN_EPI = false, bool SP2 = false>
; __device__ __forceinline__ void gemm_phase(PG8_LAS unsigned char* lds, const Gemm g, const Sched& S, const Epi& E) {
;     ...
;         for (int t = 0; t < nt; t += 2) {
;             const bool last = (t == nt - 2);
;     ...
;             PG8_LDA(At, 1, 1); PG8_STAGE(PG8_SB(1, 0), b3, voffB); PG8_STAGE(PG8_SB(1, 1), b3 + hstep, voffB); PG8_STAGE(PG8_SA(1, 0), a3, voffA);
;             PG8_WAIT_V(8); PG8_WAIT_L(0); PG8_BAR; PG8_MMA(1, 0, At, B0); PG8_MMA(1, 1, At, B1); PG8_BAR; PG8_SCHED;
;     ...
;         if constexpr (ALIGN_EPI) { if (wr == 0) PG8_BAR; }
	s_setprio 0
	s_add_i32 s28, s96, s39
	v_lshl_add_u64 v[218:219], v[218:219], 0, s[18:19]
	s_mov_b32 m0, s28
	ds_read_b128 v[178:181], v193 offset:49152
	ds_read_b128 v[182:185], v193 offset:50176
	ds_read_b128 v[186:189], v193 offset:51200
	ds_read_b128 v[196:199], v193 offset:52224
	ds_read_b128 v[200:203], v193 offset:53248
	ds_read_b128 v[204:207], v193 offset:54272
	ds_read_b128 v[208:211], v193 offset:55296
	ds_read_b128 v[214:217], v193 offset:56320
	global_load_lds_dwordx4 v[218:219], off
	s_add_i32 m0, s28, 0x2000
	s_add_u32 s28, s34, 0xb0080
	v_lshl_add_u64 v[218:219], v[220:221], 0, s[18:19]
	s_addc_u32 s29, s35, 0
	s_add_i32 s34, s97, s39
	global_load_lds_dwordx4 v[218:219], off
	v_lshl_add_u64 v[218:219], s[28:29], 0, v[154:155]
	s_mov_b32 m0, s34
	s_nop 0
	global_load_lds_dwordx4 v[218:219], off
	v_lshl_add_u64 v[218:219], s[28:29], 0, v[162:163]
	s_add_i32 m0, s34, 0x2000
	s_nop 0
	global_load_lds_dwordx4 v[218:219], off
	v_lshl_add_u64 v[218:219], v[222:223], 0, s[18:19]
	s_mov_b32 m0, s47
	s_nop 0
	global_load_lds_dwordx4 v[218:219], off
	v_lshl_add_u64 v[218:219], v[224:225], 0, s[18:19]
	s_mov_b32 m0, s49
	s_nop 0
	global_load_lds_dwordx4 v[218:219], off
	s_waitcnt vmcnt(8)
	s_waitcnt lgkmcnt(0)
	s_barrier
	s_setprio 1
	v_mfma_f32_16x16x32_bf16 v[60:63], v[128:131], v[178:181], v[60:63]
	v_mfma_f32_16x16x32_bf16 v[56:59], v[136:139], v[178:181], v[56:59]
	v_mfma_f32_16x16x32_bf16 v[52:55], v[128:131], v[186:189], v[52:55]
	v_mfma_f32_16x16x32_bf16 v[44:47], v[136:139], v[186:189], v[44:47]
	v_mfma_f32_16x16x32_bf16 v[36:39], v[128:131], v[200:203], v[36:39]
	v_mfma_f32_16x16x32_bf16 v[28:31], v[136:139], v[200:203], v[28:31]
	v_mfma_f32_16x16x32_bf16 v[20:23], v[128:131], v[208:211], v[20:23]
	v_mfma_f32_16x16x32_bf16 v[12:15], v[136:139], v[208:211], v[12:15]
	v_mfma_f32_16x16x32_bf16 v[60:63], v[132:135], v[182:185], v[60:63]
	v_mfma_f32_16x16x32_bf16 v[56:59], v[140:143], v[182:185], v[56:59]
	v_mfma_f32_16x16x32_bf16 v[52:55], v[132:135], v[196:199], v[52:55]
	v_mfma_f32_16x16x32_bf16 v[44:47], v[140:143], v[196:199], v[44:47]
	v_mfma_f32_16x16x32_bf16 v[36:39], v[132:135], v[204:207], v[36:39]
	v_mfma_f32_16x16x32_bf16 v[28:31], v[140:143], v[204:207], v[28:31]
	v_mfma_f32_16x16x32_bf16 v[20:23], v[132:135], v[214:217], v[20:23]
	v_mfma_f32_16x16x32_bf16 v[12:15], v[140:143], v[214:217], v[12:15]
	s_setprio 0
	s_setprio 1
	v_mfma_f32_16x16x32_bf16 v[48:51], v[144:147], v[178:181], v[48:51]
	v_mfma_f32_16x16x32_bf16 v[40:43], v[170:173], v[178:181], v[40:43]
	v_mfma_f32_16x16x32_bf16 v[32:35], v[144:147], v[186:189], v[32:35]
	v_mfma_f32_16x16x32_bf16 v[24:27], v[170:173], v[186:189], v[24:27]
	v_mfma_f32_16x16x32_bf16 v[16:19], v[144:147], v[200:203], v[16:19]
	v_mfma_f32_16x16x32_bf16 v[8:11], v[170:173], v[200:203], v[8:11]
	v_mfma_f32_16x16x32_bf16 v[4:7], v[144:147], v[208:211], v[4:7]
	v_mfma_f32_16x16x32_bf16 v[0:3], v[170:173], v[208:211], v[0:3]
	v_mfma_f32_16x16x32_bf16 v[48:51], v[148:151], v[182:185], v[48:51]
	v_mfma_f32_16x16x32_bf16 v[40:43], v[174:177], v[182:185], v[40:43]
	v_mfma_f32_16x16x32_bf16 v[32:35], v[148:151], v[196:199], v[32:35]
	v_mfma_f32_16x16x32_bf16 v[24:27], v[174:177], v[196:199], v[24:27]
	v_mfma_f32_16x16x32_bf16 v[16:19], v[148:151], v[204:207], v[16:19]
	v_mfma_f32_16x16x32_bf16 v[8:11], v[174:177], v[204:207], v[8:11]
	v_mfma_f32_16x16x32_bf16 v[4:7], v[148:151], v[214:217], v[4:7]
	v_mfma_f32_16x16x32_bf16 v[0:3], v[174:177], v[214:217], v[0:3]
	s_barrier
	s_setprio 0
	s_add_u32 s94, s94, 0x100
	s_addc_u32 s86, s86, 0
	s_cmp_ge_i32 s95, s92
	s_mov_b64 s[28:29], s[30:31]
	s_mov_b32 s34, s95
	s_cbranch_scc0 .LBB0_1001
	s_and_b64 vcc, exec, s[20:21]
	s_cbranch_vccz .LBB0_1004
	s_barrier
